# K-loops: the two loop-invariant v_add_u32 LDS-address adds hoisted in front of the loop (no VALU left in the load sections except GEMM3's two 64-bit pointer adds)
# speedup vs baseline: 1.0026x; 1.0026x over previous
; #define PG8_STAGE(bufoff, gbase, voff) do { _Pragma("unroll") for (int _i = 0; _i < 2; ++_i) \
;         __builtin_amdgcn_global_load_lds((const unsigned*)((const char*)(gbase) + (voff)[_i]), (PG8_LAS unsigned*)(lds + (bufoff) + ldsw + _i * 8192), 16, 0, 0); } while (0)
; #define PG8_LDA(dst, b, h) do { _Pragma("unroll") for (int m = 0; m < 4; ++m) _Pragma("unroll") for (int k = 0; k < 2; ++k) dst[m][k] = *(const PG8_LAS bf16x8*)(lds + PG8_SA(b, h) + aoff + m * 2048 + k * 1024); } while (0)
; #define PG8_LDB(dst, b, h) do { _Pragma("unroll") for (int n = 0; n < 2; ++n) _Pragma("unroll") for (int k = 0; k < 2; ++k) dst[n][k] = *(const PG8_LAS bf16x8*)(lds + PG8_SB(b, h) + boff + n * 2048 + k * 1024); } while (0)
; #define PG8_WAIT_V(n) asm volatile("s_waitcnt vmcnt(" #n ")" ::: "memory")
; #define PG8_WAIT_L(n) asm volatile("s_waitcnt lgkmcnt(" #n ")" ::: "memory")
; #define PG8_BAR __builtin_amdgcn_s_barrier()
; template <class Epi, class Sched, bool ALIGN_EPI = false, bool SP2 = false>
; __device__ __forceinline__ void gemm_phase(PG8_LAS unsigned char* lds, const Gemm g, const Sched& S, const Epi& E) {
;     ...
;         const bool has_next = S.next(ui + 1, nxt);
;         const char* nA = has_next ? (const char*)g.A + (size_t)nxt.pm * tstep : cA; const char* nB = has_next ? (const char*)g.Bt + (size_t)nxt.pn * tstep : cB;
;         for (int t = 0; t < nt; t += 2) {
;             const bool last = (t == nt - 2);
;             const char* a1 = cA + (size_t)(t + 1) * kstepA;
;             const char* a2 = last ? nA : cA + (size_t)(t + 2) * kstepA; const char* b2 = last ? nB : cB + (size_t)(t + 2) * kstep;
;             const char* a3 = a2 + kstepA; const char* b3 = b2 + kstep;
;             if (last && has_next) S.a_ready(nxt);
;             if constexpr (SP2) {
;             PG8_LDB(B0, 0, 0); PG8_LDB(B1, 0, 1); PG8_SCHED; PG8_LDA(At, 0, 0); PG8_STAGE(PG8_SA(1, 1), a1 + hstepA, voffA);
;             PG8_WAIT_V(8); PG8_WAIT_L(0); PG8_BAR; PG8_MMA(0, 0, At, B0); PG8_MMA(0, 1, At, B1); PG8_BAR; PG8_SCHED;
;     ...
; #pragma unroll
;         for (int a = 0; a < 2; ++a)
; #pragma unroll
;             for (int b = 0; b < 2; ++b)
; #pragma unroll
;                 for (int m = 0; m < 4; ++m)
; #pragma unroll
;                     for (int n = 0; n < 2; ++n) acc[a][b][m][n] = (f32x4){0.f, 0.f, 0.f, 0.f};
;         cur = nxt; cA = nA; cB = nB; ++ui;
.LBB0_114:
	s_ashr_i32 s21, s20, 31
	s_lshl_b64 s[22:23], s[20:21], 21
	s_add_u32 s22, s92, s22
	s_addc_u32 s23, s93, s23
	s_and_b64 s[24:25], s[0:1], exec
	s_cselect_b32 s21, s23, s35
	s_cselect_b32 s27, s22, s34
	s_ashr_i32 s19, s18, 31
	s_lshl_b64 s[24:25], s[18:19], 21
	s_add_u32 s24, s3, s24
	s_addc_u32 s25, s29, s25
	s_and_b64 s[66:67], s[0:1], exec
	s_cselect_b32 s19, s25, s85
	s_cselect_b32 s31, s24, s84
	s_add_u32 s34, s34, 0x100080
	s_addc_u32 s35, s35, 0
	s_add_u32 s65, s84, 0x100
	v_mov_b32_e32 v0, 0
	s_addc_u32 s66, s85, 0
	s_mov_b32 s67, -2
	v_mov_b32_e32 v1, v0
	v_mov_b32_e32 v2, v0
	v_mov_b32_e32 v3, v0
	v_mov_b32_e32 v4, v0
	v_mov_b32_e32 v5, v0
	v_mov_b32_e32 v6, v0
	v_mov_b32_e32 v7, v0
	v_mov_b32_e32 v16, v0
	v_mov_b32_e32 v17, v0
	v_mov_b32_e32 v18, v0
	v_mov_b32_e32 v19, v0
	v_mov_b32_e32 v20, v0
	v_mov_b32_e32 v21, v0
	v_mov_b32_e32 v22, v0
	v_mov_b32_e32 v23, v0
	v_mov_b32_e32 v32, v0
	v_mov_b32_e32 v33, v0
	v_mov_b32_e32 v34, v0
	v_mov_b32_e32 v35, v0
	v_mov_b32_e32 v36, v0
	v_mov_b32_e32 v37, v0
	v_mov_b32_e32 v38, v0
	v_mov_b32_e32 v39, v0
	v_mov_b32_e32 v48, v0
	v_mov_b32_e32 v49, v0
	v_mov_b32_e32 v50, v0
	v_mov_b32_e32 v51, v0
	v_mov_b32_e32 v52, v0
	v_mov_b32_e32 v53, v0
	v_mov_b32_e32 v54, v0
	v_mov_b32_e32 v55, v0
	v_mov_b32_e32 v8, v0
	v_mov_b32_e32 v9, v0
	v_mov_b32_e32 v10, v0
	v_mov_b32_e32 v11, v0
	v_mov_b32_e32 v12, v0
	v_mov_b32_e32 v13, v0
	v_mov_b32_e32 v14, v0
	v_mov_b32_e32 v15, v0
	v_mov_b32_e32 v24, v0
	v_mov_b32_e32 v25, v0
	v_mov_b32_e32 v26, v0
	v_mov_b32_e32 v27, v0
	v_mov_b32_e32 v28, v0
	v_mov_b32_e32 v29, v0
	v_mov_b32_e32 v30, v0
	v_mov_b32_e32 v31, v0
	v_mov_b32_e32 v40, v0
	v_mov_b32_e32 v41, v0
	v_mov_b32_e32 v42, v0
	v_mov_b32_e32 v43, v0
	v_mov_b32_e32 v44, v0
	v_mov_b32_e32 v45, v0
	v_mov_b32_e32 v46, v0
	v_mov_b32_e32 v47, v0
	v_mov_b32_e32 v56, v0
	v_mov_b32_e32 v57, v0
	v_mov_b32_e32 v58, v0
	v_mov_b32_e32 v59, v0
	v_mov_b32_e32 v60, v0
	v_mov_b32_e32 v61, v0
	v_mov_b32_e32 v62, v0
	v_mov_b32_e32 v63, v0
	v_mov_b32_e32 v64, v0
	v_mov_b32_e32 v65, v0
	v_mov_b32_e32 v66, v0
	v_mov_b32_e32 v67, v0
	v_mov_b32_e32 v68, v0
	v_mov_b32_e32 v69, v0
	v_mov_b32_e32 v70, v0
	v_mov_b32_e32 v71, v0
	v_mov_b32_e32 v80, v0
	v_mov_b32_e32 v81, v0
	v_mov_b32_e32 v82, v0
	v_mov_b32_e32 v83, v0
	v_mov_b32_e32 v84, v0
	v_mov_b32_e32 v85, v0
	v_mov_b32_e32 v86, v0
	v_mov_b32_e32 v87, v0
	v_mov_b32_e32 v96, v0
	v_mov_b32_e32 v97, v0
	v_mov_b32_e32 v98, v0
	v_mov_b32_e32 v99, v0
	v_mov_b32_e32 v100, v0
	v_mov_b32_e32 v101, v0
	v_mov_b32_e32 v102, v0
	v_mov_b32_e32 v103, v0
	v_mov_b32_e32 v112, v0
	v_mov_b32_e32 v113, v0
	v_mov_b32_e32 v114, v0
	v_mov_b32_e32 v115, v0
	v_mov_b32_e32 v116, v0
	v_mov_b32_e32 v117, v0
	v_mov_b32_e32 v118, v0
	v_mov_b32_e32 v119, v0
	v_mov_b32_e32 v72, v0
	v_mov_b32_e32 v73, v0
	v_mov_b32_e32 v74, v0
	v_mov_b32_e32 v75, v0
	v_mov_b32_e32 v76, v0
	v_mov_b32_e32 v77, v0
	v_mov_b32_e32 v78, v0
	v_mov_b32_e32 v79, v0
	v_mov_b32_e32 v88, v0
	v_mov_b32_e32 v89, v0
	v_mov_b32_e32 v90, v0
	v_mov_b32_e32 v91, v0
	v_mov_b32_e32 v92, v0
	v_mov_b32_e32 v93, v0
	v_mov_b32_e32 v94, v0
	v_mov_b32_e32 v95, v0
	v_mov_b32_e32 v104, v0
	v_mov_b32_e32 v105, v0
	v_mov_b32_e32 v106, v0
	v_mov_b32_e32 v107, v0
	v_mov_b32_e32 v108, v0
	v_mov_b32_e32 v109, v0
	v_mov_b32_e32 v110, v0
	v_mov_b32_e32 v111, v0
	v_mov_b32_e32 v120, v0
	v_mov_b32_e32 v121, v0
	v_mov_b32_e32 v122, v0
	v_mov_b32_e32 v123, v0
	v_mov_b32_e32 v124, v0
	v_mov_b32_e32 v125, v0
	v_mov_b32_e32 v126, v0
	v_mov_b32_e32 v127, v0
	v_add_u32_e32 v154, 0x18000, v157
	v_add_u32_e32 v155, 0x1c000, v157
.LBB0_115:
	ds_read_b128 v[150:153], v158
	ds_read_b128 v[162:165], v158 offset:1024
	ds_read_b128 v[166:169], v158 offset:2048
	ds_read_b128 v[170:173], v158 offset:3072
	ds_read_b128 v[174:177], v159
	ds_read_b128 v[178:181], v159 offset:1024
	ds_read_b128 v[182:185], v159 offset:2048
	ds_read_b128 v[186:189], v159 offset:3072
	s_add_u32 s68, s34, 0xfff00080
	s_addc_u32 s69, s35, -1
	s_cmp_eq_u32 s67, 60
	s_cselect_b32 s87, s21, s69
	s_cselect_b32 s86, s27, s68
	s_cselect_b32 s85, s19, s66
	s_cselect_b32 s84, s31, s65
	s_add_i32 m0, s53, 0xc000
	ds_read_b128 v[190:193], v160
	ds_read_b128 v[194:197], v160 offset:1024
	ds_read_b128 v[198:201], v160 offset:2048
	ds_read_b128 v[202:205], v160 offset:3072
	ds_read_b128 v[206:209], v160 offset:4096
	ds_read_b128 v[210:213], v160 offset:5120
	ds_read_b128 v[214:217], v160 offset:6144
	ds_read_b128 v[218:221], v160 offset:7168
	global_load_lds_dwordx4 v140, s[34:35]
	s_add_i32 m0, s53, 0xe000
	s_nop 0
	global_load_lds_dwordx4 v142, s[34:35]
	s_waitcnt vmcnt(8)
	s_waitcnt lgkmcnt(0)
	s_barrier
; #define PG8_STAGE(bufoff, gbase, voff) do { _Pragma("unroll") for (int _i = 0; _i < 2; ++_i) \
;         __builtin_amdgcn_global_load_lds((const unsigned*)((const char*)(gbase) + (voff)[_i]), (PG8_LAS unsigned*)(lds + (bufoff) + ldsw + _i * 8192), 16, 0, 0); } while (0)
; #define PG8_LDA(dst, b, h) do { _Pragma("unroll") for (int m = 0; m < 4; ++m) _Pragma("unroll") for (int k = 0; k < 2; ++k) dst[m][k] = *(const PG8_LAS bf16x8*)(lds + PG8_SA(b, h) + aoff + m * 2048 + k * 1024); } while (0)
; #define PG8_MMA(ai, bj, At, Bt) do { __builtin_amdgcn_s_setprio(1); _Pragma("unroll") for (int m = 0; m < 4; ++m) _Pragma("unroll") for (int n = 0; n < 2; ++n) _Pragma("unroll") for (int k = 0; k < 2; ++k) \
;         acc[ai][bj][m][n] = __builtin_amdgcn_mfma_f32_16x16x32_bf16(Bt[n][k], At[m][k], acc[ai][bj][m][n], 0, 0, 0); __builtin_amdgcn_s_setprio(0); } while (0)
; #define PG8_WAIT_V(n) asm volatile("s_waitcnt vmcnt(" #n ")" ::: "memory")
; #define PG8_WAIT_L(n) asm volatile("s_waitcnt lgkmcnt(" #n ")" ::: "memory")
; #define PG8_BAR __builtin_amdgcn_s_barrier()
; #define PG8_SCHED __builtin_amdgcn_sched_barrier(0)
; template <class Epi, class Sched, bool ALIGN_EPI = false, bool SP2 = false>
; __device__ __forceinline__ void gemm_phase(PG8_LAS unsigned char* lds, const Gemm g, const Sched& S, const Epi& E) {
;     ...
;             PG8_WAIT_V(8); PG8_WAIT_L(0); PG8_BAR; PG8_MMA(0, 0, At, B0); PG8_MMA(0, 1, At, B1); PG8_BAR; PG8_SCHED;
;             PG8_LDA(At, 0, 1); PG8_STAGE(PG8_SB(0, 0), b2, voffB); PG8_STAGE(PG8_SB(0, 1), b2 + hstep, voffB); PG8_STAGE(PG8_SA(0, 0), a2, voffA);
;             PG8_WAIT_V(8); PG8_WAIT_L(0); PG8_BAR; PG8_MMA(1, 0, At, B0); PG8_MMA(1, 1, At, B1); PG8_BAR; PG8_SCHED;
	v_mfma_f32_16x16x32_bf16 v[124:127], v[150:153], v[190:193], v[124:127]
	v_mfma_f32_16x16x32_bf16 v[120:123], v[166:169], v[190:193], v[120:123]
	v_mfma_f32_16x16x32_bf16 v[108:111], v[150:153], v[198:201], v[108:111]
	v_mfma_f32_16x16x32_bf16 v[104:107], v[166:169], v[198:201], v[104:107]
	v_mfma_f32_16x16x32_bf16 v[92:95], v[150:153], v[206:209], v[92:95]
	v_mfma_f32_16x16x32_bf16 v[88:91], v[166:169], v[206:209], v[88:91]
	v_mfma_f32_16x16x32_bf16 v[76:79], v[150:153], v[214:217], v[76:79]
	v_mfma_f32_16x16x32_bf16 v[72:75], v[166:169], v[214:217], v[72:75]
	v_mfma_f32_16x16x32_bf16 v[124:127], v[162:165], v[194:197], v[124:127]
	v_mfma_f32_16x16x32_bf16 v[120:123], v[170:173], v[194:197], v[120:123]
	v_mfma_f32_16x16x32_bf16 v[108:111], v[162:165], v[202:205], v[108:111]
	v_mfma_f32_16x16x32_bf16 v[104:107], v[170:173], v[202:205], v[104:107]
	v_mfma_f32_16x16x32_bf16 v[92:95], v[162:165], v[210:213], v[92:95]
	v_mfma_f32_16x16x32_bf16 v[88:91], v[170:173], v[210:213], v[88:91]
	v_mfma_f32_16x16x32_bf16 v[76:79], v[162:165], v[218:221], v[76:79]
	v_mfma_f32_16x16x32_bf16 v[72:75], v[170:173], v[218:221], v[72:75]
	v_mfma_f32_16x16x32_bf16 v[116:119], v[174:177], v[190:193], v[116:119]
	v_mfma_f32_16x16x32_bf16 v[112:115], v[182:185], v[190:193], v[112:115]
	v_mfma_f32_16x16x32_bf16 v[100:103], v[174:177], v[198:201], v[100:103]
	v_mfma_f32_16x16x32_bf16 v[96:99], v[182:185], v[198:201], v[96:99]
	v_mfma_f32_16x16x32_bf16 v[84:87], v[174:177], v[206:209], v[84:87]
	v_mfma_f32_16x16x32_bf16 v[80:83], v[182:185], v[206:209], v[80:83]
	v_mfma_f32_16x16x32_bf16 v[68:71], v[174:177], v[214:217], v[68:71]
	v_mfma_f32_16x16x32_bf16 v[64:67], v[182:185], v[214:217], v[64:67]
	v_mfma_f32_16x16x32_bf16 v[116:119], v[178:181], v[194:197], v[116:119]
	v_mfma_f32_16x16x32_bf16 v[112:115], v[186:189], v[194:197], v[112:115]
	v_mfma_f32_16x16x32_bf16 v[100:103], v[178:181], v[202:205], v[100:103]
	v_mfma_f32_16x16x32_bf16 v[96:99], v[186:189], v[202:205], v[96:99]
	v_mfma_f32_16x16x32_bf16 v[84:87], v[178:181], v[210:213], v[84:87]
	v_mfma_f32_16x16x32_bf16 v[80:83], v[186:189], v[210:213], v[80:83]
	v_mfma_f32_16x16x32_bf16 v[68:71], v[178:181], v[218:221], v[68:71]
	v_mfma_f32_16x16x32_bf16 v[64:67], v[186:189], v[218:221], v[64:67]
	s_barrier
	s_add_u32 s98, s84, s12
	s_addc_u32 s99, s85, s13
	s_add_u32 s100, s86, s12
	s_addc_u32 s101, s87, s13
	s_add_i32 s68, s62, s33
	s_mov_b32 m0, s68
	ds_read_b128 v[190:193], v160 offset:16384
	ds_read_b128 v[194:197], v160 offset:17408
	ds_read_b128 v[198:201], v160 offset:18432
	ds_read_b128 v[202:205], v160 offset:19456
	ds_read_b128 v[206:209], v160 offset:20480
	ds_read_b128 v[210:213], v160 offset:21504
	ds_read_b128 v[214:217], v160 offset:22528
	ds_read_b128 v[218:221], v160 offset:23552
	global_load_lds_dwordx4 v132, s[84:85]
	s_add_i32 m0, s68, 0x2000
	s_add_u32 s68, s84, 0x100000
	s_addc_u32 s69, s85, 0
	s_add_i32 s70, s63, s33
	global_load_lds_dwordx4 v128, s[84:85]
	s_mov_b32 m0, s70
	s_nop 0
	global_load_lds_dwordx4 v132, s[68:69]
	s_add_i32 m0, s70, 0x2000
	s_nop 0
	global_load_lds_dwordx4 v128, s[68:69]
	s_mov_b32 m0, s53
	s_nop 0
	global_load_lds_dwordx4 v134, s[86:87]
	s_mov_b32 m0, s54
	s_nop 0
	global_load_lds_dwordx4 v130, s[86:87]
	s_waitcnt vmcnt(8)
	s_waitcnt lgkmcnt(0)
	s_barrier
	v_mfma_f32_16x16x32_bf16 v[60:63], v[150:153], v[190:193], v[60:63]
	v_mfma_f32_16x16x32_bf16 v[56:59], v[166:169], v[190:193], v[56:59]
	v_mfma_f32_16x16x32_bf16 v[44:47], v[150:153], v[198:201], v[44:47]
	v_mfma_f32_16x16x32_bf16 v[40:43], v[166:169], v[198:201], v[40:43]
	v_mfma_f32_16x16x32_bf16 v[28:31], v[150:153], v[206:209], v[28:31]
	v_mfma_f32_16x16x32_bf16 v[24:27], v[166:169], v[206:209], v[24:27]
	v_mfma_f32_16x16x32_bf16 v[12:15], v[150:153], v[214:217], v[12:15]
	v_mfma_f32_16x16x32_bf16 v[8:11], v[166:169], v[214:217], v[8:11]
	v_mfma_f32_16x16x32_bf16 v[60:63], v[162:165], v[194:197], v[60:63]
	v_mfma_f32_16x16x32_bf16 v[56:59], v[170:173], v[194:197], v[56:59]
	v_mfma_f32_16x16x32_bf16 v[44:47], v[162:165], v[202:205], v[44:47]
	v_mfma_f32_16x16x32_bf16 v[40:43], v[170:173], v[202:205], v[40:43]
	v_mfma_f32_16x16x32_bf16 v[28:31], v[162:165], v[210:213], v[28:31]
	v_mfma_f32_16x16x32_bf16 v[24:27], v[170:173], v[210:213], v[24:27]
	v_mfma_f32_16x16x32_bf16 v[12:15], v[162:165], v[218:221], v[12:15]
	v_mfma_f32_16x16x32_bf16 v[8:11], v[170:173], v[218:221], v[8:11]
	v_mfma_f32_16x16x32_bf16 v[52:55], v[174:177], v[190:193], v[52:55]
	v_mfma_f32_16x16x32_bf16 v[48:51], v[182:185], v[190:193], v[48:51]
	v_mfma_f32_16x16x32_bf16 v[36:39], v[174:177], v[198:201], v[36:39]
	v_mfma_f32_16x16x32_bf16 v[32:35], v[182:185], v[198:201], v[32:35]
	v_mfma_f32_16x16x32_bf16 v[20:23], v[174:177], v[206:209], v[20:23]
	v_mfma_f32_16x16x32_bf16 v[16:19], v[182:185], v[206:209], v[16:19]
	v_mfma_f32_16x16x32_bf16 v[4:7], v[174:177], v[214:217], v[4:7]
	v_mfma_f32_16x16x32_bf16 v[0:3], v[182:185], v[214:217], v[0:3]
	v_mfma_f32_16x16x32_bf16 v[52:55], v[178:181], v[194:197], v[52:55]
	v_mfma_f32_16x16x32_bf16 v[48:51], v[186:189], v[194:197], v[48:51]
	v_mfma_f32_16x16x32_bf16 v[36:39], v[178:181], v[202:205], v[36:39]
	v_mfma_f32_16x16x32_bf16 v[32:35], v[186:189], v[202:205], v[32:35]
	v_mfma_f32_16x16x32_bf16 v[20:23], v[178:181], v[210:213], v[20:23]
	v_mfma_f32_16x16x32_bf16 v[16:19], v[186:189], v[210:213], v[16:19]
	v_mfma_f32_16x16x32_bf16 v[4:7], v[178:181], v[218:221], v[4:7]
	v_mfma_f32_16x16x32_bf16 v[0:3], v[186:189], v[218:221], v[0:3]
	s_barrier
; #define PG8_STAGE(bufoff, gbase, voff) do { _Pragma("unroll") for (int _i = 0; _i < 2; ++_i) \
;         __builtin_amdgcn_global_load_lds((const unsigned*)((const char*)(gbase) + (voff)[_i]), (PG8_LAS unsigned*)(lds + (bufoff) + ldsw + _i * 8192), 16, 0, 0); } while (0)
; #define PG8_LDA(dst, b, h) do { _Pragma("unroll") for (int m = 0; m < 4; ++m) _Pragma("unroll") for (int k = 0; k < 2; ++k) dst[m][k] = *(const PG8_LAS bf16x8*)(lds + PG8_SA(b, h) + aoff + m * 2048 + k * 1024); } while (0)
; #define PG8_LDB(dst, b, h) do { _Pragma("unroll") for (int n = 0; n < 2; ++n) _Pragma("unroll") for (int k = 0; k < 2; ++k) dst[n][k] = *(const PG8_LAS bf16x8*)(lds + PG8_SB(b, h) + boff + n * 2048 + k * 1024); } while (0)
; #define PG8_MMA(ai, bj, At, Bt) do { __builtin_amdgcn_s_setprio(1); _Pragma("unroll") for (int m = 0; m < 4; ++m) _Pragma("unroll") for (int n = 0; n < 2; ++n) _Pragma("unroll") for (int k = 0; k < 2; ++k) \
;         acc[ai][bj][m][n] = __builtin_amdgcn_mfma_f32_16x16x32_bf16(Bt[n][k], At[m][k], acc[ai][bj][m][n], 0, 0, 0); __builtin_amdgcn_s_setprio(0); } while (0)
; #define PG8_WAIT_V(n) asm volatile("s_waitcnt vmcnt(" #n ")" ::: "memory")
; #define PG8_WAIT_L(n) asm volatile("s_waitcnt lgkmcnt(" #n ")" ::: "memory")
; #define PG8_BAR __builtin_amdgcn_s_barrier()
; #define PG8_SCHED __builtin_amdgcn_sched_barrier(0)
; template <class Epi, class Sched, bool ALIGN_EPI = false, bool SP2 = false>
; __device__ __forceinline__ void gemm_phase(PG8_LAS unsigned char* lds, const Gemm g, const Sched& S, const Epi& E) {
;     ...
;         for (int t = 0; t < nt; t += 2) {
;     ...
;             PG8_LDB(B0, 1, 0); PG8_LDB(B1, 1, 1); PG8_SCHED; PG8_LDA(At, 1, 0); PG8_STAGE(PG8_SA(0, 1), a2 + hstepA, voffA);
;             PG8_WAIT_V(8); PG8_WAIT_L(0); PG8_BAR; PG8_MMA(0, 0, At, B0); PG8_MMA(0, 1, At, B1); PG8_BAR; PG8_SCHED;
;             PG8_LDA(At, 1, 1); PG8_STAGE(PG8_SB(1, 0), b3, voffB); PG8_STAGE(PG8_SB(1, 1), b3 + hstep, voffB); PG8_STAGE(PG8_SA(1, 0), a3, voffA);
;             PG8_WAIT_V(8); PG8_WAIT_L(0); PG8_BAR; PG8_MMA(1, 0, At, B0); PG8_MMA(1, 1, At, B1); PG8_BAR; PG8_SCHED;
	s_add_i32 s70, 0, 0x18000
	s_add_i32 s71, 0, 0x1c000
	ds_read_b128 v[150:153], v154
	ds_read_b128 v[162:165], v154 offset:1024
	ds_read_b128 v[166:169], v154 offset:2048
	ds_read_b128 v[170:173], v154 offset:3072
	ds_read_b128 v[174:177], v155
	ds_read_b128 v[178:181], v155 offset:1024
	ds_read_b128 v[182:185], v155 offset:2048
	ds_read_b128 v[186:189], v155 offset:3072
	s_add_u32 s68, s86, 0x100000
	s_addc_u32 s69, s87, 0
	s_mov_b32 m0, s55
	ds_read_b128 v[190:193], v160 offset:32768
	ds_read_b128 v[194:197], v160 offset:33792
	ds_read_b128 v[198:201], v160 offset:34816
	ds_read_b128 v[202:205], v160 offset:35840
	ds_read_b128 v[206:209], v160 offset:36864
	ds_read_b128 v[210:213], v160 offset:37888
	ds_read_b128 v[214:217], v160 offset:38912
	ds_read_b128 v[218:221], v160 offset:39936
	global_load_lds_dwordx4 v134, s[68:69]
	s_mov_b32 m0, s56
	s_nop 0
	global_load_lds_dwordx4 v130, s[68:69]
	s_waitcnt vmcnt(8)
	s_waitcnt lgkmcnt(0)
	s_barrier
	v_mfma_f32_16x16x32_bf16 v[124:127], v[150:153], v[190:193], v[124:127]
	v_mfma_f32_16x16x32_bf16 v[120:123], v[166:169], v[190:193], v[120:123]
	v_mfma_f32_16x16x32_bf16 v[108:111], v[150:153], v[198:201], v[108:111]
	v_mfma_f32_16x16x32_bf16 v[104:107], v[166:169], v[198:201], v[104:107]
	v_mfma_f32_16x16x32_bf16 v[92:95], v[150:153], v[206:209], v[92:95]
	v_mfma_f32_16x16x32_bf16 v[88:91], v[166:169], v[206:209], v[88:91]
	v_mfma_f32_16x16x32_bf16 v[76:79], v[150:153], v[214:217], v[76:79]
	v_mfma_f32_16x16x32_bf16 v[72:75], v[166:169], v[214:217], v[72:75]
	v_mfma_f32_16x16x32_bf16 v[124:127], v[162:165], v[194:197], v[124:127]
	v_mfma_f32_16x16x32_bf16 v[120:123], v[170:173], v[194:197], v[120:123]
	v_mfma_f32_16x16x32_bf16 v[108:111], v[162:165], v[202:205], v[108:111]
	v_mfma_f32_16x16x32_bf16 v[104:107], v[170:173], v[202:205], v[104:107]
	v_mfma_f32_16x16x32_bf16 v[92:95], v[162:165], v[210:213], v[92:95]
	v_mfma_f32_16x16x32_bf16 v[88:91], v[170:173], v[210:213], v[88:91]
	v_mfma_f32_16x16x32_bf16 v[76:79], v[162:165], v[218:221], v[76:79]
	v_mfma_f32_16x16x32_bf16 v[72:75], v[170:173], v[218:221], v[72:75]
	v_mfma_f32_16x16x32_bf16 v[116:119], v[174:177], v[190:193], v[116:119]
	v_mfma_f32_16x16x32_bf16 v[112:115], v[182:185], v[190:193], v[112:115]
	v_mfma_f32_16x16x32_bf16 v[100:103], v[174:177], v[198:201], v[100:103]
	v_mfma_f32_16x16x32_bf16 v[96:99], v[182:185], v[198:201], v[96:99]
	v_mfma_f32_16x16x32_bf16 v[84:87], v[174:177], v[206:209], v[84:87]
	v_mfma_f32_16x16x32_bf16 v[80:83], v[182:185], v[206:209], v[80:83]
	v_mfma_f32_16x16x32_bf16 v[68:71], v[174:177], v[214:217], v[68:71]
	v_mfma_f32_16x16x32_bf16 v[64:67], v[182:185], v[214:217], v[64:67]
	v_mfma_f32_16x16x32_bf16 v[116:119], v[178:181], v[194:197], v[116:119]
	v_mfma_f32_16x16x32_bf16 v[112:115], v[186:189], v[194:197], v[112:115]
	v_mfma_f32_16x16x32_bf16 v[100:103], v[178:181], v[202:205], v[100:103]
	v_mfma_f32_16x16x32_bf16 v[96:99], v[186:189], v[202:205], v[96:99]
	v_mfma_f32_16x16x32_bf16 v[84:87], v[178:181], v[210:213], v[84:87]
	v_mfma_f32_16x16x32_bf16 v[80:83], v[186:189], v[210:213], v[80:83]
	v_mfma_f32_16x16x32_bf16 v[68:71], v[178:181], v[218:221], v[68:71]
	v_mfma_f32_16x16x32_bf16 v[64:67], v[186:189], v[218:221], v[64:67]
	s_barrier
	s_add_i32 s68, s70, s33
	s_mov_b32 m0, s68
	ds_read_b128 v[190:193], v160 offset:49152
	ds_read_b128 v[194:197], v160 offset:50176
	ds_read_b128 v[198:201], v160 offset:51200
	ds_read_b128 v[202:205], v160 offset:52224
	ds_read_b128 v[206:209], v160 offset:53248
	ds_read_b128 v[210:213], v160 offset:54272
	ds_read_b128 v[214:217], v160 offset:55296
	ds_read_b128 v[218:221], v160 offset:56320
	global_load_lds_dwordx4 v132, s[98:99]
	s_add_i32 m0, s68, 0x2000
	s_add_u32 s68, s84, 0x100080
	s_addc_u32 s69, s85, 0
	s_add_i32 s70, s71, s33
	global_load_lds_dwordx4 v128, s[98:99]
	s_mov_b32 m0, s70
	s_nop 0
	global_load_lds_dwordx4 v132, s[68:69]
	s_add_i32 m0, s70, 0x2000
	s_nop 0
	global_load_lds_dwordx4 v128, s[68:69]
	s_mov_b32 m0, s60
	s_nop 0
	global_load_lds_dwordx4 v134, s[100:101]
	s_mov_b32 m0, s61
	s_nop 0
	global_load_lds_dwordx4 v130, s[100:101]
	s_waitcnt vmcnt(8)
	s_waitcnt lgkmcnt(0)
	s_barrier
	v_mfma_f32_16x16x32_bf16 v[60:63], v[150:153], v[190:193], v[60:63]
	v_mfma_f32_16x16x32_bf16 v[56:59], v[166:169], v[190:193], v[56:59]
	v_mfma_f32_16x16x32_bf16 v[44:47], v[150:153], v[198:201], v[44:47]
	v_mfma_f32_16x16x32_bf16 v[40:43], v[166:169], v[198:201], v[40:43]
	v_mfma_f32_16x16x32_bf16 v[28:31], v[150:153], v[206:209], v[28:31]
	v_mfma_f32_16x16x32_bf16 v[24:27], v[166:169], v[206:209], v[24:27]
	v_mfma_f32_16x16x32_bf16 v[12:15], v[150:153], v[214:217], v[12:15]
	v_mfma_f32_16x16x32_bf16 v[8:11], v[166:169], v[214:217], v[8:11]
	v_mfma_f32_16x16x32_bf16 v[60:63], v[162:165], v[194:197], v[60:63]
	v_mfma_f32_16x16x32_bf16 v[56:59], v[170:173], v[194:197], v[56:59]
	v_mfma_f32_16x16x32_bf16 v[44:47], v[162:165], v[202:205], v[44:47]
	v_mfma_f32_16x16x32_bf16 v[40:43], v[170:173], v[202:205], v[40:43]
	v_mfma_f32_16x16x32_bf16 v[28:31], v[162:165], v[210:213], v[28:31]
	v_mfma_f32_16x16x32_bf16 v[24:27], v[170:173], v[210:213], v[24:27]
	v_mfma_f32_16x16x32_bf16 v[12:15], v[162:165], v[218:221], v[12:15]
	v_mfma_f32_16x16x32_bf16 v[8:11], v[170:173], v[218:221], v[8:11]
	v_mfma_f32_16x16x32_bf16 v[52:55], v[174:177], v[190:193], v[52:55]
	v_mfma_f32_16x16x32_bf16 v[48:51], v[182:185], v[190:193], v[48:51]
	v_mfma_f32_16x16x32_bf16 v[36:39], v[174:177], v[198:201], v[36:39]
	v_mfma_f32_16x16x32_bf16 v[32:35], v[182:185], v[198:201], v[32:35]
	v_mfma_f32_16x16x32_bf16 v[20:23], v[174:177], v[206:209], v[20:23]
	v_mfma_f32_16x16x32_bf16 v[16:19], v[182:185], v[206:209], v[16:19]
	v_mfma_f32_16x16x32_bf16 v[4:7], v[174:177], v[214:217], v[4:7]
	v_mfma_f32_16x16x32_bf16 v[0:3], v[182:185], v[214:217], v[0:3]
	v_mfma_f32_16x16x32_bf16 v[52:55], v[178:181], v[194:197], v[52:55]
	v_mfma_f32_16x16x32_bf16 v[48:51], v[186:189], v[194:197], v[48:51]
	v_mfma_f32_16x16x32_bf16 v[36:39], v[178:181], v[202:205], v[36:39]
	v_mfma_f32_16x16x32_bf16 v[32:35], v[186:189], v[202:205], v[32:35]
	v_mfma_f32_16x16x32_bf16 v[20:23], v[178:181], v[210:213], v[20:23]
	v_mfma_f32_16x16x32_bf16 v[16:19], v[186:189], v[210:213], v[16:19]
	v_mfma_f32_16x16x32_bf16 v[4:7], v[178:181], v[218:221], v[4:7]
	v_mfma_f32_16x16x32_bf16 v[0:3], v[186:189], v[218:221], v[0:3]
	s_barrier
	s_add_i32 s67, s67, 2
	s_add_u32 s34, s34, 0x100
	s_addc_u32 s35, s35, 0
	s_add_u32 s65, s65, 0x100
	s_addc_u32 s66, s66, 0
	s_cmp_gt_u32 s67, 61
	s_cbranch_scc0 .LBB0_115
	s_and_b64 vcc, exec, s[14:15]
	s_cbranch_vccz .LBB0_118
	s_barrier

; #define PG8_STAGE(bufoff, gbase, voff) do { _Pragma("unroll") for (int _i = 0; _i < 2; ++_i) \
;         __builtin_amdgcn_global_load_lds((const unsigned*)((const char*)(gbase) + (voff)[_i]), (PG8_LAS unsigned*)(lds + (bufoff) + ldsw + _i * 8192), 16, 0, 0); } while (0)
; #define PG8_LDA(dst, b, h) do { _Pragma("unroll") for (int m = 0; m < 4; ++m) _Pragma("unroll") for (int k = 0; k < 2; ++k) dst[m][k] = *(const PG8_LAS bf16x8*)(lds + PG8_SA(b, h) + aoff + m * 2048 + k * 1024); } while (0)
; #define PG8_LDB(dst, b, h) do { _Pragma("unroll") for (int n = 0; n < 2; ++n) _Pragma("unroll") for (int k = 0; k < 2; ++k) dst[n][k] = *(const PG8_LAS bf16x8*)(lds + PG8_SB(b, h) + boff + n * 2048 + k * 1024); } while (0)
; #define PG8_WAIT_V(n) asm volatile("s_waitcnt vmcnt(" #n ")" ::: "memory")
; #define PG8_WAIT_L(n) asm volatile("s_waitcnt lgkmcnt(" #n ")" ::: "memory")
; #define PG8_BAR __builtin_amdgcn_s_barrier()
; template <class Epi, class Sched, bool ALIGN_EPI = false, bool SP2 = false>
; __device__ __forceinline__ void gemm_phase(PG8_LAS unsigned char* lds, const Gemm g, const Sched& S, const Epi& E) {
;     ...
;         const bool has_next = S.next(ui + 1, nxt);
;         const char* nA = has_next ? (const char*)g.A + (size_t)nxt.pm * tstep : cA; const char* nB = has_next ? (const char*)g.Bt + (size_t)nxt.pn * tstep : cB;
;         for (int t = 0; t < nt; t += 2) {
;             const bool last = (t == nt - 2);
;             const char* a1 = cA + (size_t)(t + 1) * kstepA;
;             const char* a2 = last ? nA : cA + (size_t)(t + 2) * kstepA; const char* b2 = last ? nB : cB + (size_t)(t + 2) * kstep;
;             const char* a3 = a2 + kstepA; const char* b3 = b2 + kstep;
;             if (last && has_next) S.a_ready(nxt);
;             if constexpr (SP2) {
;             PG8_LDB(B0, 0, 0); PG8_LDB(B1, 0, 1); PG8_SCHED; PG8_LDA(At, 0, 0); PG8_STAGE(PG8_SA(1, 1), a1 + hstepA, voffA);
;             PG8_WAIT_V(8); PG8_WAIT_L(0); PG8_BAR; PG8_MMA(0, 0, At, B0); PG8_MMA(0, 1, At, B1); PG8_BAR; PG8_SCHED;
;     ...
; #pragma unroll
;         for (int a = 0; a < 2; ++a)
; #pragma unroll
;             for (int b = 0; b < 2; ++b)
; #pragma unroll
;                 for (int m = 0; m < 4; ++m)
; #pragma unroll
;                     for (int n = 0; n < 2; ++n) acc[a][b][m][n] = (f32x4){0.f, 0.f, 0.f, 0.f};
;         cur = nxt; cA = nA; cB = nB; ++ui;
.LBB0_1197:
	s_ashr_i32 s21, s20, 31
	s_lshl_b64 s[22:23], s[20:21], 21
	s_add_u32 s22, s3, s22
	s_addc_u32 s23, s29, s23
	s_and_b64 s[24:25], s[4:5], exec
	s_cselect_b32 s21, s23, s35
	s_cselect_b32 s27, s22, s34
	s_ashr_i32 s19, s18, 31
	s_lshl_b64 s[24:25], s[18:19], 21
	s_add_u32 s24, s10, s24
	s_addc_u32 s25, s11, s25
	s_and_b64 s[40:41], s[4:5], exec
	s_cselect_b32 s19, s25, s39
	s_cselect_b32 s62, s24, s38
	s_add_u32 s34, s34, 0x100080
	s_addc_u32 s35, s35, 0
	s_add_u32 s63, s38, 0x100
	v_mov_b32_e32 v0, 0
	s_addc_u32 s64, s39, 0
	s_mov_b32 s65, -2
	s_waitcnt lgkmcnt(0)
	v_mov_b32_e32 v1, v0
	v_mov_b32_e32 v2, v0
	v_mov_b32_e32 v3, v0
	v_mov_b32_e32 v4, v0
	v_mov_b32_e32 v5, v0
	v_mov_b32_e32 v6, v0
	v_mov_b32_e32 v7, v0
	v_mov_b32_e32 v16, v0
	v_mov_b32_e32 v17, v0
	v_mov_b32_e32 v18, v0
	v_mov_b32_e32 v19, v0
	v_mov_b32_e32 v20, v0
	v_mov_b32_e32 v21, v0
	v_mov_b32_e32 v22, v0
	v_mov_b32_e32 v23, v0
	v_mov_b32_e32 v32, v0
	v_mov_b32_e32 v33, v0
	v_mov_b32_e32 v34, v0
	v_mov_b32_e32 v35, v0
	s_waitcnt vmcnt(0)
	v_mov_b32_e32 v36, v0
	v_mov_b32_e32 v37, v0
	v_mov_b32_e32 v38, v0
	v_mov_b32_e32 v39, v0
	v_mov_b32_e32 v56, v0
	v_mov_b32_e32 v57, v0
	v_mov_b32_e32 v58, v0
	v_mov_b32_e32 v59, v0
	v_mov_b32_e32 v60, v0
	v_mov_b32_e32 v61, v0
	v_mov_b32_e32 v62, v0
	v_mov_b32_e32 v63, v0
	v_mov_b32_e32 v8, v0
	v_mov_b32_e32 v9, v0
	v_mov_b32_e32 v10, v0
	v_mov_b32_e32 v11, v0
	v_mov_b32_e32 v12, v0
	v_mov_b32_e32 v13, v0
	v_mov_b32_e32 v14, v0
	v_mov_b32_e32 v15, v0
	v_mov_b32_e32 v24, v0
	v_mov_b32_e32 v25, v0
	v_mov_b32_e32 v26, v0
	v_mov_b32_e32 v27, v0
	v_mov_b32_e32 v28, v0
	v_mov_b32_e32 v29, v0
	v_mov_b32_e32 v30, v0
	v_mov_b32_e32 v31, v0
	v_mov_b32_e32 v40, v0
	v_mov_b32_e32 v41, v0
	v_mov_b32_e32 v42, v0
	v_mov_b32_e32 v43, v0
	v_mov_b32_e32 v44, v0
	v_mov_b32_e32 v45, v0
	v_mov_b32_e32 v46, v0
	v_mov_b32_e32 v47, v0
	v_mov_b32_e32 v68, v0
	v_mov_b32_e32 v69, v0
	v_mov_b32_e32 v70, v0
	v_mov_b32_e32 v71, v0
	v_mov_b32_e32 v72, v0
	v_mov_b32_e32 v73, v0
	v_mov_b32_e32 v74, v0
	v_mov_b32_e32 v75, v0
	v_mov_b32_e32 v84, v0
	v_mov_b32_e32 v85, v0
	v_mov_b32_e32 v86, v0
	v_mov_b32_e32 v87, v0
	v_mov_b32_e32 v88, v0
	v_mov_b32_e32 v89, v0
	v_mov_b32_e32 v90, v0
	v_mov_b32_e32 v91, v0
	v_mov_b32_e32 v76, v0
	v_mov_b32_e32 v77, v0
	v_mov_b32_e32 v78, v0
	v_mov_b32_e32 v79, v0
	v_mov_b32_e32 v96, v0
	v_mov_b32_e32 v97, v0
	v_mov_b32_e32 v98, v0
	v_mov_b32_e32 v99, v0
	v_mov_b32_e32 v52, v0
	v_mov_b32_e32 v53, v0
	v_mov_b32_e32 v54, v0
	v_mov_b32_e32 v55, v0
	v_mov_b32_e32 v104, v0
	v_mov_b32_e32 v105, v0
	v_mov_b32_e32 v106, v0
	v_mov_b32_e32 v107, v0
	v_mov_b32_e32 v112, v0
	v_mov_b32_e32 v113, v0
	v_mov_b32_e32 v114, v0
	v_mov_b32_e32 v115, v0
	v_mov_b32_e32 v116, v0
	v_mov_b32_e32 v117, v0
	v_mov_b32_e32 v118, v0
	v_mov_b32_e32 v119, v0
	v_mov_b32_e32 v80, v0
	v_mov_b32_e32 v81, v0
	v_mov_b32_e32 v82, v0
	v_mov_b32_e32 v83, v0
	v_mov_b32_e32 v92, v0
	v_mov_b32_e32 v93, v0
	v_mov_b32_e32 v94, v0
	v_mov_b32_e32 v95, v0
	v_mov_b32_e32 v64, v0
	v_mov_b32_e32 v65, v0
	v_mov_b32_e32 v66, v0
	v_mov_b32_e32 v67, v0
	v_mov_b32_e32 v100, v0
	v_mov_b32_e32 v101, v0
	v_mov_b32_e32 v102, v0
	v_mov_b32_e32 v103, v0
	v_mov_b32_e32 v48, v0
	v_mov_b32_e32 v49, v0
	v_mov_b32_e32 v50, v0
	v_mov_b32_e32 v51, v0
	v_mov_b32_e32 v108, v0
	v_mov_b32_e32 v109, v0
	v_mov_b32_e32 v110, v0
	v_mov_b32_e32 v111, v0
	v_mov_b32_e32 v120, v0
	v_mov_b32_e32 v121, v0
	v_mov_b32_e32 v122, v0
	v_mov_b32_e32 v123, v0
	v_mov_b32_e32 v124, v0
	v_mov_b32_e32 v125, v0
	v_mov_b32_e32 v126, v0
	v_mov_b32_e32 v127, v0
	v_add_u32_e32 v148, 0x18000, v151
	v_add_u32_e32 v149, 0x1c000, v151
.LBB0_1198:
	ds_read_b128 v[144:147], v153
	ds_read_b128 v[158:161], v153 offset:1024
	ds_read_b128 v[162:165], v153 offset:2048
	ds_read_b128 v[166:169], v153 offset:3072
	ds_read_b128 v[170:173], v154
	ds_read_b128 v[174:177], v154 offset:1024
	ds_read_b128 v[178:181], v154 offset:2048
	ds_read_b128 v[182:185], v154 offset:3072
	s_add_u32 s38, s34, 0xfff00080
	s_addc_u32 s39, s35, -1
	s_cmp_eq_u32 s65, 60
	s_cselect_b32 s41, s21, s39
	s_cselect_b32 s40, s27, s38
	s_cselect_b32 s39, s19, s64
	s_cselect_b32 s38, s62, s63
	s_add_i32 m0, s31, 0xc000
	ds_read_b128 v[186:189], v155
	ds_read_b128 v[190:193], v155 offset:1024
	ds_read_b128 v[194:197], v155 offset:2048
	ds_read_b128 v[198:201], v155 offset:3072
	ds_read_b128 v[202:205], v155 offset:4096
	ds_read_b128 v[206:209], v155 offset:5120
	ds_read_b128 v[210:213], v155 offset:6144
	ds_read_b128 v[214:217], v155 offset:7168
	global_load_lds_dwordx4 v136, s[34:35]
	s_add_i32 m0, s31, 0xe000
	s_nop 0
	global_load_lds_dwordx4 v138, s[34:35]
	s_waitcnt vmcnt(8)
	s_waitcnt lgkmcnt(0)
	s_barrier
; #define PG8_STAGE(bufoff, gbase, voff) do { _Pragma("unroll") for (int _i = 0; _i < 2; ++_i) \
;         __builtin_amdgcn_global_load_lds((const unsigned*)((const char*)(gbase) + (voff)[_i]), (PG8_LAS unsigned*)(lds + (bufoff) + ldsw + _i * 8192), 16, 0, 0); } while (0)
; #define PG8_LDA(dst, b, h) do { _Pragma("unroll") for (int m = 0; m < 4; ++m) _Pragma("unroll") for (int k = 0; k < 2; ++k) dst[m][k] = *(const PG8_LAS bf16x8*)(lds + PG8_SA(b, h) + aoff + m * 2048 + k * 1024); } while (0)
; #define PG8_MMA(ai, bj, At, Bt) do { __builtin_amdgcn_s_setprio(1); _Pragma("unroll") for (int m = 0; m < 4; ++m) _Pragma("unroll") for (int n = 0; n < 2; ++n) _Pragma("unroll") for (int k = 0; k < 2; ++k) \
;         acc[ai][bj][m][n] = __builtin_amdgcn_mfma_f32_16x16x32_bf16(Bt[n][k], At[m][k], acc[ai][bj][m][n], 0, 0, 0); __builtin_amdgcn_s_setprio(0); } while (0)
; #define PG8_WAIT_V(n) asm volatile("s_waitcnt vmcnt(" #n ")" ::: "memory")
; #define PG8_WAIT_L(n) asm volatile("s_waitcnt lgkmcnt(" #n ")" ::: "memory")
; #define PG8_BAR __builtin_amdgcn_s_barrier()
; #define PG8_SCHED __builtin_amdgcn_sched_barrier(0)
; template <class Epi, class Sched, bool ALIGN_EPI = false, bool SP2 = false>
; __device__ __forceinline__ void gemm_phase(PG8_LAS unsigned char* lds, const Gemm g, const Sched& S, const Epi& E) {
;     ...
;             PG8_WAIT_V(8); PG8_WAIT_L(0); PG8_BAR; PG8_MMA(0, 0, At, B0); PG8_MMA(0, 1, At, B1); PG8_BAR; PG8_SCHED;
;             PG8_LDA(At, 0, 1); PG8_STAGE(PG8_SB(0, 0), b2, voffB); PG8_STAGE(PG8_SB(0, 1), b2 + hstep, voffB); PG8_STAGE(PG8_SA(0, 0), a2, voffA);
;             PG8_WAIT_V(8); PG8_WAIT_L(0); PG8_BAR; PG8_MMA(1, 0, At, B0); PG8_MMA(1, 1, At, B1); PG8_BAR; PG8_SCHED;
	v_mfma_f32_16x16x32_bf16 v[124:127], v[144:147], v[186:189], v[124:127]
	v_mfma_f32_16x16x32_bf16 v[120:123], v[162:165], v[186:189], v[120:123]
	v_mfma_f32_16x16x32_bf16 v[108:111], v[144:147], v[194:197], v[108:111]
	v_mfma_f32_16x16x32_bf16 v[48:51], v[162:165], v[194:197], v[48:51]
	v_mfma_f32_16x16x32_bf16 v[100:103], v[144:147], v[202:205], v[100:103]
	v_mfma_f32_16x16x32_bf16 v[64:67], v[162:165], v[202:205], v[64:67]
	v_mfma_f32_16x16x32_bf16 v[92:95], v[144:147], v[210:213], v[92:95]
	v_mfma_f32_16x16x32_bf16 v[80:83], v[162:165], v[210:213], v[80:83]
	v_mfma_f32_16x16x32_bf16 v[124:127], v[158:161], v[190:193], v[124:127]
	v_mfma_f32_16x16x32_bf16 v[120:123], v[166:169], v[190:193], v[120:123]
	v_mfma_f32_16x16x32_bf16 v[108:111], v[158:161], v[198:201], v[108:111]
	v_mfma_f32_16x16x32_bf16 v[48:51], v[166:169], v[198:201], v[48:51]
	v_mfma_f32_16x16x32_bf16 v[100:103], v[158:161], v[206:209], v[100:103]
	v_mfma_f32_16x16x32_bf16 v[64:67], v[166:169], v[206:209], v[64:67]
	v_mfma_f32_16x16x32_bf16 v[92:95], v[158:161], v[214:217], v[92:95]
	v_mfma_f32_16x16x32_bf16 v[80:83], v[166:169], v[214:217], v[80:83]
	v_mfma_f32_16x16x32_bf16 v[116:119], v[170:173], v[186:189], v[116:119]
	v_mfma_f32_16x16x32_bf16 v[112:115], v[178:181], v[186:189], v[112:115]
	v_mfma_f32_16x16x32_bf16 v[104:107], v[170:173], v[194:197], v[104:107]
	v_mfma_f32_16x16x32_bf16 v[52:55], v[178:181], v[194:197], v[52:55]
	v_mfma_f32_16x16x32_bf16 v[96:99], v[170:173], v[202:205], v[96:99]
	v_mfma_f32_16x16x32_bf16 v[76:79], v[178:181], v[202:205], v[76:79]
	v_mfma_f32_16x16x32_bf16 v[88:91], v[170:173], v[210:213], v[88:91]
	v_mfma_f32_16x16x32_bf16 v[84:87], v[178:181], v[210:213], v[84:87]
	v_mfma_f32_16x16x32_bf16 v[116:119], v[174:177], v[190:193], v[116:119]
	v_mfma_f32_16x16x32_bf16 v[112:115], v[182:185], v[190:193], v[112:115]
	v_mfma_f32_16x16x32_bf16 v[104:107], v[174:177], v[198:201], v[104:107]
	v_mfma_f32_16x16x32_bf16 v[52:55], v[182:185], v[198:201], v[52:55]
	v_mfma_f32_16x16x32_bf16 v[96:99], v[174:177], v[206:209], v[96:99]
	v_mfma_f32_16x16x32_bf16 v[76:79], v[182:185], v[206:209], v[76:79]
	v_mfma_f32_16x16x32_bf16 v[88:91], v[174:177], v[214:217], v[88:91]
	v_mfma_f32_16x16x32_bf16 v[84:87], v[182:185], v[214:217], v[84:87]
	s_barrier
	s_add_u32 s98, s38, s14
	s_addc_u32 s99, s39, s15
	s_add_u32 s100, s40, s14
	s_addc_u32 s101, s41, s15
	s_add_i32 s66, s60, s33
	s_mov_b32 m0, s66
	ds_read_b128 v[186:189], v155 offset:16384
	ds_read_b128 v[190:193], v155 offset:17408
	ds_read_b128 v[194:197], v155 offset:18432
	ds_read_b128 v[198:201], v155 offset:19456
	ds_read_b128 v[202:205], v155 offset:20480
	ds_read_b128 v[206:209], v155 offset:21504
	ds_read_b128 v[210:213], v155 offset:22528
	ds_read_b128 v[214:217], v155 offset:23552
	global_load_lds_dwordx4 v130, s[38:39]
	s_add_i32 m0, s66, 0x2000
	s_add_u32 s66, s38, 0x100000
	s_addc_u32 s67, s39, 0
	s_add_i32 s68, s61, s33
	global_load_lds_dwordx4 v134, s[38:39]
	s_mov_b32 m0, s68
	s_nop 0
	global_load_lds_dwordx4 v130, s[66:67]
	s_add_i32 m0, s68, 0x2000
	s_nop 0
	global_load_lds_dwordx4 v134, s[66:67]
	s_mov_b32 m0, s31
	s_nop 0
	global_load_lds_dwordx4 v128, s[40:41]
	s_mov_b32 m0, s52
	s_nop 0
	global_load_lds_dwordx4 v132, s[40:41]
	s_waitcnt vmcnt(8)
	s_waitcnt lgkmcnt(0)
	s_barrier
	v_mfma_f32_16x16x32_bf16 v[72:75], v[144:147], v[186:189], v[72:75]
	v_mfma_f32_16x16x32_bf16 v[68:71], v[162:165], v[186:189], v[68:71]
	v_mfma_f32_16x16x32_bf16 v[44:47], v[144:147], v[194:197], v[44:47]
	v_mfma_f32_16x16x32_bf16 v[40:43], v[162:165], v[194:197], v[40:43]
	v_mfma_f32_16x16x32_bf16 v[28:31], v[144:147], v[202:205], v[28:31]
	v_mfma_f32_16x16x32_bf16 v[24:27], v[162:165], v[202:205], v[24:27]
	v_mfma_f32_16x16x32_bf16 v[12:15], v[144:147], v[210:213], v[12:15]
	v_mfma_f32_16x16x32_bf16 v[8:11], v[162:165], v[210:213], v[8:11]
	v_mfma_f32_16x16x32_bf16 v[72:75], v[158:161], v[190:193], v[72:75]
	v_mfma_f32_16x16x32_bf16 v[68:71], v[166:169], v[190:193], v[68:71]
	v_mfma_f32_16x16x32_bf16 v[44:47], v[158:161], v[198:201], v[44:47]
	v_mfma_f32_16x16x32_bf16 v[40:43], v[166:169], v[198:201], v[40:43]
	v_mfma_f32_16x16x32_bf16 v[28:31], v[158:161], v[206:209], v[28:31]
	v_mfma_f32_16x16x32_bf16 v[24:27], v[166:169], v[206:209], v[24:27]
	v_mfma_f32_16x16x32_bf16 v[12:15], v[158:161], v[214:217], v[12:15]
	v_mfma_f32_16x16x32_bf16 v[8:11], v[166:169], v[214:217], v[8:11]
	v_mfma_f32_16x16x32_bf16 v[60:63], v[170:173], v[186:189], v[60:63]
	v_mfma_f32_16x16x32_bf16 v[56:59], v[178:181], v[186:189], v[56:59]
	v_mfma_f32_16x16x32_bf16 v[36:39], v[170:173], v[194:197], v[36:39]
	v_mfma_f32_16x16x32_bf16 v[32:35], v[178:181], v[194:197], v[32:35]
	v_mfma_f32_16x16x32_bf16 v[20:23], v[170:173], v[202:205], v[20:23]
	v_mfma_f32_16x16x32_bf16 v[16:19], v[178:181], v[202:205], v[16:19]
	v_mfma_f32_16x16x32_bf16 v[4:7], v[170:173], v[210:213], v[4:7]
	v_mfma_f32_16x16x32_bf16 v[0:3], v[178:181], v[210:213], v[0:3]
	v_mfma_f32_16x16x32_bf16 v[60:63], v[174:177], v[190:193], v[60:63]
	v_mfma_f32_16x16x32_bf16 v[56:59], v[182:185], v[190:193], v[56:59]
	v_mfma_f32_16x16x32_bf16 v[36:39], v[174:177], v[198:201], v[36:39]
	v_mfma_f32_16x16x32_bf16 v[32:35], v[182:185], v[198:201], v[32:35]
	v_mfma_f32_16x16x32_bf16 v[20:23], v[174:177], v[206:209], v[20:23]
	v_mfma_f32_16x16x32_bf16 v[16:19], v[182:185], v[206:209], v[16:19]
	v_mfma_f32_16x16x32_bf16 v[4:7], v[174:177], v[214:217], v[4:7]
	v_mfma_f32_16x16x32_bf16 v[0:3], v[182:185], v[214:217], v[0:3]
	s_barrier
; #define PG8_STAGE(bufoff, gbase, voff) do { _Pragma("unroll") for (int _i = 0; _i < 2; ++_i) \
;         __builtin_amdgcn_global_load_lds((const unsigned*)((const char*)(gbase) + (voff)[_i]), (PG8_LAS unsigned*)(lds + (bufoff) + ldsw + _i * 8192), 16, 0, 0); } while (0)
; #define PG8_LDA(dst, b, h) do { _Pragma("unroll") for (int m = 0; m < 4; ++m) _Pragma("unroll") for (int k = 0; k < 2; ++k) dst[m][k] = *(const PG8_LAS bf16x8*)(lds + PG8_SA(b, h) + aoff + m * 2048 + k * 1024); } while (0)
; #define PG8_LDB(dst, b, h) do { _Pragma("unroll") for (int n = 0; n < 2; ++n) _Pragma("unroll") for (int k = 0; k < 2; ++k) dst[n][k] = *(const PG8_LAS bf16x8*)(lds + PG8_SB(b, h) + boff + n * 2048 + k * 1024); } while (0)
; #define PG8_MMA(ai, bj, At, Bt) do { __builtin_amdgcn_s_setprio(1); _Pragma("unroll") for (int m = 0; m < 4; ++m) _Pragma("unroll") for (int n = 0; n < 2; ++n) _Pragma("unroll") for (int k = 0; k < 2; ++k) \
;         acc[ai][bj][m][n] = __builtin_amdgcn_mfma_f32_16x16x32_bf16(Bt[n][k], At[m][k], acc[ai][bj][m][n], 0, 0, 0); __builtin_amdgcn_s_setprio(0); } while (0)
; #define PG8_WAIT_V(n) asm volatile("s_waitcnt vmcnt(" #n ")" ::: "memory")
; #define PG8_WAIT_L(n) asm volatile("s_waitcnt lgkmcnt(" #n ")" ::: "memory")
; #define PG8_BAR __builtin_amdgcn_s_barrier()
; #define PG8_SCHED __builtin_amdgcn_sched_barrier(0)
; template <class Epi, class Sched, bool ALIGN_EPI = false, bool SP2 = false>
; __device__ __forceinline__ void gemm_phase(PG8_LAS unsigned char* lds, const Gemm g, const Sched& S, const Epi& E) {
;     ...
;         for (int t = 0; t < nt; t += 2) {
;     ...
;             PG8_LDB(B0, 1, 0); PG8_LDB(B1, 1, 1); PG8_SCHED; PG8_LDA(At, 1, 0); PG8_STAGE(PG8_SA(0, 1), a2 + hstepA, voffA);
;             PG8_WAIT_V(8); PG8_WAIT_L(0); PG8_BAR; PG8_MMA(0, 0, At, B0); PG8_MMA(0, 1, At, B1); PG8_BAR; PG8_SCHED;
;             PG8_LDA(At, 1, 1); PG8_STAGE(PG8_SB(1, 0), b3, voffB); PG8_STAGE(PG8_SB(1, 1), b3 + hstep, voffB); PG8_STAGE(PG8_SA(1, 0), a3, voffA);
;             PG8_WAIT_V(8); PG8_WAIT_L(0); PG8_BAR; PG8_MMA(1, 0, At, B0); PG8_MMA(1, 1, At, B1); PG8_BAR; PG8_SCHED;
	s_add_i32 s66, 0, 0x18000
	s_add_i32 s67, 0, 0x1c000
	ds_read_b128 v[144:147], v148
	ds_read_b128 v[158:161], v148 offset:1024
	ds_read_b128 v[162:165], v148 offset:2048
	ds_read_b128 v[166:169], v148 offset:3072
	ds_read_b128 v[170:173], v149
	ds_read_b128 v[174:177], v149 offset:1024
	ds_read_b128 v[178:181], v149 offset:2048
	ds_read_b128 v[182:185], v149 offset:3072
	s_add_u32 s40, s40, 0x100000
	s_addc_u32 s41, s41, 0
	s_mov_b32 m0, s53
	ds_read_b128 v[186:189], v155 offset:32768
	ds_read_b128 v[190:193], v155 offset:33792
	ds_read_b128 v[194:197], v155 offset:34816
	ds_read_b128 v[198:201], v155 offset:35840
	ds_read_b128 v[202:205], v155 offset:36864
	ds_read_b128 v[206:209], v155 offset:37888
	ds_read_b128 v[210:213], v155 offset:38912
	ds_read_b128 v[214:217], v155 offset:39936
	global_load_lds_dwordx4 v128, s[40:41]
	s_mov_b32 m0, s54
	s_nop 0
	global_load_lds_dwordx4 v132, s[40:41]
	s_waitcnt vmcnt(8)
	s_waitcnt lgkmcnt(0)
	s_barrier
	v_mfma_f32_16x16x32_bf16 v[124:127], v[144:147], v[186:189], v[124:127]
	v_mfma_f32_16x16x32_bf16 v[120:123], v[162:165], v[186:189], v[120:123]
	v_mfma_f32_16x16x32_bf16 v[108:111], v[144:147], v[194:197], v[108:111]
	v_mfma_f32_16x16x32_bf16 v[48:51], v[162:165], v[194:197], v[48:51]
	v_mfma_f32_16x16x32_bf16 v[100:103], v[144:147], v[202:205], v[100:103]
	v_mfma_f32_16x16x32_bf16 v[64:67], v[162:165], v[202:205], v[64:67]
	v_mfma_f32_16x16x32_bf16 v[92:95], v[144:147], v[210:213], v[92:95]
	v_mfma_f32_16x16x32_bf16 v[80:83], v[162:165], v[210:213], v[80:83]
	v_mfma_f32_16x16x32_bf16 v[124:127], v[158:161], v[190:193], v[124:127]
	v_mfma_f32_16x16x32_bf16 v[120:123], v[166:169], v[190:193], v[120:123]
	v_mfma_f32_16x16x32_bf16 v[108:111], v[158:161], v[198:201], v[108:111]
	v_mfma_f32_16x16x32_bf16 v[48:51], v[166:169], v[198:201], v[48:51]
	v_mfma_f32_16x16x32_bf16 v[100:103], v[158:161], v[206:209], v[100:103]
	v_mfma_f32_16x16x32_bf16 v[64:67], v[166:169], v[206:209], v[64:67]
	v_mfma_f32_16x16x32_bf16 v[92:95], v[158:161], v[214:217], v[92:95]
	v_mfma_f32_16x16x32_bf16 v[80:83], v[166:169], v[214:217], v[80:83]
	v_mfma_f32_16x16x32_bf16 v[116:119], v[170:173], v[186:189], v[116:119]
	v_mfma_f32_16x16x32_bf16 v[112:115], v[178:181], v[186:189], v[112:115]
	v_mfma_f32_16x16x32_bf16 v[104:107], v[170:173], v[194:197], v[104:107]
	v_mfma_f32_16x16x32_bf16 v[52:55], v[178:181], v[194:197], v[52:55]
	v_mfma_f32_16x16x32_bf16 v[96:99], v[170:173], v[202:205], v[96:99]
	v_mfma_f32_16x16x32_bf16 v[76:79], v[178:181], v[202:205], v[76:79]
	v_mfma_f32_16x16x32_bf16 v[88:91], v[170:173], v[210:213], v[88:91]
	v_mfma_f32_16x16x32_bf16 v[84:87], v[178:181], v[210:213], v[84:87]
	v_mfma_f32_16x16x32_bf16 v[116:119], v[174:177], v[190:193], v[116:119]
	v_mfma_f32_16x16x32_bf16 v[112:115], v[182:185], v[190:193], v[112:115]
	v_mfma_f32_16x16x32_bf16 v[104:107], v[174:177], v[198:201], v[104:107]
	v_mfma_f32_16x16x32_bf16 v[52:55], v[182:185], v[198:201], v[52:55]
	v_mfma_f32_16x16x32_bf16 v[96:99], v[174:177], v[206:209], v[96:99]
	v_mfma_f32_16x16x32_bf16 v[76:79], v[182:185], v[206:209], v[76:79]
	v_mfma_f32_16x16x32_bf16 v[88:91], v[174:177], v[214:217], v[88:91]
	v_mfma_f32_16x16x32_bf16 v[84:87], v[182:185], v[214:217], v[84:87]
	s_barrier
	s_add_i32 s40, s66, s33
	s_mov_b32 m0, s40
	ds_read_b128 v[186:189], v155 offset:49152
	ds_read_b128 v[190:193], v155 offset:50176
	ds_read_b128 v[194:197], v155 offset:51200
	ds_read_b128 v[198:201], v155 offset:52224
	ds_read_b128 v[202:205], v155 offset:53248
	ds_read_b128 v[206:209], v155 offset:54272
	ds_read_b128 v[210:213], v155 offset:55296
	ds_read_b128 v[214:217], v155 offset:56320
	global_load_lds_dwordx4 v130, s[98:99]
	s_add_i32 m0, s40, 0x2000
	s_add_u32 s38, s38, 0x100080
	s_addc_u32 s39, s39, 0
	s_add_i32 s40, s67, s33
	global_load_lds_dwordx4 v134, s[98:99]
	s_mov_b32 m0, s40
	s_nop 0
	global_load_lds_dwordx4 v130, s[38:39]
	s_add_i32 m0, s40, 0x2000
	s_nop 0
	global_load_lds_dwordx4 v134, s[38:39]
	s_mov_b32 m0, s56
	s_nop 0
	global_load_lds_dwordx4 v128, s[100:101]
	s_mov_b32 m0, s57
	s_nop 0
	global_load_lds_dwordx4 v132, s[100:101]
	s_waitcnt vmcnt(8)
	s_waitcnt lgkmcnt(0)
	s_barrier
	v_mfma_f32_16x16x32_bf16 v[72:75], v[144:147], v[186:189], v[72:75]
	v_mfma_f32_16x16x32_bf16 v[68:71], v[162:165], v[186:189], v[68:71]
	v_mfma_f32_16x16x32_bf16 v[44:47], v[144:147], v[194:197], v[44:47]
	v_mfma_f32_16x16x32_bf16 v[40:43], v[162:165], v[194:197], v[40:43]
	v_mfma_f32_16x16x32_bf16 v[28:31], v[144:147], v[202:205], v[28:31]
	v_mfma_f32_16x16x32_bf16 v[24:27], v[162:165], v[202:205], v[24:27]
	v_mfma_f32_16x16x32_bf16 v[12:15], v[144:147], v[210:213], v[12:15]
	v_mfma_f32_16x16x32_bf16 v[8:11], v[162:165], v[210:213], v[8:11]
	v_mfma_f32_16x16x32_bf16 v[72:75], v[158:161], v[190:193], v[72:75]
	v_mfma_f32_16x16x32_bf16 v[68:71], v[166:169], v[190:193], v[68:71]
	v_mfma_f32_16x16x32_bf16 v[44:47], v[158:161], v[198:201], v[44:47]
	v_mfma_f32_16x16x32_bf16 v[40:43], v[166:169], v[198:201], v[40:43]
	v_mfma_f32_16x16x32_bf16 v[28:31], v[158:161], v[206:209], v[28:31]
	v_mfma_f32_16x16x32_bf16 v[24:27], v[166:169], v[206:209], v[24:27]
	v_mfma_f32_16x16x32_bf16 v[12:15], v[158:161], v[214:217], v[12:15]
	v_mfma_f32_16x16x32_bf16 v[8:11], v[166:169], v[214:217], v[8:11]
	v_mfma_f32_16x16x32_bf16 v[60:63], v[170:173], v[186:189], v[60:63]
	v_mfma_f32_16x16x32_bf16 v[56:59], v[178:181], v[186:189], v[56:59]
	v_mfma_f32_16x16x32_bf16 v[36:39], v[170:173], v[194:197], v[36:39]
	v_mfma_f32_16x16x32_bf16 v[32:35], v[178:181], v[194:197], v[32:35]
	v_mfma_f32_16x16x32_bf16 v[20:23], v[170:173], v[202:205], v[20:23]
	v_mfma_f32_16x16x32_bf16 v[16:19], v[178:181], v[202:205], v[16:19]
	v_mfma_f32_16x16x32_bf16 v[4:7], v[170:173], v[210:213], v[4:7]
	v_mfma_f32_16x16x32_bf16 v[0:3], v[178:181], v[210:213], v[0:3]
	v_mfma_f32_16x16x32_bf16 v[60:63], v[174:177], v[190:193], v[60:63]
	v_mfma_f32_16x16x32_bf16 v[56:59], v[182:185], v[190:193], v[56:59]
	v_mfma_f32_16x16x32_bf16 v[36:39], v[174:177], v[198:201], v[36:39]
	v_mfma_f32_16x16x32_bf16 v[32:35], v[182:185], v[198:201], v[32:35]
	v_mfma_f32_16x16x32_bf16 v[20:23], v[174:177], v[206:209], v[20:23]
	v_mfma_f32_16x16x32_bf16 v[16:19], v[182:185], v[206:209], v[16:19]
	v_mfma_f32_16x16x32_bf16 v[4:7], v[174:177], v[214:217], v[4:7]
	v_mfma_f32_16x16x32_bf16 v[0:3], v[182:185], v[214:217], v[0:3]
	s_barrier
	s_add_i32 s65, s65, 2
	s_add_u32 s34, s34, 0x100
	s_addc_u32 s35, s35, 0
	s_add_u32 s63, s63, 0x100
	s_addc_u32 s64, s64, 0
	s_cmp_gt_u32 s65, 61
	s_cbranch_scc0 .LBB0_1198
	s_and_b64 vcc, exec, s[16:17]
	s_cbranch_vccz .LBB0_1201
	s_barrier

; #define PG8_STAGE(bufoff, gbase, voff) do { _Pragma("unroll") for (int _i = 0; _i < 2; ++_i) \
;         __builtin_amdgcn_global_load_lds((const unsigned*)((const char*)(gbase) + (voff)[_i]), (PG8_LAS unsigned*)(lds + (bufoff) + ldsw + _i * 8192), 16, 0, 0); } while (0)
; #define PG8_LDA(dst, b, h) do { _Pragma("unroll") for (int m = 0; m < 4; ++m) _Pragma("unroll") for (int k = 0; k < 2; ++k) dst[m][k] = *(const PG8_LAS bf16x8*)(lds + PG8_SA(b, h) + aoff + m * 2048 + k * 1024); } while (0)
; #define PG8_LDB(dst, b, h) do { _Pragma("unroll") for (int n = 0; n < 2; ++n) _Pragma("unroll") for (int k = 0; k < 2; ++k) dst[n][k] = *(const PG8_LAS bf16x8*)(lds + PG8_SB(b, h) + boff + n * 2048 + k * 1024); } while (0)
; #define PG8_WAIT_V(n) asm volatile("s_waitcnt vmcnt(" #n ")" ::: "memory")
; #define PG8_WAIT_L(n) asm volatile("s_waitcnt lgkmcnt(" #n ")" ::: "memory")
; #define PG8_BAR __builtin_amdgcn_s_barrier()
; template <class Epi, class Sched, bool ALIGN_EPI = false, bool SP2 = false>
; __device__ __forceinline__ void gemm_phase(PG8_LAS unsigned char* lds, const Gemm g, const Sched& S, const Epi& E) {
;     ...
;         const bool has_next = S.next(ui + 1, nxt);
;         const char* nA = has_next ? (const char*)g.A + (size_t)nxt.pm * tstep : cA; const char* nB = has_next ? (const char*)g.Bt + (size_t)nxt.pn * tstep : cB;
;         for (int t = 0; t < nt; t += 2) {
;             const bool last = (t == nt - 2);
;             const char* a1 = cA + (size_t)(t + 1) * kstepA;
;             const char* a2 = last ? nA : cA + (size_t)(t + 2) * kstepA; const char* b2 = last ? nB : cB + (size_t)(t + 2) * kstep;
;             const char* a3 = a2 + kstepA; const char* b3 = b2 + kstep;
;             if (last && has_next) S.a_ready(nxt);
;             if constexpr (SP2) {
;             PG8_LDB(B0, 0, 0); PG8_LDB(B1, 0, 1); PG8_SCHED; PG8_LDA(At, 0, 0); PG8_STAGE(PG8_SA(1, 1), a1 + hstepA, voffA);
;             PG8_WAIT_V(8); PG8_WAIT_L(0); PG8_BAR; PG8_MMA(0, 0, At, B0); PG8_MMA(0, 1, At, B1); PG8_BAR; PG8_SCHED;
;     ...
; #pragma unroll
;         for (int a = 0; a < 2; ++a)
; #pragma unroll
;             for (int b = 0; b < 2; ++b)
; #pragma unroll
;                 for (int m = 0; m < 4; ++m)
; #pragma unroll
;                     for (int n = 0; n < 2; ++n) acc[a][b][m][n] = (f32x4){0.f, 0.f, 0.f, 0.f};
;         cur = nxt; cA = nA; cB = nB; ++ui;
.LBB0_1309:
	s_ashr_i32 s41, s40, 31
	s_lshl_b64 s[6:7], s[40:41], 21
	s_add_u32 s84, s92, s6
	s_addc_u32 s85, s93, s7
	s_and_b64 s[6:7], s[4:5], exec
	s_cselect_b32 s41, s85, s95
	s_cselect_b32 s52, s84, s94
	s_ashr_i32 s39, s38, 31
	s_lshl_b64 s[6:7], s[38:39], 21
	s_add_u32 s86, s75, s6
	s_addc_u32 s87, s33, s7
	s_and_b64 s[6:7], s[4:5], exec
	s_cselect_b32 s39, s87, s97
	s_cselect_b32 s53, s86, s96
	s_add_u32 s69, s96, 0x100
	v_mov_b32_e32 v0, 0
	s_addc_u32 s70, s97, 0
	s_mov_b32 s71, -2
	v_mov_b32_e32 v1, v0
	v_mov_b32_e32 v2, v0
	v_mov_b32_e32 v3, v0
	v_mov_b32_e32 v4, v0
	v_mov_b32_e32 v5, v0
	v_mov_b32_e32 v6, v0
	v_mov_b32_e32 v7, v0
	v_mov_b32_e32 v16, v0
	v_mov_b32_e32 v17, v0
	v_mov_b32_e32 v18, v0
	v_mov_b32_e32 v19, v0
	v_mov_b32_e32 v20, v0
	v_mov_b32_e32 v21, v0
	v_mov_b32_e32 v22, v0
	v_mov_b32_e32 v23, v0
	v_mov_b32_e32 v32, v0
	v_mov_b32_e32 v33, v0
	v_mov_b32_e32 v34, v0
	v_mov_b32_e32 v35, v0
	s_waitcnt vmcnt(0)
	v_mov_b32_e32 v36, v0
	v_mov_b32_e32 v37, v0
	v_mov_b32_e32 v38, v0
	v_mov_b32_e32 v39, v0
	v_mov_b32_e32 v48, v0
	v_mov_b32_e32 v49, v0
	v_mov_b32_e32 v50, v0
	v_mov_b32_e32 v51, v0
	v_mov_b32_e32 v52, v0
	v_mov_b32_e32 v53, v0
	v_mov_b32_e32 v54, v0
	v_mov_b32_e32 v55, v0
	v_mov_b32_e32 v8, v0
	v_mov_b32_e32 v9, v0
	v_mov_b32_e32 v10, v0
	v_mov_b32_e32 v11, v0
	v_mov_b32_e32 v12, v0
	v_mov_b32_e32 v13, v0
	v_mov_b32_e32 v14, v0
	v_mov_b32_e32 v15, v0
	v_mov_b32_e32 v24, v0
	v_mov_b32_e32 v25, v0
	v_mov_b32_e32 v26, v0
	v_mov_b32_e32 v27, v0
	v_mov_b32_e32 v28, v0
	v_mov_b32_e32 v29, v0
	v_mov_b32_e32 v30, v0
	v_mov_b32_e32 v31, v0
	v_mov_b32_e32 v40, v0
	v_mov_b32_e32 v41, v0
	v_mov_b32_e32 v42, v0
	v_mov_b32_e32 v43, v0
	v_mov_b32_e32 v44, v0
	v_mov_b32_e32 v45, v0
	v_mov_b32_e32 v46, v0
	v_mov_b32_e32 v47, v0
	v_mov_b32_e32 v56, v0
	v_mov_b32_e32 v57, v0
	v_mov_b32_e32 v58, v0
	v_mov_b32_e32 v59, v0
	v_mov_b32_e32 v60, v0
	v_mov_b32_e32 v61, v0
	v_mov_b32_e32 v62, v0
	v_mov_b32_e32 v63, v0
	v_mov_b32_e32 v64, v0
	v_mov_b32_e32 v65, v0
	v_mov_b32_e32 v66, v0
	v_mov_b32_e32 v67, v0
	v_mov_b32_e32 v68, v0
	v_mov_b32_e32 v69, v0
	v_mov_b32_e32 v70, v0
	v_mov_b32_e32 v71, v0
	v_mov_b32_e32 v80, v0
	v_mov_b32_e32 v81, v0
	v_mov_b32_e32 v82, v0
	v_mov_b32_e32 v83, v0
	v_mov_b32_e32 v84, v0
	v_mov_b32_e32 v85, v0
	v_mov_b32_e32 v86, v0
	v_mov_b32_e32 v87, v0
	v_mov_b32_e32 v96, v0
	v_mov_b32_e32 v97, v0
	v_mov_b32_e32 v98, v0
	v_mov_b32_e32 v99, v0
	v_mov_b32_e32 v100, v0
	v_mov_b32_e32 v101, v0
	v_mov_b32_e32 v102, v0
	v_mov_b32_e32 v103, v0
	v_mov_b32_e32 v112, v0
	v_mov_b32_e32 v113, v0
	v_mov_b32_e32 v114, v0
	v_mov_b32_e32 v115, v0
	v_mov_b32_e32 v116, v0
	v_mov_b32_e32 v117, v0
	v_mov_b32_e32 v118, v0
	v_mov_b32_e32 v119, v0
	v_mov_b32_e32 v72, v0
	v_mov_b32_e32 v73, v0
	v_mov_b32_e32 v74, v0
	v_mov_b32_e32 v75, v0
	v_mov_b32_e32 v76, v0
	v_mov_b32_e32 v77, v0
	v_mov_b32_e32 v78, v0
	v_mov_b32_e32 v79, v0
	v_mov_b32_e32 v88, v0
	v_mov_b32_e32 v89, v0
	v_mov_b32_e32 v90, v0
	v_mov_b32_e32 v91, v0
	v_mov_b32_e32 v92, v0
	v_mov_b32_e32 v93, v0
	v_mov_b32_e32 v94, v0
	v_mov_b32_e32 v95, v0
	v_mov_b32_e32 v104, v0
	v_mov_b32_e32 v105, v0
	v_mov_b32_e32 v106, v0
	v_mov_b32_e32 v107, v0
	v_mov_b32_e32 v108, v0
	v_mov_b32_e32 v109, v0
	v_mov_b32_e32 v110, v0
	v_mov_b32_e32 v111, v0
	v_mov_b32_e32 v120, v0
	v_mov_b32_e32 v121, v0
	v_mov_b32_e32 v122, v0
	v_mov_b32_e32 v123, v0
	v_mov_b32_e32 v124, v0
	v_mov_b32_e32 v125, v0
	v_mov_b32_e32 v126, v0
	v_mov_b32_e32 v127, v0
	v_add_u32_e32 v214, 0x18000, v234
	v_add_u32_e32 v215, 0x1c000, v234
.LBB0_1310:
	ds_read_b128 v[128:131], v236
	ds_read_b128 v[132:135], v236 offset:1024
	ds_read_b128 v[136:139], v236 offset:2048
	ds_read_b128 v[140:143], v236 offset:3072
	ds_read_b128 v[144:147], v237
	ds_read_b128 v[148:151], v237 offset:1024
	ds_read_b128 v[152:155], v237 offset:2048
	ds_read_b128 v[156:159], v237 offset:3072
	s_add_u32 s96, s94, 0x100
	s_addc_u32 s97, s95, 0
	s_cmp_eq_u32 s71, 60
	s_cselect_b32 s7, s41, s97
	s_cselect_b32 s6, s52, s96
	s_cselect_b32 vcc_hi, s39, s70
	s_cselect_b32 vcc_lo, s53, s69
	v_lshl_add_u64 v[164:165], s[94:95], 0, v[178:179]
	s_add_i32 m0, s56, 0xc000
	ds_read_b128 v[160:163], v238
	ds_read_b128 v[186:189], v238 offset:1024
	ds_read_b128 v[190:193], v238 offset:2048
	ds_read_b128 v[194:197], v238 offset:3072
	ds_read_b128 v[198:201], v238 offset:4096
	ds_read_b128 v[202:205], v238 offset:5120
	ds_read_b128 v[206:209], v238 offset:6144
	ds_read_b128 v[210:213], v238 offset:7168
	global_load_lds_dwordx4 v[164:165], off
	v_lshl_add_u64 v[164:165], s[94:95], 0, v[180:181]
	s_add_i32 m0, s56, 0xe000
	s_nop 0
	global_load_lds_dwordx4 v[164:165], off
	s_waitcnt vmcnt(8)
	s_waitcnt lgkmcnt(0)
	s_barrier
; #define PG8_STAGE(bufoff, gbase, voff) do { _Pragma("unroll") for (int _i = 0; _i < 2; ++_i) \
;         __builtin_amdgcn_global_load_lds((const unsigned*)((const char*)(gbase) + (voff)[_i]), (PG8_LAS unsigned*)(lds + (bufoff) + ldsw + _i * 8192), 16, 0, 0); } while (0)
; #define PG8_LDA(dst, b, h) do { _Pragma("unroll") for (int m = 0; m < 4; ++m) _Pragma("unroll") for (int k = 0; k < 2; ++k) dst[m][k] = *(const PG8_LAS bf16x8*)(lds + PG8_SA(b, h) + aoff + m * 2048 + k * 1024); } while (0)
; #define PG8_MMA(ai, bj, At, Bt) do { __builtin_amdgcn_s_setprio(1); _Pragma("unroll") for (int m = 0; m < 4; ++m) _Pragma("unroll") for (int n = 0; n < 2; ++n) _Pragma("unroll") for (int k = 0; k < 2; ++k) \
;         acc[ai][bj][m][n] = __builtin_amdgcn_mfma_f32_16x16x32_bf16(Bt[n][k], At[m][k], acc[ai][bj][m][n], 0, 0, 0); __builtin_amdgcn_s_setprio(0); } while (0)
; #define PG8_WAIT_V(n) asm volatile("s_waitcnt vmcnt(" #n ")" ::: "memory")
; #define PG8_WAIT_L(n) asm volatile("s_waitcnt lgkmcnt(" #n ")" ::: "memory")
; #define PG8_BAR __builtin_amdgcn_s_barrier()
; #define PG8_SCHED __builtin_amdgcn_sched_barrier(0)
; template <class Epi, class Sched, bool ALIGN_EPI = false, bool SP2 = false>
; __device__ __forceinline__ void gemm_phase(PG8_LAS unsigned char* lds, const Gemm g, const Sched& S, const Epi& E) {
;     ...
;             PG8_WAIT_V(8); PG8_WAIT_L(0); PG8_BAR; PG8_MMA(0, 0, At, B0); PG8_MMA(0, 1, At, B1); PG8_BAR; PG8_SCHED;
;             PG8_LDA(At, 0, 1); PG8_STAGE(PG8_SB(0, 0), b2, voffB); PG8_STAGE(PG8_SB(0, 1), b2 + hstep, voffB); PG8_STAGE(PG8_SA(0, 0), a2, voffA);
;             PG8_WAIT_V(8); PG8_WAIT_L(0); PG8_BAR; PG8_MMA(1, 0, At, B0); PG8_MMA(1, 1, At, B1); PG8_BAR; PG8_SCHED;
	v_mfma_f32_16x16x32_bf16 v[124:127], v[128:131], v[160:163], v[124:127]
	v_mfma_f32_16x16x32_bf16 v[120:123], v[136:139], v[160:163], v[120:123]
	v_mfma_f32_16x16x32_bf16 v[108:111], v[128:131], v[190:193], v[108:111]
	v_mfma_f32_16x16x32_bf16 v[104:107], v[136:139], v[190:193], v[104:107]
	v_mfma_f32_16x16x32_bf16 v[92:95], v[128:131], v[198:201], v[92:95]
	v_mfma_f32_16x16x32_bf16 v[88:91], v[136:139], v[198:201], v[88:91]
	v_mfma_f32_16x16x32_bf16 v[76:79], v[128:131], v[206:209], v[76:79]
	v_mfma_f32_16x16x32_bf16 v[72:75], v[136:139], v[206:209], v[72:75]
	v_mfma_f32_16x16x32_bf16 v[124:127], v[132:135], v[186:189], v[124:127]
	v_mfma_f32_16x16x32_bf16 v[120:123], v[140:143], v[186:189], v[120:123]
	v_mfma_f32_16x16x32_bf16 v[108:111], v[132:135], v[194:197], v[108:111]
	v_mfma_f32_16x16x32_bf16 v[104:107], v[140:143], v[194:197], v[104:107]
	v_mfma_f32_16x16x32_bf16 v[92:95], v[132:135], v[202:205], v[92:95]
	v_mfma_f32_16x16x32_bf16 v[88:91], v[140:143], v[202:205], v[88:91]
	v_mfma_f32_16x16x32_bf16 v[76:79], v[132:135], v[210:213], v[76:79]
	v_mfma_f32_16x16x32_bf16 v[72:75], v[140:143], v[210:213], v[72:75]
	v_mfma_f32_16x16x32_bf16 v[116:119], v[144:147], v[160:163], v[116:119]
	v_mfma_f32_16x16x32_bf16 v[112:115], v[152:155], v[160:163], v[112:115]
	v_mfma_f32_16x16x32_bf16 v[100:103], v[144:147], v[190:193], v[100:103]
	v_mfma_f32_16x16x32_bf16 v[96:99], v[152:155], v[190:193], v[96:99]
	v_mfma_f32_16x16x32_bf16 v[84:87], v[144:147], v[198:201], v[84:87]
	v_mfma_f32_16x16x32_bf16 v[80:83], v[152:155], v[198:201], v[80:83]
	v_mfma_f32_16x16x32_bf16 v[68:71], v[144:147], v[206:209], v[68:71]
	v_mfma_f32_16x16x32_bf16 v[64:67], v[152:155], v[206:209], v[64:67]
	v_mfma_f32_16x16x32_bf16 v[116:119], v[148:151], v[186:189], v[116:119]
	v_mfma_f32_16x16x32_bf16 v[112:115], v[156:159], v[186:189], v[112:115]
	v_mfma_f32_16x16x32_bf16 v[100:103], v[148:151], v[194:197], v[100:103]
	v_mfma_f32_16x16x32_bf16 v[96:99], v[156:159], v[194:197], v[96:99]
	v_mfma_f32_16x16x32_bf16 v[84:87], v[148:151], v[202:205], v[84:87]
	v_mfma_f32_16x16x32_bf16 v[80:83], v[156:159], v[202:205], v[80:83]
	v_mfma_f32_16x16x32_bf16 v[68:71], v[148:151], v[210:213], v[68:71]
	v_mfma_f32_16x16x32_bf16 v[64:67], v[156:159], v[210:213], v[64:67]
	s_barrier
	s_add_u32 s98, vcc_lo, s10
	s_addc_u32 s99, vcc_hi, s11
	s_add_u32 s100, s6, s10
	s_addc_u32 s101, s7, s11
	s_add_i32 s72, s65, s55
	s_mov_b32 m0, s72
	ds_read_b128 v[160:163], v238 offset:16384
	ds_read_b128 v[186:189], v238 offset:17408
	ds_read_b128 v[190:193], v238 offset:18432
	ds_read_b128 v[194:197], v238 offset:19456
	ds_read_b128 v[198:201], v238 offset:20480
	ds_read_b128 v[202:205], v238 offset:21504
	ds_read_b128 v[206:209], v238 offset:22528
	ds_read_b128 v[210:213], v238 offset:23552
	global_load_lds_dwordx4 v168, vcc
	s_add_i32 m0, s72, 0x2000
	s_add_u32 s72, vcc_lo, 0x100000
	s_addc_u32 s73, vcc_hi, 0
	s_add_i32 s74, s66, s55
	global_load_lds_dwordx4 v172, vcc
	s_mov_b32 m0, s74
	s_nop 0
	global_load_lds_dwordx4 v168, s[72:73]
	s_add_i32 m0, s74, 0x2000
	s_nop 0
	global_load_lds_dwordx4 v172, s[72:73]
	s_mov_b32 m0, s56
	s_nop 0
	global_load_lds_dwordx4 v166, s[6:7]
	s_mov_b32 m0, s57
	s_nop 0
	global_load_lds_dwordx4 v170, s[6:7]
	s_waitcnt vmcnt(8)
	s_waitcnt lgkmcnt(0)
	s_barrier
	v_mfma_f32_16x16x32_bf16 v[60:63], v[128:131], v[160:163], v[60:63]
	v_mfma_f32_16x16x32_bf16 v[56:59], v[136:139], v[160:163], v[56:59]
	v_mfma_f32_16x16x32_bf16 v[44:47], v[128:131], v[190:193], v[44:47]
	v_mfma_f32_16x16x32_bf16 v[40:43], v[136:139], v[190:193], v[40:43]
	v_mfma_f32_16x16x32_bf16 v[28:31], v[128:131], v[198:201], v[28:31]
	v_mfma_f32_16x16x32_bf16 v[24:27], v[136:139], v[198:201], v[24:27]
	v_mfma_f32_16x16x32_bf16 v[12:15], v[128:131], v[206:209], v[12:15]
	v_mfma_f32_16x16x32_bf16 v[8:11], v[136:139], v[206:209], v[8:11]
	v_mfma_f32_16x16x32_bf16 v[60:63], v[132:135], v[186:189], v[60:63]
	v_mfma_f32_16x16x32_bf16 v[56:59], v[140:143], v[186:189], v[56:59]
	v_mfma_f32_16x16x32_bf16 v[44:47], v[132:135], v[194:197], v[44:47]
	v_mfma_f32_16x16x32_bf16 v[40:43], v[140:143], v[194:197], v[40:43]
	v_mfma_f32_16x16x32_bf16 v[28:31], v[132:135], v[202:205], v[28:31]
	v_mfma_f32_16x16x32_bf16 v[24:27], v[140:143], v[202:205], v[24:27]
	v_mfma_f32_16x16x32_bf16 v[12:15], v[132:135], v[210:213], v[12:15]
	v_mfma_f32_16x16x32_bf16 v[8:11], v[140:143], v[210:213], v[8:11]
	v_mfma_f32_16x16x32_bf16 v[52:55], v[144:147], v[160:163], v[52:55]
	v_mfma_f32_16x16x32_bf16 v[48:51], v[152:155], v[160:163], v[48:51]
	v_mfma_f32_16x16x32_bf16 v[36:39], v[144:147], v[190:193], v[36:39]
	v_mfma_f32_16x16x32_bf16 v[32:35], v[152:155], v[190:193], v[32:35]
	v_mfma_f32_16x16x32_bf16 v[20:23], v[144:147], v[198:201], v[20:23]
	v_mfma_f32_16x16x32_bf16 v[16:19], v[152:155], v[198:201], v[16:19]
	v_mfma_f32_16x16x32_bf16 v[4:7], v[144:147], v[206:209], v[4:7]
	v_mfma_f32_16x16x32_bf16 v[0:3], v[152:155], v[206:209], v[0:3]
	v_mfma_f32_16x16x32_bf16 v[52:55], v[148:151], v[186:189], v[52:55]
	v_mfma_f32_16x16x32_bf16 v[48:51], v[156:159], v[186:189], v[48:51]
	v_mfma_f32_16x16x32_bf16 v[36:39], v[148:151], v[194:197], v[36:39]
	v_mfma_f32_16x16x32_bf16 v[32:35], v[156:159], v[194:197], v[32:35]
	v_mfma_f32_16x16x32_bf16 v[20:23], v[148:151], v[202:205], v[20:23]
	v_mfma_f32_16x16x32_bf16 v[16:19], v[156:159], v[202:205], v[16:19]
	v_mfma_f32_16x16x32_bf16 v[4:7], v[148:151], v[210:213], v[4:7]
	v_mfma_f32_16x16x32_bf16 v[0:3], v[156:159], v[210:213], v[0:3]
	s_barrier
; #define PG8_STAGE(bufoff, gbase, voff) do { _Pragma("unroll") for (int _i = 0; _i < 2; ++_i) \
;         __builtin_amdgcn_global_load_lds((const unsigned*)((const char*)(gbase) + (voff)[_i]), (PG8_LAS unsigned*)(lds + (bufoff) + ldsw + _i * 8192), 16, 0, 0); } while (0)
; #define PG8_LDA(dst, b, h) do { _Pragma("unroll") for (int m = 0; m < 4; ++m) _Pragma("unroll") for (int k = 0; k < 2; ++k) dst[m][k] = *(const PG8_LAS bf16x8*)(lds + PG8_SA(b, h) + aoff + m * 2048 + k * 1024); } while (0)
; #define PG8_LDB(dst, b, h) do { _Pragma("unroll") for (int n = 0; n < 2; ++n) _Pragma("unroll") for (int k = 0; k < 2; ++k) dst[n][k] = *(const PG8_LAS bf16x8*)(lds + PG8_SB(b, h) + boff + n * 2048 + k * 1024); } while (0)
; #define PG8_MMA(ai, bj, At, Bt) do { __builtin_amdgcn_s_setprio(1); _Pragma("unroll") for (int m = 0; m < 4; ++m) _Pragma("unroll") for (int n = 0; n < 2; ++n) _Pragma("unroll") for (int k = 0; k < 2; ++k) \
;         acc[ai][bj][m][n] = __builtin_amdgcn_mfma_f32_16x16x32_bf16(Bt[n][k], At[m][k], acc[ai][bj][m][n], 0, 0, 0); __builtin_amdgcn_s_setprio(0); } while (0)
; #define PG8_WAIT_V(n) asm volatile("s_waitcnt vmcnt(" #n ")" ::: "memory")
; #define PG8_WAIT_L(n) asm volatile("s_waitcnt lgkmcnt(" #n ")" ::: "memory")
; #define PG8_BAR __builtin_amdgcn_s_barrier()
; #define PG8_SCHED __builtin_amdgcn_sched_barrier(0)
; template <class Epi, class Sched, bool ALIGN_EPI = false, bool SP2 = false>
; __device__ __forceinline__ void gemm_phase(PG8_LAS unsigned char* lds, const Gemm g, const Sched& S, const Epi& E) {
;     ...
;             PG8_LDB(B0, 1, 0); PG8_LDB(B1, 1, 1); PG8_SCHED; PG8_LDA(At, 1, 0); PG8_STAGE(PG8_SA(0, 1), a2 + hstepA, voffA);
;             PG8_WAIT_V(8); PG8_WAIT_L(0); PG8_BAR; PG8_MMA(0, 0, At, B0); PG8_MMA(0, 1, At, B1); PG8_BAR; PG8_SCHED;
;             PG8_LDA(At, 1, 1); PG8_STAGE(PG8_SB(1, 0), b3, voffB); PG8_STAGE(PG8_SB(1, 1), b3 + hstep, voffB); PG8_STAGE(PG8_SA(1, 0), a3, voffA);
;             PG8_WAIT_V(8); PG8_WAIT_L(0); PG8_BAR; PG8_MMA(1, 0, At, B0); PG8_MMA(1, 1, At, B1); PG8_BAR; PG8_SCHED;
;     ...
;         if constexpr (ALIGN_EPI) { if (wr == 0) PG8_BAR; }
	s_add_i32 s72, 0, 0x18000
	s_add_i32 s73, 0, 0x1c000
	ds_read_b128 v[128:131], v214
	ds_read_b128 v[132:135], v214 offset:1024
	ds_read_b128 v[136:139], v214 offset:2048
	ds_read_b128 v[140:143], v214 offset:3072
	ds_read_b128 v[144:147], v215
	ds_read_b128 v[148:151], v215 offset:1024
	ds_read_b128 v[152:155], v215 offset:2048
	ds_read_b128 v[156:159], v215 offset:3072
	s_add_u32 s6, s6, 0x100000
	s_addc_u32 s7, s7, 0
	s_mov_b32 m0, s58
	ds_read_b128 v[160:163], v238 offset:32768
	ds_read_b128 v[186:189], v238 offset:33792
	ds_read_b128 v[190:193], v238 offset:34816
	ds_read_b128 v[194:197], v238 offset:35840
	ds_read_b128 v[198:201], v238 offset:36864
	ds_read_b128 v[202:205], v238 offset:37888
	ds_read_b128 v[206:209], v238 offset:38912
	ds_read_b128 v[210:213], v238 offset:39936
	global_load_lds_dwordx4 v166, s[6:7]
	s_mov_b32 m0, s59
	s_nop 0
	global_load_lds_dwordx4 v170, s[6:7]
	s_waitcnt vmcnt(8)
	s_waitcnt lgkmcnt(0)
	s_barrier
	v_mfma_f32_16x16x32_bf16 v[124:127], v[128:131], v[160:163], v[124:127]
	v_mfma_f32_16x16x32_bf16 v[120:123], v[136:139], v[160:163], v[120:123]
	v_mfma_f32_16x16x32_bf16 v[108:111], v[128:131], v[190:193], v[108:111]
	v_mfma_f32_16x16x32_bf16 v[104:107], v[136:139], v[190:193], v[104:107]
	v_mfma_f32_16x16x32_bf16 v[92:95], v[128:131], v[198:201], v[92:95]
	v_mfma_f32_16x16x32_bf16 v[88:91], v[136:139], v[198:201], v[88:91]
	v_mfma_f32_16x16x32_bf16 v[76:79], v[128:131], v[206:209], v[76:79]
	v_mfma_f32_16x16x32_bf16 v[72:75], v[136:139], v[206:209], v[72:75]
	v_mfma_f32_16x16x32_bf16 v[124:127], v[132:135], v[186:189], v[124:127]
	v_mfma_f32_16x16x32_bf16 v[120:123], v[140:143], v[186:189], v[120:123]
	v_mfma_f32_16x16x32_bf16 v[108:111], v[132:135], v[194:197], v[108:111]
	v_mfma_f32_16x16x32_bf16 v[104:107], v[140:143], v[194:197], v[104:107]
	v_mfma_f32_16x16x32_bf16 v[92:95], v[132:135], v[202:205], v[92:95]
	v_mfma_f32_16x16x32_bf16 v[88:91], v[140:143], v[202:205], v[88:91]
	v_mfma_f32_16x16x32_bf16 v[76:79], v[132:135], v[210:213], v[76:79]
	v_mfma_f32_16x16x32_bf16 v[72:75], v[140:143], v[210:213], v[72:75]
	v_mfma_f32_16x16x32_bf16 v[116:119], v[144:147], v[160:163], v[116:119]
	v_mfma_f32_16x16x32_bf16 v[112:115], v[152:155], v[160:163], v[112:115]
	v_mfma_f32_16x16x32_bf16 v[100:103], v[144:147], v[190:193], v[100:103]
	v_mfma_f32_16x16x32_bf16 v[96:99], v[152:155], v[190:193], v[96:99]
	v_mfma_f32_16x16x32_bf16 v[84:87], v[144:147], v[198:201], v[84:87]
	v_mfma_f32_16x16x32_bf16 v[80:83], v[152:155], v[198:201], v[80:83]
	v_mfma_f32_16x16x32_bf16 v[68:71], v[144:147], v[206:209], v[68:71]
	v_mfma_f32_16x16x32_bf16 v[64:67], v[152:155], v[206:209], v[64:67]
	v_mfma_f32_16x16x32_bf16 v[116:119], v[148:151], v[186:189], v[116:119]
	v_mfma_f32_16x16x32_bf16 v[112:115], v[156:159], v[186:189], v[112:115]
	v_mfma_f32_16x16x32_bf16 v[100:103], v[148:151], v[194:197], v[100:103]
	v_mfma_f32_16x16x32_bf16 v[96:99], v[156:159], v[194:197], v[96:99]
	v_mfma_f32_16x16x32_bf16 v[84:87], v[148:151], v[202:205], v[84:87]
	v_mfma_f32_16x16x32_bf16 v[80:83], v[156:159], v[202:205], v[80:83]
	v_mfma_f32_16x16x32_bf16 v[68:71], v[148:151], v[210:213], v[68:71]
	v_mfma_f32_16x16x32_bf16 v[64:67], v[156:159], v[210:213], v[64:67]
	s_barrier
	s_add_i32 s6, s72, s55
	s_mov_b32 m0, s6
	ds_read_b128 v[160:163], v238 offset:49152
	ds_read_b128 v[186:189], v238 offset:50176
	ds_read_b128 v[190:193], v238 offset:51200
	ds_read_b128 v[194:197], v238 offset:52224
	ds_read_b128 v[198:201], v238 offset:53248
	ds_read_b128 v[202:205], v238 offset:54272
	ds_read_b128 v[206:209], v238 offset:55296
	ds_read_b128 v[210:213], v238 offset:56320
	global_load_lds_dwordx4 v168, s[98:99]
	s_add_i32 m0, s6, 0x2000
	s_add_u32 s6, vcc_lo, 0x100080
	s_addc_u32 s7, vcc_hi, 0
	s_add_i32 s72, s73, s55
	global_load_lds_dwordx4 v172, s[98:99]
	s_mov_b32 m0, s72
	s_nop 0
	global_load_lds_dwordx4 v168, s[6:7]
	s_add_i32 m0, s72, 0x2000
	s_nop 0
	global_load_lds_dwordx4 v172, s[6:7]
	s_mov_b32 m0, s63
	s_nop 0
	global_load_lds_dwordx4 v166, s[100:101]
	s_mov_b32 m0, s64
	s_nop 0
	global_load_lds_dwordx4 v170, s[100:101]
	s_waitcnt vmcnt(8)
	s_waitcnt lgkmcnt(0)
	s_barrier
	v_mfma_f32_16x16x32_bf16 v[60:63], v[128:131], v[160:163], v[60:63]
	v_mfma_f32_16x16x32_bf16 v[56:59], v[136:139], v[160:163], v[56:59]
	v_mfma_f32_16x16x32_bf16 v[44:47], v[128:131], v[190:193], v[44:47]
	v_mfma_f32_16x16x32_bf16 v[40:43], v[136:139], v[190:193], v[40:43]
	v_mfma_f32_16x16x32_bf16 v[28:31], v[128:131], v[198:201], v[28:31]
	v_mfma_f32_16x16x32_bf16 v[24:27], v[136:139], v[198:201], v[24:27]
	v_mfma_f32_16x16x32_bf16 v[12:15], v[128:131], v[206:209], v[12:15]
	v_mfma_f32_16x16x32_bf16 v[8:11], v[136:139], v[206:209], v[8:11]
	v_mfma_f32_16x16x32_bf16 v[60:63], v[132:135], v[186:189], v[60:63]
	v_mfma_f32_16x16x32_bf16 v[56:59], v[140:143], v[186:189], v[56:59]
	v_mfma_f32_16x16x32_bf16 v[44:47], v[132:135], v[194:197], v[44:47]
	v_mfma_f32_16x16x32_bf16 v[40:43], v[140:143], v[194:197], v[40:43]
	v_mfma_f32_16x16x32_bf16 v[28:31], v[132:135], v[202:205], v[28:31]
	v_mfma_f32_16x16x32_bf16 v[24:27], v[140:143], v[202:205], v[24:27]
	v_mfma_f32_16x16x32_bf16 v[12:15], v[132:135], v[210:213], v[12:15]
	v_mfma_f32_16x16x32_bf16 v[8:11], v[140:143], v[210:213], v[8:11]
	v_mfma_f32_16x16x32_bf16 v[52:55], v[144:147], v[160:163], v[52:55]
	v_mfma_f32_16x16x32_bf16 v[48:51], v[152:155], v[160:163], v[48:51]
	v_mfma_f32_16x16x32_bf16 v[36:39], v[144:147], v[190:193], v[36:39]
	v_mfma_f32_16x16x32_bf16 v[32:35], v[152:155], v[190:193], v[32:35]
	v_mfma_f32_16x16x32_bf16 v[20:23], v[144:147], v[198:201], v[20:23]
	v_mfma_f32_16x16x32_bf16 v[16:19], v[152:155], v[198:201], v[16:19]
	v_mfma_f32_16x16x32_bf16 v[4:7], v[144:147], v[206:209], v[4:7]
	v_mfma_f32_16x16x32_bf16 v[0:3], v[152:155], v[206:209], v[0:3]
	v_mfma_f32_16x16x32_bf16 v[52:55], v[148:151], v[186:189], v[52:55]
	v_mfma_f32_16x16x32_bf16 v[48:51], v[156:159], v[186:189], v[48:51]
	v_mfma_f32_16x16x32_bf16 v[36:39], v[148:151], v[194:197], v[36:39]
	v_mfma_f32_16x16x32_bf16 v[32:35], v[156:159], v[194:197], v[32:35]
	v_mfma_f32_16x16x32_bf16 v[20:23], v[148:151], v[202:205], v[20:23]
	v_mfma_f32_16x16x32_bf16 v[16:19], v[156:159], v[202:205], v[16:19]
	v_mfma_f32_16x16x32_bf16 v[4:7], v[148:151], v[210:213], v[4:7]
	v_mfma_f32_16x16x32_bf16 v[0:3], v[156:159], v[210:213], v[0:3]
	s_barrier
	s_add_i32 s71, s71, 2
	s_add_u32 s69, s69, 0x100
	s_addc_u32 s70, s70, 0
	s_cmp_gt_u32 s71, 61
	s_mov_b64 s[94:95], s[96:97]
	s_cbranch_scc0 .LBB0_1310
	s_and_b64 vcc, exec, s[12:13]
	s_cbranch_vccz .LBB0_1313
	s_barrier

; #define PG8_STAGE(bufoff, gbase, voff) do { _Pragma("unroll") for (int _i = 0; _i < 2; ++_i) \
;         __builtin_amdgcn_global_load_lds((const unsigned*)((const char*)(gbase) + (voff)[_i]), (PG8_LAS unsigned*)(lds + (bufoff) + ldsw + _i * 8192), 16, 0, 0); } while (0)
; #define PG8_LDA(dst, b, h) do { _Pragma("unroll") for (int m = 0; m < 4; ++m) _Pragma("unroll") for (int k = 0; k < 2; ++k) dst[m][k] = *(const PG8_LAS bf16x8*)(lds + PG8_SA(b, h) + aoff + m * 2048 + k * 1024); } while (0)
; #define PG8_LDB(dst, b, h) do { _Pragma("unroll") for (int n = 0; n < 2; ++n) _Pragma("unroll") for (int k = 0; k < 2; ++k) dst[n][k] = *(const PG8_LAS bf16x8*)(lds + PG8_SB(b, h) + boff + n * 2048 + k * 1024); } while (0)
; #define PG8_MMA(ai, bj, At, Bt) do { __builtin_amdgcn_s_setprio(1); _Pragma("unroll") for (int m = 0; m < 4; ++m) _Pragma("unroll") for (int n = 0; n < 2; ++n) _Pragma("unroll") for (int k = 0; k < 2; ++k) \
;         acc[ai][bj][m][n] = __builtin_amdgcn_mfma_f32_16x16x32_bf16(Bt[n][k], At[m][k], acc[ai][bj][m][n], 0, 0, 0); __builtin_amdgcn_s_setprio(0); } while (0)
; #define PG8_WAIT_V(n) asm volatile("s_waitcnt vmcnt(" #n ")" ::: "memory")
; #define PG8_WAIT_L(n) asm volatile("s_waitcnt lgkmcnt(" #n ")" ::: "memory")
; #define PG8_BAR __builtin_amdgcn_s_barrier()
; #define PG8_SCHED __builtin_amdgcn_sched_barrier(0)
; template <class Epi, class Sched, bool ALIGN_EPI = false, bool SP2 = false>
; __device__ __forceinline__ void gemm_phase(PG8_LAS unsigned char* lds, const Gemm g, const Sched& S, const Epi& E) {
;     ...
;             PG8_LDB(B0, 0, 0); PG8_LDB(B1, 0, 1); PG8_SCHED; PG8_LDA(At, 0, 0); PG8_STAGE(PG8_SA(1, 1), a1 + hstepA, voffA);
;             PG8_WAIT_V(8); PG8_WAIT_L(0); PG8_BAR; PG8_MMA(0, 0, At, B0); PG8_MMA(0, 1, At, B1); PG8_BAR; PG8_SCHED;
;     ...
;         for (int a = 0; a < 2; ++a)
; #pragma unroll
;             for (int b = 0; b < 2; ++b)
; #pragma unroll
;                 for (int m = 0; m < 4; ++m)
; #pragma unroll
;                     for (int n = 0; n < 2; ++n) acc[a][b][m][n] = (f32x4){0.f, 0.f, 0.f, 0.f};
.LBB0_1514:
	s_add_u32 s61, s22, 0x100
	s_addc_u32 s62, s23, 0
	s_add_u32 s22, s24, 0xc000
	v_mov_b32_e32 v0, 0
	s_addc_u32 s23, s25, 0
	s_mov_b32 s63, -2
	s_waitcnt lgkmcnt(0)
	v_mov_b32_e32 v1, v0
	v_mov_b32_e32 v2, v0
	v_mov_b32_e32 v3, v0
	v_mov_b32_e32 v4, v0
	v_mov_b32_e32 v5, v0
	v_mov_b32_e32 v6, v0
	v_mov_b32_e32 v7, v0
	v_mov_b32_e32 v16, v0
	v_mov_b32_e32 v17, v0
	v_mov_b32_e32 v18, v0
	v_mov_b32_e32 v19, v0
	v_mov_b32_e32 v20, v0
	v_mov_b32_e32 v21, v0
	v_mov_b32_e32 v22, v0
	v_mov_b32_e32 v23, v0
	v_mov_b32_e32 v32, v0
	v_mov_b32_e32 v33, v0
	v_mov_b32_e32 v34, v0
	v_mov_b32_e32 v35, v0
	s_waitcnt vmcnt(0)
	v_mov_b32_e32 v36, v0
	v_mov_b32_e32 v37, v0
	v_mov_b32_e32 v38, v0
	v_mov_b32_e32 v39, v0
	v_mov_b32_e32 v56, v0
	v_mov_b32_e32 v57, v0
	v_mov_b32_e32 v58, v0
	v_mov_b32_e32 v59, v0
	v_mov_b32_e32 v60, v0
	v_mov_b32_e32 v61, v0
	v_mov_b32_e32 v62, v0
	v_mov_b32_e32 v63, v0
	v_mov_b32_e32 v8, v0
	v_mov_b32_e32 v9, v0
	v_mov_b32_e32 v10, v0
	v_mov_b32_e32 v11, v0
	v_mov_b32_e32 v12, v0
	v_mov_b32_e32 v13, v0
	v_mov_b32_e32 v14, v0
	v_mov_b32_e32 v15, v0
	v_mov_b32_e32 v24, v0
	v_mov_b32_e32 v25, v0
	v_mov_b32_e32 v26, v0
	v_mov_b32_e32 v27, v0
	v_mov_b32_e32 v28, v0
	v_mov_b32_e32 v29, v0
	v_mov_b32_e32 v30, v0
	v_mov_b32_e32 v31, v0
	v_mov_b32_e32 v40, v0
	v_mov_b32_e32 v41, v0
	v_mov_b32_e32 v42, v0
	v_mov_b32_e32 v43, v0
	v_mov_b32_e32 v44, v0
	v_mov_b32_e32 v45, v0
	v_mov_b32_e32 v46, v0
	v_mov_b32_e32 v47, v0
	v_mov_b32_e32 v68, v0
	v_mov_b32_e32 v69, v0
	v_mov_b32_e32 v70, v0
	v_mov_b32_e32 v71, v0
	v_mov_b32_e32 v72, v0
	v_mov_b32_e32 v73, v0
	v_mov_b32_e32 v74, v0
	v_mov_b32_e32 v75, v0
	v_mov_b32_e32 v84, v0
	v_mov_b32_e32 v85, v0
	v_mov_b32_e32 v86, v0
	v_mov_b32_e32 v87, v0
	v_mov_b32_e32 v88, v0
	v_mov_b32_e32 v89, v0
	v_mov_b32_e32 v90, v0
	v_mov_b32_e32 v91, v0
	v_mov_b32_e32 v76, v0
	v_mov_b32_e32 v77, v0
	v_mov_b32_e32 v78, v0
	v_mov_b32_e32 v79, v0
	v_mov_b32_e32 v96, v0
	v_mov_b32_e32 v97, v0
	v_mov_b32_e32 v98, v0
	v_mov_b32_e32 v99, v0
	v_mov_b32_e32 v52, v0
	v_mov_b32_e32 v53, v0
	v_mov_b32_e32 v54, v0
	v_mov_b32_e32 v55, v0
	v_mov_b32_e32 v104, v0
	v_mov_b32_e32 v105, v0
	v_mov_b32_e32 v106, v0
	v_mov_b32_e32 v107, v0
	v_mov_b32_e32 v112, v0
	v_mov_b32_e32 v113, v0
	v_mov_b32_e32 v114, v0
	v_mov_b32_e32 v115, v0
	v_mov_b32_e32 v116, v0
	v_mov_b32_e32 v117, v0
	v_mov_b32_e32 v118, v0
	v_mov_b32_e32 v119, v0
	v_mov_b32_e32 v80, v0
	v_mov_b32_e32 v81, v0
	v_mov_b32_e32 v82, v0
	v_mov_b32_e32 v83, v0
	v_mov_b32_e32 v92, v0
	v_mov_b32_e32 v93, v0
	v_mov_b32_e32 v94, v0
	v_mov_b32_e32 v95, v0
	v_mov_b32_e32 v64, v0
	v_mov_b32_e32 v65, v0
	v_mov_b32_e32 v66, v0
	v_mov_b32_e32 v67, v0
	v_mov_b32_e32 v100, v0
	v_mov_b32_e32 v101, v0
	v_mov_b32_e32 v102, v0
	v_mov_b32_e32 v103, v0
	v_mov_b32_e32 v48, v0
	v_mov_b32_e32 v49, v0
	v_mov_b32_e32 v50, v0
	v_mov_b32_e32 v51, v0
	v_mov_b32_e32 v108, v0
	v_mov_b32_e32 v109, v0
	v_mov_b32_e32 v110, v0
	v_mov_b32_e32 v111, v0
	v_mov_b32_e32 v120, v0
	v_mov_b32_e32 v121, v0
	v_mov_b32_e32 v122, v0
	v_mov_b32_e32 v123, v0
	v_mov_b32_e32 v124, v0
	v_mov_b32_e32 v125, v0
	v_mov_b32_e32 v126, v0
	v_mov_b32_e32 v127, v0
	v_add_u32_e32 v148, 0x18000, v151
	v_add_u32_e32 v149, 0x1c000, v151
.LBB0_1515:
	ds_read_b128 v[144:147], v153
	ds_read_b128 v[158:161], v153 offset:1024
	ds_read_b128 v[162:165], v153 offset:2048
	ds_read_b128 v[166:169], v153 offset:3072
	ds_read_b128 v[170:173], v154
	ds_read_b128 v[174:177], v154 offset:1024
	ds_read_b128 v[178:181], v154 offset:2048
	ds_read_b128 v[182:185], v154 offset:3072
	s_add_u32 s24, s22, 0x4000
	s_addc_u32 s25, s23, 0
	s_cmpk_eq_i32 s63, 0xa8
	s_cselect_b32 s30, s6, s24
	s_cselect_b32 s31, s7, s25
	s_cselect_b32 s26, s20, s61
	s_cselect_b32 s27, s21, s62
	s_add_u32 s24, s30, 0x8000
	s_addc_u32 s25, s31, 0
	s_add_i32 m0, s34, 0xc000
	ds_read_b128 v[186:189], v155
	ds_read_b128 v[190:193], v155 offset:1024
	ds_read_b128 v[194:197], v155 offset:2048
	ds_read_b128 v[198:201], v155 offset:3072
	ds_read_b128 v[202:205], v155 offset:4096
	ds_read_b128 v[206:209], v155 offset:5120
	ds_read_b128 v[210:213], v155 offset:6144
	ds_read_b128 v[214:217], v155 offset:7168
	global_load_lds_dwordx4 v136, s[22:23]
	s_add_i32 m0, s34, 0xe000
	s_nop 0
	global_load_lds_dwordx4 v138, s[22:23]
	s_waitcnt vmcnt(8)
	s_waitcnt lgkmcnt(0)
	s_barrier
	v_mfma_f32_16x16x32_bf16 v[124:127], v[144:147], v[186:189], v[124:127]
	v_mfma_f32_16x16x32_bf16 v[120:123], v[162:165], v[186:189], v[120:123]
	v_mfma_f32_16x16x32_bf16 v[108:111], v[144:147], v[194:197], v[108:111]
	v_mfma_f32_16x16x32_bf16 v[48:51], v[162:165], v[194:197], v[48:51]
	v_mfma_f32_16x16x32_bf16 v[100:103], v[144:147], v[202:205], v[100:103]
	v_mfma_f32_16x16x32_bf16 v[64:67], v[162:165], v[202:205], v[64:67]
	v_mfma_f32_16x16x32_bf16 v[92:95], v[144:147], v[210:213], v[92:95]
	v_mfma_f32_16x16x32_bf16 v[80:83], v[162:165], v[210:213], v[80:83]
	v_mfma_f32_16x16x32_bf16 v[124:127], v[158:161], v[190:193], v[124:127]
	v_mfma_f32_16x16x32_bf16 v[120:123], v[166:169], v[190:193], v[120:123]
	v_mfma_f32_16x16x32_bf16 v[108:111], v[158:161], v[198:201], v[108:111]
	v_mfma_f32_16x16x32_bf16 v[48:51], v[166:169], v[198:201], v[48:51]
	v_mfma_f32_16x16x32_bf16 v[100:103], v[158:161], v[206:209], v[100:103]
	v_mfma_f32_16x16x32_bf16 v[64:67], v[166:169], v[206:209], v[64:67]
	v_mfma_f32_16x16x32_bf16 v[92:95], v[158:161], v[214:217], v[92:95]
	v_mfma_f32_16x16x32_bf16 v[80:83], v[166:169], v[214:217], v[80:83]
	v_mfma_f32_16x16x32_bf16 v[116:119], v[170:173], v[186:189], v[116:119]
	v_mfma_f32_16x16x32_bf16 v[112:115], v[178:181], v[186:189], v[112:115]
	v_mfma_f32_16x16x32_bf16 v[104:107], v[170:173], v[194:197], v[104:107]
	v_mfma_f32_16x16x32_bf16 v[52:55], v[178:181], v[194:197], v[52:55]
	v_mfma_f32_16x16x32_bf16 v[96:99], v[170:173], v[202:205], v[96:99]
	v_mfma_f32_16x16x32_bf16 v[76:79], v[178:181], v[202:205], v[76:79]
	v_mfma_f32_16x16x32_bf16 v[88:91], v[170:173], v[210:213], v[88:91]
	v_mfma_f32_16x16x32_bf16 v[84:87], v[178:181], v[210:213], v[84:87]
	v_mfma_f32_16x16x32_bf16 v[116:119], v[174:177], v[190:193], v[116:119]
	v_mfma_f32_16x16x32_bf16 v[112:115], v[182:185], v[190:193], v[112:115]
	v_mfma_f32_16x16x32_bf16 v[104:107], v[174:177], v[198:201], v[104:107]
	v_mfma_f32_16x16x32_bf16 v[52:55], v[182:185], v[198:201], v[52:55]
	v_mfma_f32_16x16x32_bf16 v[96:99], v[174:177], v[206:209], v[96:99]
	v_mfma_f32_16x16x32_bf16 v[76:79], v[182:185], v[206:209], v[76:79]
	v_mfma_f32_16x16x32_bf16 v[88:91], v[174:177], v[214:217], v[88:91]
	v_mfma_f32_16x16x32_bf16 v[84:87], v[182:185], v[214:217], v[84:87]
	s_barrier
; #define PG8_STAGE(bufoff, gbase, voff) do { _Pragma("unroll") for (int _i = 0; _i < 2; ++_i) \
;         __builtin_amdgcn_global_load_lds((const unsigned*)((const char*)(gbase) + (voff)[_i]), (PG8_LAS unsigned*)(lds + (bufoff) + ldsw + _i * 8192), 16, 0, 0); } while (0)
; #define PG8_LDA(dst, b, h) do { _Pragma("unroll") for (int m = 0; m < 4; ++m) _Pragma("unroll") for (int k = 0; k < 2; ++k) dst[m][k] = *(const PG8_LAS bf16x8*)(lds + PG8_SA(b, h) + aoff + m * 2048 + k * 1024); } while (0)
; #define PG8_LDB(dst, b, h) do { _Pragma("unroll") for (int n = 0; n < 2; ++n) _Pragma("unroll") for (int k = 0; k < 2; ++k) dst[n][k] = *(const PG8_LAS bf16x8*)(lds + PG8_SB(b, h) + boff + n * 2048 + k * 1024); } while (0)
; #define PG8_MMA(ai, bj, At, Bt) do { __builtin_amdgcn_s_setprio(1); _Pragma("unroll") for (int m = 0; m < 4; ++m) _Pragma("unroll") for (int n = 0; n < 2; ++n) _Pragma("unroll") for (int k = 0; k < 2; ++k) \
;         acc[ai][bj][m][n] = __builtin_amdgcn_mfma_f32_16x16x32_bf16(Bt[n][k], At[m][k], acc[ai][bj][m][n], 0, 0, 0); __builtin_amdgcn_s_setprio(0); } while (0)
; #define PG8_WAIT_V(n) asm volatile("s_waitcnt vmcnt(" #n ")" ::: "memory")
; #define PG8_WAIT_L(n) asm volatile("s_waitcnt lgkmcnt(" #n ")" ::: "memory")
; #define PG8_BAR __builtin_amdgcn_s_barrier()
; #define PG8_SCHED __builtin_amdgcn_sched_barrier(0)
; template <class Epi, class Sched, bool ALIGN_EPI = false, bool SP2 = false>
; __device__ __forceinline__ void gemm_phase(PG8_LAS unsigned char* lds, const Gemm g, const Sched& S, const Epi& E) {
;     ...
;             PG8_LDA(At, 0, 1); PG8_STAGE(PG8_SB(0, 0), b2, voffB); PG8_STAGE(PG8_SB(0, 1), b2 + hstep, voffB); PG8_STAGE(PG8_SA(0, 0), a2, voffA);
;             PG8_WAIT_V(8); PG8_WAIT_L(0); PG8_BAR; PG8_MMA(1, 0, At, B0); PG8_MMA(1, 1, At, B1); PG8_BAR; PG8_SCHED;
;             PG8_LDB(B0, 1, 0); PG8_LDB(B1, 1, 1); PG8_SCHED; PG8_LDA(At, 1, 0); PG8_STAGE(PG8_SA(0, 1), a2 + hstepA, voffA);
;             PG8_WAIT_V(8); PG8_WAIT_L(0); PG8_BAR; PG8_MMA(0, 0, At, B0); PG8_MMA(0, 1, At, B1); PG8_BAR; PG8_SCHED;
	s_add_u32 s98, s26, s16
	s_addc_u32 s99, s27, s17
	s_add_i32 s64, s55, s33
	s_mov_b32 m0, s64
	ds_read_b128 v[186:189], v155 offset:16384
	ds_read_b128 v[190:193], v155 offset:17408
	ds_read_b128 v[194:197], v155 offset:18432
	ds_read_b128 v[198:201], v155 offset:19456
	ds_read_b128 v[202:205], v155 offset:20480
	ds_read_b128 v[206:209], v155 offset:21504
	ds_read_b128 v[210:213], v155 offset:22528
	ds_read_b128 v[214:217], v155 offset:23552
	global_load_lds_dwordx4 v130, s[26:27]
	s_add_i32 m0, s64, 0x2000
	s_add_u32 s64, s26, 0x2b0000
	s_addc_u32 s65, s27, 0
	s_add_i32 s66, s56, s33
	global_load_lds_dwordx4 v134, s[26:27]
	s_mov_b32 m0, s66
	s_nop 0
	global_load_lds_dwordx4 v130, s[64:65]
	s_add_i32 m0, s66, 0x2000
	s_nop 0
	global_load_lds_dwordx4 v134, s[64:65]
	s_mov_b32 m0, s34
	s_nop 0
	global_load_lds_dwordx4 v128, s[30:31]
	s_mov_b32 m0, s35
	s_nop 0
	global_load_lds_dwordx4 v132, s[30:31]
	s_waitcnt vmcnt(8)
	s_waitcnt lgkmcnt(0)
	s_barrier
	v_mfma_f32_16x16x32_bf16 v[72:75], v[144:147], v[186:189], v[72:75]
	v_mfma_f32_16x16x32_bf16 v[68:71], v[162:165], v[186:189], v[68:71]
	v_mfma_f32_16x16x32_bf16 v[44:47], v[144:147], v[194:197], v[44:47]
	v_mfma_f32_16x16x32_bf16 v[40:43], v[162:165], v[194:197], v[40:43]
	v_mfma_f32_16x16x32_bf16 v[28:31], v[144:147], v[202:205], v[28:31]
	v_mfma_f32_16x16x32_bf16 v[24:27], v[162:165], v[202:205], v[24:27]
	v_mfma_f32_16x16x32_bf16 v[12:15], v[144:147], v[210:213], v[12:15]
	v_mfma_f32_16x16x32_bf16 v[8:11], v[162:165], v[210:213], v[8:11]
	v_mfma_f32_16x16x32_bf16 v[72:75], v[158:161], v[190:193], v[72:75]
	v_mfma_f32_16x16x32_bf16 v[68:71], v[166:169], v[190:193], v[68:71]
	v_mfma_f32_16x16x32_bf16 v[44:47], v[158:161], v[198:201], v[44:47]
	v_mfma_f32_16x16x32_bf16 v[40:43], v[166:169], v[198:201], v[40:43]
	v_mfma_f32_16x16x32_bf16 v[28:31], v[158:161], v[206:209], v[28:31]
	v_mfma_f32_16x16x32_bf16 v[24:27], v[166:169], v[206:209], v[24:27]
	v_mfma_f32_16x16x32_bf16 v[12:15], v[158:161], v[214:217], v[12:15]
	v_mfma_f32_16x16x32_bf16 v[8:11], v[166:169], v[214:217], v[8:11]
	v_mfma_f32_16x16x32_bf16 v[60:63], v[170:173], v[186:189], v[60:63]
	v_mfma_f32_16x16x32_bf16 v[56:59], v[178:181], v[186:189], v[56:59]
	v_mfma_f32_16x16x32_bf16 v[36:39], v[170:173], v[194:197], v[36:39]
	v_mfma_f32_16x16x32_bf16 v[32:35], v[178:181], v[194:197], v[32:35]
	v_mfma_f32_16x16x32_bf16 v[20:23], v[170:173], v[202:205], v[20:23]
	v_mfma_f32_16x16x32_bf16 v[16:19], v[178:181], v[202:205], v[16:19]
	v_mfma_f32_16x16x32_bf16 v[4:7], v[170:173], v[210:213], v[4:7]
	v_mfma_f32_16x16x32_bf16 v[0:3], v[178:181], v[210:213], v[0:3]
	v_mfma_f32_16x16x32_bf16 v[60:63], v[174:177], v[190:193], v[60:63]
	v_mfma_f32_16x16x32_bf16 v[56:59], v[182:185], v[190:193], v[56:59]
	v_mfma_f32_16x16x32_bf16 v[36:39], v[174:177], v[198:201], v[36:39]
	v_mfma_f32_16x16x32_bf16 v[32:35], v[182:185], v[198:201], v[32:35]
	v_mfma_f32_16x16x32_bf16 v[20:23], v[174:177], v[206:209], v[20:23]
	v_mfma_f32_16x16x32_bf16 v[16:19], v[182:185], v[206:209], v[16:19]
	v_mfma_f32_16x16x32_bf16 v[4:7], v[174:177], v[214:217], v[4:7]
	v_mfma_f32_16x16x32_bf16 v[0:3], v[182:185], v[214:217], v[0:3]
	s_barrier
	s_add_i32 s64, 0, 0x18000
	s_add_i32 s65, 0, 0x1c000
	ds_read_b128 v[144:147], v148
	ds_read_b128 v[158:161], v148 offset:1024
	ds_read_b128 v[162:165], v148 offset:2048
	ds_read_b128 v[166:169], v148 offset:3072
	ds_read_b128 v[170:173], v149
	ds_read_b128 v[174:177], v149 offset:1024
	ds_read_b128 v[178:181], v149 offset:2048
	ds_read_b128 v[182:185], v149 offset:3072
	s_add_u32 s30, s30, 0x4000
	s_addc_u32 s31, s31, 0
	s_mov_b32 m0, s38
	ds_read_b128 v[186:189], v155 offset:32768
	ds_read_b128 v[190:193], v155 offset:33792
	ds_read_b128 v[194:197], v155 offset:34816
	ds_read_b128 v[198:201], v155 offset:35840
	ds_read_b128 v[202:205], v155 offset:36864
	ds_read_b128 v[206:209], v155 offset:37888
	ds_read_b128 v[210:213], v155 offset:38912
	ds_read_b128 v[214:217], v155 offset:39936
	global_load_lds_dwordx4 v128, s[30:31]
	s_mov_b32 m0, s39
	s_nop 0
	global_load_lds_dwordx4 v132, s[30:31]
	s_waitcnt vmcnt(8)
	s_waitcnt lgkmcnt(0)
	s_barrier
; #define PG8_STAGE(bufoff, gbase, voff) do { _Pragma("unroll") for (int _i = 0; _i < 2; ++_i) \
;         __builtin_amdgcn_global_load_lds((const unsigned*)((const char*)(gbase) + (voff)[_i]), (PG8_LAS unsigned*)(lds + (bufoff) + ldsw + _i * 8192), 16, 0, 0); } while (0)
; #define PG8_LDA(dst, b, h) do { _Pragma("unroll") for (int m = 0; m < 4; ++m) _Pragma("unroll") for (int k = 0; k < 2; ++k) dst[m][k] = *(const PG8_LAS bf16x8*)(lds + PG8_SA(b, h) + aoff + m * 2048 + k * 1024); } while (0)
; #define PG8_MMA(ai, bj, At, Bt) do { __builtin_amdgcn_s_setprio(1); _Pragma("unroll") for (int m = 0; m < 4; ++m) _Pragma("unroll") for (int n = 0; n < 2; ++n) _Pragma("unroll") for (int k = 0; k < 2; ++k) \
;         acc[ai][bj][m][n] = __builtin_amdgcn_mfma_f32_16x16x32_bf16(Bt[n][k], At[m][k], acc[ai][bj][m][n], 0, 0, 0); __builtin_amdgcn_s_setprio(0); } while (0)
; #define PG8_WAIT_V(n) asm volatile("s_waitcnt vmcnt(" #n ")" ::: "memory")
; #define PG8_WAIT_L(n) asm volatile("s_waitcnt lgkmcnt(" #n ")" ::: "memory")
; #define PG8_BAR __builtin_amdgcn_s_barrier()
; #define PG8_SCHED __builtin_amdgcn_sched_barrier(0)
; template <class Epi, class Sched, bool ALIGN_EPI = false, bool SP2 = false>
; __device__ __forceinline__ void gemm_phase(PG8_LAS unsigned char* lds, const Gemm g, const Sched& S, const Epi& E) {
;     ...
;             PG8_WAIT_V(8); PG8_WAIT_L(0); PG8_BAR; PG8_MMA(0, 0, At, B0); PG8_MMA(0, 1, At, B1); PG8_BAR; PG8_SCHED;
;             PG8_LDA(At, 1, 1); PG8_STAGE(PG8_SB(1, 0), b3, voffB); PG8_STAGE(PG8_SB(1, 1), b3 + hstep, voffB); PG8_STAGE(PG8_SA(1, 0), a3, voffA);
;             PG8_WAIT_V(8); PG8_WAIT_L(0); PG8_BAR; PG8_MMA(1, 0, At, B0); PG8_MMA(1, 1, At, B1); PG8_BAR; PG8_SCHED;
;     ...
;         if constexpr (ALIGN_EPI) { if (wr == 0) PG8_BAR; }
	v_mfma_f32_16x16x32_bf16 v[124:127], v[144:147], v[186:189], v[124:127]
	v_mfma_f32_16x16x32_bf16 v[120:123], v[162:165], v[186:189], v[120:123]
	v_mfma_f32_16x16x32_bf16 v[108:111], v[144:147], v[194:197], v[108:111]
	v_mfma_f32_16x16x32_bf16 v[48:51], v[162:165], v[194:197], v[48:51]
	v_mfma_f32_16x16x32_bf16 v[100:103], v[144:147], v[202:205], v[100:103]
	v_mfma_f32_16x16x32_bf16 v[64:67], v[162:165], v[202:205], v[64:67]
	v_mfma_f32_16x16x32_bf16 v[92:95], v[144:147], v[210:213], v[92:95]
	v_mfma_f32_16x16x32_bf16 v[80:83], v[162:165], v[210:213], v[80:83]
	v_mfma_f32_16x16x32_bf16 v[124:127], v[158:161], v[190:193], v[124:127]
	v_mfma_f32_16x16x32_bf16 v[120:123], v[166:169], v[190:193], v[120:123]
	v_mfma_f32_16x16x32_bf16 v[108:111], v[158:161], v[198:201], v[108:111]
	v_mfma_f32_16x16x32_bf16 v[48:51], v[166:169], v[198:201], v[48:51]
	v_mfma_f32_16x16x32_bf16 v[100:103], v[158:161], v[206:209], v[100:103]
	v_mfma_f32_16x16x32_bf16 v[64:67], v[166:169], v[206:209], v[64:67]
	v_mfma_f32_16x16x32_bf16 v[92:95], v[158:161], v[214:217], v[92:95]
	v_mfma_f32_16x16x32_bf16 v[80:83], v[166:169], v[214:217], v[80:83]
	v_mfma_f32_16x16x32_bf16 v[116:119], v[170:173], v[186:189], v[116:119]
	v_mfma_f32_16x16x32_bf16 v[112:115], v[178:181], v[186:189], v[112:115]
	v_mfma_f32_16x16x32_bf16 v[104:107], v[170:173], v[194:197], v[104:107]
	v_mfma_f32_16x16x32_bf16 v[52:55], v[178:181], v[194:197], v[52:55]
	v_mfma_f32_16x16x32_bf16 v[96:99], v[170:173], v[202:205], v[96:99]
	v_mfma_f32_16x16x32_bf16 v[76:79], v[178:181], v[202:205], v[76:79]
	v_mfma_f32_16x16x32_bf16 v[88:91], v[170:173], v[210:213], v[88:91]
	v_mfma_f32_16x16x32_bf16 v[84:87], v[178:181], v[210:213], v[84:87]
	v_mfma_f32_16x16x32_bf16 v[116:119], v[174:177], v[190:193], v[116:119]
	v_mfma_f32_16x16x32_bf16 v[112:115], v[182:185], v[190:193], v[112:115]
	v_mfma_f32_16x16x32_bf16 v[104:107], v[174:177], v[198:201], v[104:107]
	v_mfma_f32_16x16x32_bf16 v[52:55], v[182:185], v[198:201], v[52:55]
	v_mfma_f32_16x16x32_bf16 v[96:99], v[174:177], v[206:209], v[96:99]
	v_mfma_f32_16x16x32_bf16 v[76:79], v[182:185], v[206:209], v[76:79]
	v_mfma_f32_16x16x32_bf16 v[88:91], v[174:177], v[214:217], v[88:91]
	v_mfma_f32_16x16x32_bf16 v[84:87], v[182:185], v[214:217], v[84:87]
	s_barrier
	s_add_i32 s30, s64, s33
	s_mov_b32 m0, s30
	ds_read_b128 v[186:189], v155 offset:49152
	ds_read_b128 v[190:193], v155 offset:50176
	ds_read_b128 v[194:197], v155 offset:51200
	ds_read_b128 v[198:201], v155 offset:52224
	ds_read_b128 v[202:205], v155 offset:53248
	ds_read_b128 v[206:209], v155 offset:54272
	ds_read_b128 v[210:213], v155 offset:55296
	ds_read_b128 v[214:217], v155 offset:56320
	global_load_lds_dwordx4 v130, s[98:99]
	s_add_i32 m0, s30, 0x2000
	s_add_u32 s26, s26, 0x2b0080
	s_addc_u32 s27, s27, 0
	s_add_i32 s30, s65, s33
	global_load_lds_dwordx4 v134, s[98:99]
	s_mov_b32 m0, s30
	s_nop 0
	global_load_lds_dwordx4 v130, s[26:27]
	s_add_i32 m0, s30, 0x2000
	s_nop 0
	global_load_lds_dwordx4 v134, s[26:27]
	s_mov_b32 m0, s41
	s_nop 0
	global_load_lds_dwordx4 v128, s[24:25]
	s_mov_b32 m0, s52
	s_nop 0
	global_load_lds_dwordx4 v132, s[24:25]
	s_waitcnt vmcnt(8)
	s_waitcnt lgkmcnt(0)
	s_barrier
	v_mfma_f32_16x16x32_bf16 v[72:75], v[144:147], v[186:189], v[72:75]
	v_mfma_f32_16x16x32_bf16 v[68:71], v[162:165], v[186:189], v[68:71]
	v_mfma_f32_16x16x32_bf16 v[44:47], v[144:147], v[194:197], v[44:47]
	v_mfma_f32_16x16x32_bf16 v[40:43], v[162:165], v[194:197], v[40:43]
	v_mfma_f32_16x16x32_bf16 v[28:31], v[144:147], v[202:205], v[28:31]
	v_mfma_f32_16x16x32_bf16 v[24:27], v[162:165], v[202:205], v[24:27]
	v_mfma_f32_16x16x32_bf16 v[12:15], v[144:147], v[210:213], v[12:15]
	v_mfma_f32_16x16x32_bf16 v[8:11], v[162:165], v[210:213], v[8:11]
	v_mfma_f32_16x16x32_bf16 v[72:75], v[158:161], v[190:193], v[72:75]
	v_mfma_f32_16x16x32_bf16 v[68:71], v[166:169], v[190:193], v[68:71]
	v_mfma_f32_16x16x32_bf16 v[44:47], v[158:161], v[198:201], v[44:47]
	v_mfma_f32_16x16x32_bf16 v[40:43], v[166:169], v[198:201], v[40:43]
	v_mfma_f32_16x16x32_bf16 v[28:31], v[158:161], v[206:209], v[28:31]
	v_mfma_f32_16x16x32_bf16 v[24:27], v[166:169], v[206:209], v[24:27]
	v_mfma_f32_16x16x32_bf16 v[12:15], v[158:161], v[214:217], v[12:15]
	v_mfma_f32_16x16x32_bf16 v[8:11], v[166:169], v[214:217], v[8:11]
	v_mfma_f32_16x16x32_bf16 v[60:63], v[170:173], v[186:189], v[60:63]
	v_mfma_f32_16x16x32_bf16 v[56:59], v[178:181], v[186:189], v[56:59]
	v_mfma_f32_16x16x32_bf16 v[36:39], v[170:173], v[194:197], v[36:39]
	v_mfma_f32_16x16x32_bf16 v[32:35], v[178:181], v[194:197], v[32:35]
	v_mfma_f32_16x16x32_bf16 v[20:23], v[170:173], v[202:205], v[20:23]
	v_mfma_f32_16x16x32_bf16 v[16:19], v[178:181], v[202:205], v[16:19]
	v_mfma_f32_16x16x32_bf16 v[4:7], v[170:173], v[210:213], v[4:7]
	v_mfma_f32_16x16x32_bf16 v[0:3], v[178:181], v[210:213], v[0:3]
	v_mfma_f32_16x16x32_bf16 v[60:63], v[174:177], v[190:193], v[60:63]
	v_mfma_f32_16x16x32_bf16 v[56:59], v[182:185], v[190:193], v[56:59]
	v_mfma_f32_16x16x32_bf16 v[36:39], v[174:177], v[198:201], v[36:39]
	v_mfma_f32_16x16x32_bf16 v[32:35], v[182:185], v[198:201], v[32:35]
	v_mfma_f32_16x16x32_bf16 v[20:23], v[174:177], v[206:209], v[20:23]
	v_mfma_f32_16x16x32_bf16 v[16:19], v[182:185], v[206:209], v[16:19]
	v_mfma_f32_16x16x32_bf16 v[4:7], v[174:177], v[214:217], v[4:7]
	v_mfma_f32_16x16x32_bf16 v[0:3], v[182:185], v[214:217], v[0:3]
	s_barrier
	s_add_i32 s63, s63, 2
	s_add_u32 s61, s61, 0x100
	s_addc_u32 s62, s62, 0
	s_add_u32 s22, s22, 0x10000
	s_addc_u32 s23, s23, 0
	s_cmpk_gt_u32 s63, 0xa9
	s_cbranch_scc0 .LBB0_1515
	s_and_b64 vcc, exec, s[18:19]
	s_cbranch_vccz .LBB0_1518
	s_barrier

; #define PG8_STAGE(bufoff, gbase, voff) do { _Pragma("unroll") for (int _i = 0; _i < 2; ++_i) \
;         __builtin_amdgcn_global_load_lds((const unsigned*)((const char*)(gbase) + (voff)[_i]), (PG8_LAS unsigned*)(lds + (bufoff) + ldsw + _i * 8192), 16, 0, 0); } while (0)
; #define PG8_LDA(dst, b, h) do { _Pragma("unroll") for (int m = 0; m < 4; ++m) _Pragma("unroll") for (int k = 0; k < 2; ++k) dst[m][k] = *(const PG8_LAS bf16x8*)(lds + PG8_SA(b, h) + aoff + m * 2048 + k * 1024); } while (0)
; #define PG8_LDB(dst, b, h) do { _Pragma("unroll") for (int n = 0; n < 2; ++n) _Pragma("unroll") for (int k = 0; k < 2; ++k) dst[n][k] = *(const PG8_LAS bf16x8*)(lds + PG8_SB(b, h) + boff + n * 2048 + k * 1024); } while (0)
; #define PG8_SCHED __builtin_amdgcn_sched_barrier(0)
; template <class Epi, class Sched, bool ALIGN_EPI = false, bool SP2 = false>
; __device__ __forceinline__ void gemm_phase(PG8_LAS unsigned char* lds, const Gemm g, const Sched& S, const Epi& E) {
;     ...
;         const bool has_next = S.next(ui + 1, nxt);
;         const char* nA = has_next ? (const char*)g.A + (size_t)nxt.pm * tstep : cA; const char* nB = has_next ? (const char*)g.Bt + (size_t)nxt.pn * tstep : cB;
;     ...
;             PG8_LDB(B0, 0, 0); PG8_LDB(B1, 0, 1); PG8_SCHED; PG8_LDA(At, 0, 0); PG8_STAGE(PG8_SA(1, 1), a1 + hstepA, voffA);
;     ...
;         for (int a = 0; a < 2; ++a)
; #pragma unroll
;             for (int b = 0; b < 2; ++b)
; #pragma unroll
;                 for (int m = 0; m < 4; ++m)
; #pragma unroll
;                     for (int n = 0; n < 2; ++n) acc[a][b][m][n] = (f32x4){0.f, 0.f, 0.f, 0.f};
.LBB0_1630:
	s_ashr_i32 s25, s24, 31
	s_lshl_b64 s[26:27], s[24:25], 21
	s_add_u32 s26, s92, s26
	s_addc_u32 s27, s93, s27
	s_and_b64 s[30:31], s[4:5], exec
	s_cselect_b32 s25, s27, s85
	s_cselect_b32 s35, s26, s84
	s_ashr_i32 s23, s22, 31
	s_lshl_b64 s[30:31], s[22:23], 21
	s_add_u32 s30, s14, s30
	s_addc_u32 s31, s15, s31
	s_and_b64 s[62:63], s[4:5], exec
	s_cselect_b32 s23, s31, s87
	s_cselect_b32 s61, s30, s86
	s_add_u32 s84, s84, 0x100080
	s_addc_u32 s85, s85, 0
	s_add_u32 s62, s86, 0x100
	v_mov_b32_e32 v0, 0
	s_addc_u32 s63, s87, 0
	s_mov_b32 s64, -2
	s_waitcnt lgkmcnt(0)
	v_mov_b32_e32 v1, v0
	v_mov_b32_e32 v2, v0
	v_mov_b32_e32 v3, v0
	v_mov_b32_e32 v4, v0
	v_mov_b32_e32 v5, v0
	v_mov_b32_e32 v6, v0
	v_mov_b32_e32 v7, v0
	v_mov_b32_e32 v16, v0
	v_mov_b32_e32 v17, v0
	v_mov_b32_e32 v18, v0
	v_mov_b32_e32 v19, v0
	v_mov_b32_e32 v20, v0
	v_mov_b32_e32 v21, v0
	v_mov_b32_e32 v22, v0
	v_mov_b32_e32 v23, v0
	s_waitcnt vmcnt(0)
	v_mov_b32_e32 v36, v0
	v_mov_b32_e32 v37, v0
	v_mov_b32_e32 v38, v0
	v_mov_b32_e32 v39, v0
	v_mov_b32_e32 v40, v0
	v_mov_b32_e32 v41, v0
	v_mov_b32_e32 v42, v0
	v_mov_b32_e32 v43, v0
	v_mov_b32_e32 v60, v0
	v_mov_b32_e32 v61, v0
	v_mov_b32_e32 v62, v0
	v_mov_b32_e32 v63, v0
	v_mov_b32_e32 v64, v0
	v_mov_b32_e32 v65, v0
	v_mov_b32_e32 v66, v0
	v_mov_b32_e32 v67, v0
	v_mov_b32_e32 v8, v0
	v_mov_b32_e32 v9, v0
	v_mov_b32_e32 v10, v0
	v_mov_b32_e32 v11, v0
	v_mov_b32_e32 v12, v0
	v_mov_b32_e32 v13, v0
	v_mov_b32_e32 v14, v0
	v_mov_b32_e32 v15, v0
	v_mov_b32_e32 v24, v0
	v_mov_b32_e32 v25, v0
	v_mov_b32_e32 v26, v0
	v_mov_b32_e32 v27, v0
	v_mov_b32_e32 v28, v0
	v_mov_b32_e32 v29, v0
	v_mov_b32_e32 v30, v0
	v_mov_b32_e32 v31, v0
	v_mov_b32_e32 v48, v0
	v_mov_b32_e32 v49, v0
	v_mov_b32_e32 v50, v0
	v_mov_b32_e32 v51, v0
	v_mov_b32_e32 v56, v0
	v_mov_b32_e32 v57, v0
	v_mov_b32_e32 v58, v0
	v_mov_b32_e32 v59, v0
	v_mov_b32_e32 v76, v0
	v_mov_b32_e32 v77, v0
	v_mov_b32_e32 v78, v0
	v_mov_b32_e32 v79, v0
	v_mov_b32_e32 v80, v0
	v_mov_b32_e32 v81, v0
	v_mov_b32_e32 v82, v0
	v_mov_b32_e32 v83, v0
	v_mov_b32_e32 v84, v0
	v_mov_b32_e32 v85, v0
	v_mov_b32_e32 v86, v0
	v_mov_b32_e32 v87, v0
	v_mov_b32_e32 v88, v0
	v_mov_b32_e32 v89, v0
	v_mov_b32_e32 v90, v0
	v_mov_b32_e32 v91, v0
	v_mov_b32_e32 v68, v0
	v_mov_b32_e32 v69, v0
	v_mov_b32_e32 v70, v0
	v_mov_b32_e32 v71, v0
	v_mov_b32_e32 v96, v0
	v_mov_b32_e32 v97, v0
	v_mov_b32_e32 v98, v0
	v_mov_b32_e32 v99, v0
	v_mov_b32_e32 v44, v0
	v_mov_b32_e32 v45, v0
	v_mov_b32_e32 v46, v0
	v_mov_b32_e32 v47, v0
	v_mov_b32_e32 v104, v0
	v_mov_b32_e32 v105, v0
	v_mov_b32_e32 v106, v0
	v_mov_b32_e32 v107, v0
	v_mov_b32_e32 v112, v0
	v_mov_b32_e32 v113, v0
	v_mov_b32_e32 v114, v0
	v_mov_b32_e32 v115, v0
	v_mov_b32_e32 v116, v0
	v_mov_b32_e32 v117, v0
	v_mov_b32_e32 v118, v0
	v_mov_b32_e32 v119, v0
	v_mov_b32_e32 v72, v0
	v_mov_b32_e32 v73, v0
	v_mov_b32_e32 v74, v0
	v_mov_b32_e32 v75, v0
	v_mov_b32_e32 v92, v0
	v_mov_b32_e32 v93, v0
	v_mov_b32_e32 v94, v0
	v_mov_b32_e32 v95, v0
	v_mov_b32_e32 v52, v0
	v_mov_b32_e32 v53, v0
	v_mov_b32_e32 v54, v0
	v_mov_b32_e32 v55, v0
	v_mov_b32_e32 v100, v0
	v_mov_b32_e32 v101, v0
	v_mov_b32_e32 v102, v0
	v_mov_b32_e32 v103, v0
	v_mov_b32_e32 v32, v0
	v_mov_b32_e32 v33, v0
	v_mov_b32_e32 v34, v0
	v_mov_b32_e32 v35, v0
	v_mov_b32_e32 v108, v0
	v_mov_b32_e32 v109, v0
	v_mov_b32_e32 v110, v0
	v_mov_b32_e32 v111, v0
	v_mov_b32_e32 v120, v0
	v_mov_b32_e32 v121, v0
	v_mov_b32_e32 v122, v0
	v_mov_b32_e32 v123, v0
	v_mov_b32_e32 v124, v0
	v_mov_b32_e32 v125, v0
	v_mov_b32_e32 v126, v0
	v_mov_b32_e32 v127, v0
	v_add_u32_e32 v216, 0x18000, v153
	v_add_u32_e32 v217, 0x1c000, v153
.LBB0_1631:
	ds_read_b128 v[144:147], v155
	ds_read_b128 v[148:151], v155 offset:1024
	ds_read_b128 v[160:163], v155 offset:2048
	ds_read_b128 v[164:167], v155 offset:3072
	ds_read_b128 v[168:171], v156
	ds_read_b128 v[172:175], v156 offset:1024
	ds_read_b128 v[176:179], v156 offset:2048
	ds_read_b128 v[180:183], v156 offset:3072
	s_add_u32 s65, s84, 0xfff00080
	s_addc_u32 s66, s85, -1
	s_cmp_eq_u32 s64, 60
	s_cselect_b32 s89, s25, s66
	s_cselect_b32 s88, s35, s65
	s_cselect_b32 s87, s23, s63
	s_cselect_b32 s86, s61, s62
	s_add_i32 m0, s29, 0xc000
	ds_read_b128 v[184:187], v157
	ds_read_b128 v[188:191], v157 offset:1024
	ds_read_b128 v[192:195], v157 offset:2048
	ds_read_b128 v[196:199], v157 offset:3072
	ds_read_b128 v[200:203], v157 offset:4096
	ds_read_b128 v[204:207], v157 offset:5120
	ds_read_b128 v[208:211], v157 offset:6144
	ds_read_b128 v[212:215], v157 offset:7168
	global_load_lds_dwordx4 v136, s[84:85]
	s_add_i32 m0, s29, 0xe000
	s_nop 0
	global_load_lds_dwordx4 v138, s[84:85]
	s_waitcnt vmcnt(8)
	s_waitcnt lgkmcnt(0)
	s_barrier
; #define PG8_STAGE(bufoff, gbase, voff) do { _Pragma("unroll") for (int _i = 0; _i < 2; ++_i) \
;         __builtin_amdgcn_global_load_lds((const unsigned*)((const char*)(gbase) + (voff)[_i]), (PG8_LAS unsigned*)(lds + (bufoff) + ldsw + _i * 8192), 16, 0, 0); } while (0)
; #define PG8_LDA(dst, b, h) do { _Pragma("unroll") for (int m = 0; m < 4; ++m) _Pragma("unroll") for (int k = 0; k < 2; ++k) dst[m][k] = *(const PG8_LAS bf16x8*)(lds + PG8_SA(b, h) + aoff + m * 2048 + k * 1024); } while (0)
; #define PG8_MMA(ai, bj, At, Bt) do { __builtin_amdgcn_s_setprio(1); _Pragma("unroll") for (int m = 0; m < 4; ++m) _Pragma("unroll") for (int n = 0; n < 2; ++n) _Pragma("unroll") for (int k = 0; k < 2; ++k) \
;         acc[ai][bj][m][n] = __builtin_amdgcn_mfma_f32_16x16x32_bf16(Bt[n][k], At[m][k], acc[ai][bj][m][n], 0, 0, 0); __builtin_amdgcn_s_setprio(0); } while (0)
; #define PG8_WAIT_V(n) asm volatile("s_waitcnt vmcnt(" #n ")" ::: "memory")
; #define PG8_WAIT_L(n) asm volatile("s_waitcnt lgkmcnt(" #n ")" ::: "memory")
; #define PG8_BAR __builtin_amdgcn_s_barrier()
; #define PG8_SCHED __builtin_amdgcn_sched_barrier(0)
; template <class Epi, class Sched, bool ALIGN_EPI = false, bool SP2 = false>
; __device__ __forceinline__ void gemm_phase(PG8_LAS unsigned char* lds, const Gemm g, const Sched& S, const Epi& E) {
;     ...
;             PG8_WAIT_V(8); PG8_WAIT_L(0); PG8_BAR; PG8_MMA(0, 0, At, B0); PG8_MMA(0, 1, At, B1); PG8_BAR; PG8_SCHED;
;             PG8_LDA(At, 0, 1); PG8_STAGE(PG8_SB(0, 0), b2, voffB); PG8_STAGE(PG8_SB(0, 1), b2 + hstep, voffB); PG8_STAGE(PG8_SA(0, 0), a2, voffA);
;             PG8_WAIT_V(8); PG8_WAIT_L(0); PG8_BAR; PG8_MMA(1, 0, At, B0); PG8_MMA(1, 1, At, B1); PG8_BAR; PG8_SCHED;
	v_mfma_f32_16x16x32_bf16 v[124:127], v[144:147], v[184:187], v[124:127]
	v_mfma_f32_16x16x32_bf16 v[120:123], v[160:163], v[184:187], v[120:123]
	v_mfma_f32_16x16x32_bf16 v[108:111], v[144:147], v[192:195], v[108:111]
	v_mfma_f32_16x16x32_bf16 v[32:35], v[160:163], v[192:195], v[32:35]
	v_mfma_f32_16x16x32_bf16 v[100:103], v[144:147], v[200:203], v[100:103]
	v_mfma_f32_16x16x32_bf16 v[52:55], v[160:163], v[200:203], v[52:55]
	v_mfma_f32_16x16x32_bf16 v[92:95], v[144:147], v[208:211], v[92:95]
	v_mfma_f32_16x16x32_bf16 v[72:75], v[160:163], v[208:211], v[72:75]
	v_mfma_f32_16x16x32_bf16 v[124:127], v[148:151], v[188:191], v[124:127]
	v_mfma_f32_16x16x32_bf16 v[120:123], v[164:167], v[188:191], v[120:123]
	v_mfma_f32_16x16x32_bf16 v[108:111], v[148:151], v[196:199], v[108:111]
	v_mfma_f32_16x16x32_bf16 v[32:35], v[164:167], v[196:199], v[32:35]
	v_mfma_f32_16x16x32_bf16 v[100:103], v[148:151], v[204:207], v[100:103]
	v_mfma_f32_16x16x32_bf16 v[52:55], v[164:167], v[204:207], v[52:55]
	v_mfma_f32_16x16x32_bf16 v[92:95], v[148:151], v[212:215], v[92:95]
	v_mfma_f32_16x16x32_bf16 v[72:75], v[164:167], v[212:215], v[72:75]
	v_mfma_f32_16x16x32_bf16 v[116:119], v[168:171], v[184:187], v[116:119]
	v_mfma_f32_16x16x32_bf16 v[112:115], v[176:179], v[184:187], v[112:115]
	v_mfma_f32_16x16x32_bf16 v[104:107], v[168:171], v[192:195], v[104:107]
	v_mfma_f32_16x16x32_bf16 v[44:47], v[176:179], v[192:195], v[44:47]
	v_mfma_f32_16x16x32_bf16 v[96:99], v[168:171], v[200:203], v[96:99]
	v_mfma_f32_16x16x32_bf16 v[68:71], v[176:179], v[200:203], v[68:71]
	v_mfma_f32_16x16x32_bf16 v[88:91], v[168:171], v[208:211], v[88:91]
	v_mfma_f32_16x16x32_bf16 v[84:87], v[176:179], v[208:211], v[84:87]
	v_mfma_f32_16x16x32_bf16 v[116:119], v[172:175], v[188:191], v[116:119]
	v_mfma_f32_16x16x32_bf16 v[112:115], v[180:183], v[188:191], v[112:115]
	v_mfma_f32_16x16x32_bf16 v[104:107], v[172:175], v[196:199], v[104:107]
	v_mfma_f32_16x16x32_bf16 v[44:47], v[180:183], v[196:199], v[44:47]
	v_mfma_f32_16x16x32_bf16 v[96:99], v[172:175], v[204:207], v[96:99]
	v_mfma_f32_16x16x32_bf16 v[68:71], v[180:183], v[204:207], v[68:71]
	v_mfma_f32_16x16x32_bf16 v[88:91], v[172:175], v[212:215], v[88:91]
	v_mfma_f32_16x16x32_bf16 v[84:87], v[180:183], v[212:215], v[84:87]
	s_barrier
	s_add_u32 s98, s86, s18
	s_addc_u32 s99, s87, s19
	s_add_u32 s100, s88, s18
	s_addc_u32 s101, s89, s19
	s_add_i32 s65, s58, s3
	s_mov_b32 m0, s65
	ds_read_b128 v[184:187], v157 offset:16384
	ds_read_b128 v[188:191], v157 offset:17408
	ds_read_b128 v[192:195], v157 offset:18432
	ds_read_b128 v[196:199], v157 offset:19456
	ds_read_b128 v[200:203], v157 offset:20480
	ds_read_b128 v[204:207], v157 offset:21504
	ds_read_b128 v[208:211], v157 offset:22528
	ds_read_b128 v[212:215], v157 offset:23552
	global_load_lds_dwordx4 v130, s[86:87]
	s_add_i32 m0, s65, 0x2000
	s_add_u32 s66, s86, 0x100000
	s_addc_u32 s67, s87, 0
	s_add_i32 s65, s59, s3
	global_load_lds_dwordx4 v134, s[86:87]
	s_mov_b32 m0, s65
	s_nop 0
	global_load_lds_dwordx4 v130, s[66:67]
	s_add_i32 m0, s65, 0x2000
	s_nop 0
	global_load_lds_dwordx4 v134, s[66:67]
	s_mov_b32 m0, s29
	s_nop 0
	global_load_lds_dwordx4 v128, s[88:89]
	s_mov_b32 m0, s33
	s_nop 0
	global_load_lds_dwordx4 v132, s[88:89]
	s_waitcnt vmcnt(8)
	s_waitcnt lgkmcnt(0)
	s_barrier
	v_mfma_f32_16x16x32_bf16 v[80:83], v[144:147], v[184:187], v[80:83]
	v_mfma_f32_16x16x32_bf16 v[76:79], v[160:163], v[184:187], v[76:79]
	v_mfma_f32_16x16x32_bf16 v[56:59], v[144:147], v[192:195], v[56:59]
	v_mfma_f32_16x16x32_bf16 v[48:51], v[160:163], v[192:195], v[48:51]
	v_mfma_f32_16x16x32_bf16 v[28:31], v[144:147], v[200:203], v[28:31]
	v_mfma_f32_16x16x32_bf16 v[24:27], v[160:163], v[200:203], v[24:27]
	v_mfma_f32_16x16x32_bf16 v[12:15], v[144:147], v[208:211], v[12:15]
	v_mfma_f32_16x16x32_bf16 v[8:11], v[160:163], v[208:211], v[8:11]
	v_mfma_f32_16x16x32_bf16 v[80:83], v[148:151], v[188:191], v[80:83]
	v_mfma_f32_16x16x32_bf16 v[76:79], v[164:167], v[188:191], v[76:79]
	v_mfma_f32_16x16x32_bf16 v[56:59], v[148:151], v[196:199], v[56:59]
	v_mfma_f32_16x16x32_bf16 v[48:51], v[164:167], v[196:199], v[48:51]
	v_mfma_f32_16x16x32_bf16 v[28:31], v[148:151], v[204:207], v[28:31]
	v_mfma_f32_16x16x32_bf16 v[24:27], v[164:167], v[204:207], v[24:27]
	v_mfma_f32_16x16x32_bf16 v[12:15], v[148:151], v[212:215], v[12:15]
	v_mfma_f32_16x16x32_bf16 v[8:11], v[164:167], v[212:215], v[8:11]
	v_mfma_f32_16x16x32_bf16 v[64:67], v[168:171], v[184:187], v[64:67]
	v_mfma_f32_16x16x32_bf16 v[60:63], v[176:179], v[184:187], v[60:63]
	v_mfma_f32_16x16x32_bf16 v[40:43], v[168:171], v[192:195], v[40:43]
	v_mfma_f32_16x16x32_bf16 v[36:39], v[176:179], v[192:195], v[36:39]
	v_mfma_f32_16x16x32_bf16 v[20:23], v[168:171], v[200:203], v[20:23]
	v_mfma_f32_16x16x32_bf16 v[16:19], v[176:179], v[200:203], v[16:19]
	v_mfma_f32_16x16x32_bf16 v[4:7], v[168:171], v[208:211], v[4:7]
	v_mfma_f32_16x16x32_bf16 v[0:3], v[176:179], v[208:211], v[0:3]
	v_mfma_f32_16x16x32_bf16 v[64:67], v[172:175], v[188:191], v[64:67]
	v_mfma_f32_16x16x32_bf16 v[60:63], v[180:183], v[188:191], v[60:63]
	v_mfma_f32_16x16x32_bf16 v[40:43], v[172:175], v[196:199], v[40:43]
	v_mfma_f32_16x16x32_bf16 v[36:39], v[180:183], v[196:199], v[36:39]
	v_mfma_f32_16x16x32_bf16 v[20:23], v[172:175], v[204:207], v[20:23]
	v_mfma_f32_16x16x32_bf16 v[16:19], v[180:183], v[204:207], v[16:19]
	v_mfma_f32_16x16x32_bf16 v[4:7], v[172:175], v[212:215], v[4:7]
	v_mfma_f32_16x16x32_bf16 v[0:3], v[180:183], v[212:215], v[0:3]
	s_barrier
; #define PG8_STAGE(bufoff, gbase, voff) do { _Pragma("unroll") for (int _i = 0; _i < 2; ++_i) \
;         __builtin_amdgcn_global_load_lds((const unsigned*)((const char*)(gbase) + (voff)[_i]), (PG8_LAS unsigned*)(lds + (bufoff) + ldsw + _i * 8192), 16, 0, 0); } while (0)
; #define PG8_LDA(dst, b, h) do { _Pragma("unroll") for (int m = 0; m < 4; ++m) _Pragma("unroll") for (int k = 0; k < 2; ++k) dst[m][k] = *(const PG8_LAS bf16x8*)(lds + PG8_SA(b, h) + aoff + m * 2048 + k * 1024); } while (0)
; #define PG8_LDB(dst, b, h) do { _Pragma("unroll") for (int n = 0; n < 2; ++n) _Pragma("unroll") for (int k = 0; k < 2; ++k) dst[n][k] = *(const PG8_LAS bf16x8*)(lds + PG8_SB(b, h) + boff + n * 2048 + k * 1024); } while (0)
; #define PG8_MMA(ai, bj, At, Bt) do { __builtin_amdgcn_s_setprio(1); _Pragma("unroll") for (int m = 0; m < 4; ++m) _Pragma("unroll") for (int n = 0; n < 2; ++n) _Pragma("unroll") for (int k = 0; k < 2; ++k) \
;         acc[ai][bj][m][n] = __builtin_amdgcn_mfma_f32_16x16x32_bf16(Bt[n][k], At[m][k], acc[ai][bj][m][n], 0, 0, 0); __builtin_amdgcn_s_setprio(0); } while (0)
; #define PG8_WAIT_V(n) asm volatile("s_waitcnt vmcnt(" #n ")" ::: "memory")
; #define PG8_WAIT_L(n) asm volatile("s_waitcnt lgkmcnt(" #n ")" ::: "memory")
; #define PG8_BAR __builtin_amdgcn_s_barrier()
; #define PG8_SCHED __builtin_amdgcn_sched_barrier(0)
; template <class Epi, class Sched, bool ALIGN_EPI = false, bool SP2 = false>
; __device__ __forceinline__ void gemm_phase(PG8_LAS unsigned char* lds, const Gemm g, const Sched& S, const Epi& E) {
;     ...
;             PG8_LDB(B0, 1, 0); PG8_LDB(B1, 1, 1); PG8_SCHED; PG8_LDA(At, 1, 0); PG8_STAGE(PG8_SA(0, 1), a2 + hstepA, voffA);
;             PG8_WAIT_V(8); PG8_WAIT_L(0); PG8_BAR; PG8_MMA(0, 0, At, B0); PG8_MMA(0, 1, At, B1); PG8_BAR; PG8_SCHED;
;             PG8_LDA(At, 1, 1); PG8_STAGE(PG8_SB(1, 0), b3, voffB); PG8_STAGE(PG8_SB(1, 1), b3 + hstep, voffB); PG8_STAGE(PG8_SA(1, 0), a3, voffA);
;             PG8_WAIT_V(8); PG8_WAIT_L(0); PG8_BAR; PG8_MMA(1, 0, At, B0); PG8_MMA(1, 1, At, B1); PG8_BAR; PG8_SCHED;
;     ...
;         if constexpr (ALIGN_EPI) { if (wr == 0) PG8_BAR; }
	s_add_i32 s65, 0, 0x18000
	s_add_i32 s68, 0, 0x1c000
	ds_read_b128 v[144:147], v216
	ds_read_b128 v[148:151], v216 offset:1024
	ds_read_b128 v[160:163], v216 offset:2048
	ds_read_b128 v[164:167], v216 offset:3072
	ds_read_b128 v[168:171], v217
	ds_read_b128 v[172:175], v217 offset:1024
	ds_read_b128 v[176:179], v217 offset:2048
	ds_read_b128 v[180:183], v217 offset:3072
	s_add_u32 s66, s88, 0x100000
	s_addc_u32 s67, s89, 0
	s_mov_b32 m0, s41
	ds_read_b128 v[184:187], v157 offset:32768
	ds_read_b128 v[188:191], v157 offset:33792
	ds_read_b128 v[192:195], v157 offset:34816
	ds_read_b128 v[196:199], v157 offset:35840
	ds_read_b128 v[200:203], v157 offset:36864
	ds_read_b128 v[204:207], v157 offset:37888
	ds_read_b128 v[208:211], v157 offset:38912
	ds_read_b128 v[212:215], v157 offset:39936
	global_load_lds_dwordx4 v128, s[66:67]
	s_mov_b32 m0, s52
	s_nop 0
	global_load_lds_dwordx4 v132, s[66:67]
	s_waitcnt vmcnt(8)
	s_waitcnt lgkmcnt(0)
	s_barrier
	v_mfma_f32_16x16x32_bf16 v[124:127], v[144:147], v[184:187], v[124:127]
	v_mfma_f32_16x16x32_bf16 v[120:123], v[160:163], v[184:187], v[120:123]
	v_mfma_f32_16x16x32_bf16 v[108:111], v[144:147], v[192:195], v[108:111]
	v_mfma_f32_16x16x32_bf16 v[32:35], v[160:163], v[192:195], v[32:35]
	v_mfma_f32_16x16x32_bf16 v[100:103], v[144:147], v[200:203], v[100:103]
	v_mfma_f32_16x16x32_bf16 v[52:55], v[160:163], v[200:203], v[52:55]
	v_mfma_f32_16x16x32_bf16 v[92:95], v[144:147], v[208:211], v[92:95]
	v_mfma_f32_16x16x32_bf16 v[72:75], v[160:163], v[208:211], v[72:75]
	v_mfma_f32_16x16x32_bf16 v[124:127], v[148:151], v[188:191], v[124:127]
	v_mfma_f32_16x16x32_bf16 v[120:123], v[164:167], v[188:191], v[120:123]
	v_mfma_f32_16x16x32_bf16 v[108:111], v[148:151], v[196:199], v[108:111]
	v_mfma_f32_16x16x32_bf16 v[32:35], v[164:167], v[196:199], v[32:35]
	v_mfma_f32_16x16x32_bf16 v[100:103], v[148:151], v[204:207], v[100:103]
	v_mfma_f32_16x16x32_bf16 v[52:55], v[164:167], v[204:207], v[52:55]
	v_mfma_f32_16x16x32_bf16 v[92:95], v[148:151], v[212:215], v[92:95]
	v_mfma_f32_16x16x32_bf16 v[72:75], v[164:167], v[212:215], v[72:75]
	v_mfma_f32_16x16x32_bf16 v[116:119], v[168:171], v[184:187], v[116:119]
	v_mfma_f32_16x16x32_bf16 v[112:115], v[176:179], v[184:187], v[112:115]
	v_mfma_f32_16x16x32_bf16 v[104:107], v[168:171], v[192:195], v[104:107]
	v_mfma_f32_16x16x32_bf16 v[44:47], v[176:179], v[192:195], v[44:47]
	v_mfma_f32_16x16x32_bf16 v[96:99], v[168:171], v[200:203], v[96:99]
	v_mfma_f32_16x16x32_bf16 v[68:71], v[176:179], v[200:203], v[68:71]
	v_mfma_f32_16x16x32_bf16 v[88:91], v[168:171], v[208:211], v[88:91]
	v_mfma_f32_16x16x32_bf16 v[84:87], v[176:179], v[208:211], v[84:87]
	v_mfma_f32_16x16x32_bf16 v[116:119], v[172:175], v[188:191], v[116:119]
	v_mfma_f32_16x16x32_bf16 v[112:115], v[180:183], v[188:191], v[112:115]
	v_mfma_f32_16x16x32_bf16 v[104:107], v[172:175], v[196:199], v[104:107]
	v_mfma_f32_16x16x32_bf16 v[44:47], v[180:183], v[196:199], v[44:47]
	v_mfma_f32_16x16x32_bf16 v[96:99], v[172:175], v[204:207], v[96:99]
	v_mfma_f32_16x16x32_bf16 v[68:71], v[180:183], v[204:207], v[68:71]
	v_mfma_f32_16x16x32_bf16 v[88:91], v[172:175], v[212:215], v[88:91]
	v_mfma_f32_16x16x32_bf16 v[84:87], v[180:183], v[212:215], v[84:87]
	s_barrier
	s_add_i32 s65, s65, s3
	s_mov_b32 m0, s65
	ds_read_b128 v[184:187], v157 offset:49152
	ds_read_b128 v[188:191], v157 offset:50176
	ds_read_b128 v[192:195], v157 offset:51200
	ds_read_b128 v[196:199], v157 offset:52224
	ds_read_b128 v[200:203], v157 offset:53248
	ds_read_b128 v[204:207], v157 offset:54272
	ds_read_b128 v[208:211], v157 offset:55296
	ds_read_b128 v[212:215], v157 offset:56320
	global_load_lds_dwordx4 v130, s[98:99]
	s_add_i32 m0, s65, 0x2000
	s_add_u32 s66, s86, 0x100080
	s_addc_u32 s67, s87, 0
	s_add_i32 s65, s68, s3
	global_load_lds_dwordx4 v134, s[98:99]
	s_mov_b32 m0, s65
	s_nop 0
	global_load_lds_dwordx4 v130, s[66:67]
	s_add_i32 m0, s65, 0x2000
	s_nop 0
	global_load_lds_dwordx4 v134, s[66:67]
	s_mov_b32 m0, s54
	s_nop 0
	global_load_lds_dwordx4 v128, s[100:101]
	s_mov_b32 m0, s55
	s_nop 0
	global_load_lds_dwordx4 v132, s[100:101]
	s_waitcnt vmcnt(8)
	s_waitcnt lgkmcnt(0)
	s_barrier
	v_mfma_f32_16x16x32_bf16 v[80:83], v[144:147], v[184:187], v[80:83]
	v_mfma_f32_16x16x32_bf16 v[76:79], v[160:163], v[184:187], v[76:79]
	v_mfma_f32_16x16x32_bf16 v[56:59], v[144:147], v[192:195], v[56:59]
	v_mfma_f32_16x16x32_bf16 v[48:51], v[160:163], v[192:195], v[48:51]
	v_mfma_f32_16x16x32_bf16 v[28:31], v[144:147], v[200:203], v[28:31]
	v_mfma_f32_16x16x32_bf16 v[24:27], v[160:163], v[200:203], v[24:27]
	v_mfma_f32_16x16x32_bf16 v[12:15], v[144:147], v[208:211], v[12:15]
	v_mfma_f32_16x16x32_bf16 v[8:11], v[160:163], v[208:211], v[8:11]
	v_mfma_f32_16x16x32_bf16 v[80:83], v[148:151], v[188:191], v[80:83]
	v_mfma_f32_16x16x32_bf16 v[76:79], v[164:167], v[188:191], v[76:79]
	v_mfma_f32_16x16x32_bf16 v[56:59], v[148:151], v[196:199], v[56:59]
	v_mfma_f32_16x16x32_bf16 v[48:51], v[164:167], v[196:199], v[48:51]
	v_mfma_f32_16x16x32_bf16 v[28:31], v[148:151], v[204:207], v[28:31]
	v_mfma_f32_16x16x32_bf16 v[24:27], v[164:167], v[204:207], v[24:27]
	v_mfma_f32_16x16x32_bf16 v[12:15], v[148:151], v[212:215], v[12:15]
	v_mfma_f32_16x16x32_bf16 v[8:11], v[164:167], v[212:215], v[8:11]
	v_mfma_f32_16x16x32_bf16 v[64:67], v[168:171], v[184:187], v[64:67]
	v_mfma_f32_16x16x32_bf16 v[60:63], v[176:179], v[184:187], v[60:63]
	v_mfma_f32_16x16x32_bf16 v[40:43], v[168:171], v[192:195], v[40:43]
	v_mfma_f32_16x16x32_bf16 v[36:39], v[176:179], v[192:195], v[36:39]
	v_mfma_f32_16x16x32_bf16 v[20:23], v[168:171], v[200:203], v[20:23]
	v_mfma_f32_16x16x32_bf16 v[16:19], v[176:179], v[200:203], v[16:19]
	v_mfma_f32_16x16x32_bf16 v[4:7], v[168:171], v[208:211], v[4:7]
	v_mfma_f32_16x16x32_bf16 v[0:3], v[176:179], v[208:211], v[0:3]
	v_mfma_f32_16x16x32_bf16 v[64:67], v[172:175], v[188:191], v[64:67]
	v_mfma_f32_16x16x32_bf16 v[60:63], v[180:183], v[188:191], v[60:63]
	v_mfma_f32_16x16x32_bf16 v[40:43], v[172:175], v[196:199], v[40:43]
	v_mfma_f32_16x16x32_bf16 v[36:39], v[180:183], v[196:199], v[36:39]
	v_mfma_f32_16x16x32_bf16 v[20:23], v[172:175], v[204:207], v[20:23]
	v_mfma_f32_16x16x32_bf16 v[16:19], v[180:183], v[204:207], v[16:19]
	v_mfma_f32_16x16x32_bf16 v[4:7], v[172:175], v[212:215], v[4:7]
	v_mfma_f32_16x16x32_bf16 v[0:3], v[180:183], v[212:215], v[0:3]
	s_barrier
	s_add_i32 s64, s64, 2
	s_add_u32 s84, s84, 0x100
	s_addc_u32 s85, s85, 0
	s_add_u32 s62, s62, 0x100
	s_addc_u32 s63, s63, 0
	s_cmp_gt_u32 s64, 61
	s_cbranch_scc0 .LBB0_1631
	s_and_b64 vcc, exec, s[20:21]
	s_cbranch_vccz .LBB0_1634
	s_barrier

; #define PG8_STAGE(bufoff, gbase, voff) do { _Pragma("unroll") for (int _i = 0; _i < 2; ++_i) \
;         __builtin_amdgcn_global_load_lds((const unsigned*)((const char*)(gbase) + (voff)[_i]), (PG8_LAS unsigned*)(lds + (bufoff) + ldsw + _i * 8192), 16, 0, 0); } while (0)
; #define PG8_LDA(dst, b, h) do { _Pragma("unroll") for (int m = 0; m < 4; ++m) _Pragma("unroll") for (int k = 0; k < 2; ++k) dst[m][k] = *(const PG8_LAS bf16x8*)(lds + PG8_SA(b, h) + aoff + m * 2048 + k * 1024); } while (0)
; #define PG8_LDB(dst, b, h) do { _Pragma("unroll") for (int n = 0; n < 2; ++n) _Pragma("unroll") for (int k = 0; k < 2; ++k) dst[n][k] = *(const PG8_LAS bf16x8*)(lds + PG8_SB(b, h) + boff + n * 2048 + k * 1024); } while (0)
; #define PG8_SCHED __builtin_amdgcn_sched_barrier(0)
; template <class Epi, class Sched, bool ALIGN_EPI = false, bool SP2 = false>
; __device__ __forceinline__ void gemm_phase(PG8_LAS unsigned char* lds, const Gemm g, const Sched& S, const Epi& E) {
;     ...
;         const bool has_next = S.next(ui + 1, nxt);
;         const char* nA = has_next ? (const char*)g.A + (size_t)nxt.pm * tstep : cA; const char* nB = has_next ? (const char*)g.Bt + (size_t)nxt.pn * tstep : cB;
;     ...
;             PG8_LDB(B0, 0, 0); PG8_LDB(B1, 0, 1); PG8_SCHED; PG8_LDA(At, 0, 0); PG8_STAGE(PG8_SA(1, 1), a1 + hstepA, voffA);
;     ...
;         for (int a = 0; a < 2; ++a)
; #pragma unroll
;             for (int b = 0; b < 2; ++b)
; #pragma unroll
;                 for (int m = 0; m < 4; ++m)
; #pragma unroll
;                     for (int n = 0; n < 2; ++n) acc[a][b][m][n] = (f32x4){0.f, 0.f, 0.f, 0.f};
.LBB0_1740:
	s_ashr_i32 s21, s20, 31
	s_lshl_b64 s[22:23], s[20:21], 21
	s_add_u32 s22, s96, s22
	s_addc_u32 s23, s97, s23
	s_and_b64 s[24:25], s[0:1], exec
	s_cselect_b32 s21, s23, s35
	s_cselect_b32 s27, s22, s34
	s_ashr_i32 s19, s18, 31
	s_lshl_b64 s[24:25], s[18:19], 21
	s_add_u32 s24, s3, s24
	s_addc_u32 s25, s29, s25
	s_and_b64 s[66:67], s[0:1], exec
	s_cselect_b32 s19, s25, s41
	s_cselect_b32 s31, s24, s40
	s_add_u32 s34, s34, 0x100080
	s_addc_u32 s35, s35, 0
	s_add_u32 s65, s40, 0x100
	v_mov_b32_e32 v0, 0
	s_addc_u32 s66, s41, 0
	s_mov_b32 s67, -2
	v_mov_b32_e32 v1, v0
	v_mov_b32_e32 v2, v0
	v_mov_b32_e32 v3, v0
	v_mov_b32_e32 v4, v0
	v_mov_b32_e32 v5, v0
	v_mov_b32_e32 v6, v0
	v_mov_b32_e32 v7, v0
	v_mov_b32_e32 v16, v0
	v_mov_b32_e32 v17, v0
	v_mov_b32_e32 v18, v0
	v_mov_b32_e32 v19, v0
	v_mov_b32_e32 v20, v0
	v_mov_b32_e32 v21, v0
	v_mov_b32_e32 v22, v0
	v_mov_b32_e32 v23, v0
	v_mov_b32_e32 v32, v0
	v_mov_b32_e32 v33, v0
	v_mov_b32_e32 v34, v0
	v_mov_b32_e32 v35, v0
	s_waitcnt vmcnt(0)
	v_mov_b32_e32 v36, v0
	v_mov_b32_e32 v37, v0
	v_mov_b32_e32 v38, v0
	v_mov_b32_e32 v39, v0
	v_mov_b32_e32 v48, v0
	v_mov_b32_e32 v49, v0
	v_mov_b32_e32 v50, v0
	v_mov_b32_e32 v51, v0
	v_mov_b32_e32 v52, v0
	v_mov_b32_e32 v53, v0
	v_mov_b32_e32 v54, v0
	v_mov_b32_e32 v55, v0
	v_mov_b32_e32 v8, v0
	v_mov_b32_e32 v9, v0
	v_mov_b32_e32 v10, v0
	v_mov_b32_e32 v11, v0
	v_mov_b32_e32 v12, v0
	v_mov_b32_e32 v13, v0
	v_mov_b32_e32 v14, v0
	v_mov_b32_e32 v15, v0
	v_mov_b32_e32 v24, v0
	v_mov_b32_e32 v25, v0
	v_mov_b32_e32 v26, v0
	v_mov_b32_e32 v27, v0
	v_mov_b32_e32 v28, v0
	v_mov_b32_e32 v29, v0
	v_mov_b32_e32 v30, v0
	v_mov_b32_e32 v31, v0
	v_mov_b32_e32 v40, v0
	v_mov_b32_e32 v41, v0
	v_mov_b32_e32 v42, v0
	v_mov_b32_e32 v43, v0
	v_mov_b32_e32 v44, v0
	v_mov_b32_e32 v45, v0
	v_mov_b32_e32 v46, v0
	v_mov_b32_e32 v47, v0
	v_mov_b32_e32 v56, v0
	v_mov_b32_e32 v57, v0
	v_mov_b32_e32 v58, v0
	v_mov_b32_e32 v59, v0
	v_mov_b32_e32 v60, v0
	v_mov_b32_e32 v61, v0
	v_mov_b32_e32 v62, v0
	v_mov_b32_e32 v63, v0
	v_mov_b32_e32 v64, v0
	v_mov_b32_e32 v65, v0
	v_mov_b32_e32 v66, v0
	v_mov_b32_e32 v67, v0
	v_mov_b32_e32 v68, v0
	v_mov_b32_e32 v69, v0
	v_mov_b32_e32 v70, v0
	v_mov_b32_e32 v71, v0
	v_mov_b32_e32 v80, v0
	v_mov_b32_e32 v81, v0
	v_mov_b32_e32 v82, v0
	v_mov_b32_e32 v83, v0
	v_mov_b32_e32 v84, v0
	v_mov_b32_e32 v85, v0
	v_mov_b32_e32 v86, v0
	v_mov_b32_e32 v87, v0
	v_mov_b32_e32 v96, v0
	v_mov_b32_e32 v97, v0
	v_mov_b32_e32 v98, v0
	v_mov_b32_e32 v99, v0
	v_mov_b32_e32 v100, v0
	v_mov_b32_e32 v101, v0
	v_mov_b32_e32 v102, v0
	v_mov_b32_e32 v103, v0
	v_mov_b32_e32 v112, v0
	v_mov_b32_e32 v113, v0
	v_mov_b32_e32 v114, v0
	v_mov_b32_e32 v115, v0
	v_mov_b32_e32 v116, v0
	v_mov_b32_e32 v117, v0
	v_mov_b32_e32 v118, v0
	v_mov_b32_e32 v119, v0
	v_mov_b32_e32 v72, v0
	v_mov_b32_e32 v73, v0
	v_mov_b32_e32 v74, v0
	v_mov_b32_e32 v75, v0
	v_mov_b32_e32 v76, v0
	v_mov_b32_e32 v77, v0
	v_mov_b32_e32 v78, v0
	v_mov_b32_e32 v79, v0
	v_mov_b32_e32 v88, v0
	v_mov_b32_e32 v89, v0
	v_mov_b32_e32 v90, v0
	v_mov_b32_e32 v91, v0
	v_mov_b32_e32 v92, v0
	v_mov_b32_e32 v93, v0
	v_mov_b32_e32 v94, v0
	v_mov_b32_e32 v95, v0
	v_mov_b32_e32 v104, v0
	v_mov_b32_e32 v105, v0
	v_mov_b32_e32 v106, v0
	v_mov_b32_e32 v107, v0
	v_mov_b32_e32 v108, v0
	v_mov_b32_e32 v109, v0
	v_mov_b32_e32 v110, v0
	v_mov_b32_e32 v111, v0
	v_mov_b32_e32 v120, v0
	v_mov_b32_e32 v121, v0
	v_mov_b32_e32 v122, v0
	v_mov_b32_e32 v123, v0
	v_mov_b32_e32 v124, v0
	v_mov_b32_e32 v125, v0
	v_mov_b32_e32 v126, v0
	v_mov_b32_e32 v127, v0
	v_add_u32_e32 v154, 0x18000, v157
	v_add_u32_e32 v155, 0x1c000, v157
.LBB0_1741:
	ds_read_b128 v[150:153], v158
	ds_read_b128 v[162:165], v158 offset:1024
	ds_read_b128 v[166:169], v158 offset:2048
	ds_read_b128 v[170:173], v158 offset:3072
	ds_read_b128 v[174:177], v159
	ds_read_b128 v[178:181], v159 offset:1024
	ds_read_b128 v[182:185], v159 offset:2048
	ds_read_b128 v[186:189], v159 offset:3072
	s_add_u32 s40, s34, 0xfff00080
	s_addc_u32 s41, s35, -1
	s_cmp_eq_u32 s67, 60
	s_cselect_b32 s85, s21, s41
	s_cselect_b32 s84, s27, s40
	s_cselect_b32 s41, s19, s66
	s_cselect_b32 s40, s31, s65
	s_add_i32 m0, s53, 0xc000
	ds_read_b128 v[190:193], v160
	ds_read_b128 v[194:197], v160 offset:1024
	ds_read_b128 v[198:201], v160 offset:2048
	ds_read_b128 v[202:205], v160 offset:3072
	ds_read_b128 v[206:209], v160 offset:4096
	ds_read_b128 v[210:213], v160 offset:5120
	ds_read_b128 v[214:217], v160 offset:6144
	ds_read_b128 v[218:221], v160 offset:7168
	global_load_lds_dwordx4 v140, s[34:35]
	s_add_i32 m0, s53, 0xe000
	s_nop 0
	global_load_lds_dwordx4 v142, s[34:35]
	s_waitcnt vmcnt(8)
	s_waitcnt lgkmcnt(0)
	s_barrier
; #define PG8_STAGE(bufoff, gbase, voff) do { _Pragma("unroll") for (int _i = 0; _i < 2; ++_i) \
;         __builtin_amdgcn_global_load_lds((const unsigned*)((const char*)(gbase) + (voff)[_i]), (PG8_LAS unsigned*)(lds + (bufoff) + ldsw + _i * 8192), 16, 0, 0); } while (0)
; #define PG8_LDA(dst, b, h) do { _Pragma("unroll") for (int m = 0; m < 4; ++m) _Pragma("unroll") for (int k = 0; k < 2; ++k) dst[m][k] = *(const PG8_LAS bf16x8*)(lds + PG8_SA(b, h) + aoff + m * 2048 + k * 1024); } while (0)
; #define PG8_MMA(ai, bj, At, Bt) do { __builtin_amdgcn_s_setprio(1); _Pragma("unroll") for (int m = 0; m < 4; ++m) _Pragma("unroll") for (int n = 0; n < 2; ++n) _Pragma("unroll") for (int k = 0; k < 2; ++k) \
;         acc[ai][bj][m][n] = __builtin_amdgcn_mfma_f32_16x16x32_bf16(Bt[n][k], At[m][k], acc[ai][bj][m][n], 0, 0, 0); __builtin_amdgcn_s_setprio(0); } while (0)
; #define PG8_WAIT_V(n) asm volatile("s_waitcnt vmcnt(" #n ")" ::: "memory")
; #define PG8_WAIT_L(n) asm volatile("s_waitcnt lgkmcnt(" #n ")" ::: "memory")
; #define PG8_BAR __builtin_amdgcn_s_barrier()
; #define PG8_SCHED __builtin_amdgcn_sched_barrier(0)
; template <class Epi, class Sched, bool ALIGN_EPI = false, bool SP2 = false>
; __device__ __forceinline__ void gemm_phase(PG8_LAS unsigned char* lds, const Gemm g, const Sched& S, const Epi& E) {
;     ...
;             PG8_WAIT_V(8); PG8_WAIT_L(0); PG8_BAR; PG8_MMA(0, 0, At, B0); PG8_MMA(0, 1, At, B1); PG8_BAR; PG8_SCHED;
;             PG8_LDA(At, 0, 1); PG8_STAGE(PG8_SB(0, 0), b2, voffB); PG8_STAGE(PG8_SB(0, 1), b2 + hstep, voffB); PG8_STAGE(PG8_SA(0, 0), a2, voffA);
;             PG8_WAIT_V(8); PG8_WAIT_L(0); PG8_BAR; PG8_MMA(1, 0, At, B0); PG8_MMA(1, 1, At, B1); PG8_BAR; PG8_SCHED;
	v_mfma_f32_16x16x32_bf16 v[124:127], v[150:153], v[190:193], v[124:127]
	v_mfma_f32_16x16x32_bf16 v[120:123], v[166:169], v[190:193], v[120:123]
	v_mfma_f32_16x16x32_bf16 v[108:111], v[150:153], v[198:201], v[108:111]
	v_mfma_f32_16x16x32_bf16 v[104:107], v[166:169], v[198:201], v[104:107]
	v_mfma_f32_16x16x32_bf16 v[92:95], v[150:153], v[206:209], v[92:95]
	v_mfma_f32_16x16x32_bf16 v[88:91], v[166:169], v[206:209], v[88:91]
	v_mfma_f32_16x16x32_bf16 v[76:79], v[150:153], v[214:217], v[76:79]
	v_mfma_f32_16x16x32_bf16 v[72:75], v[166:169], v[214:217], v[72:75]
	v_mfma_f32_16x16x32_bf16 v[124:127], v[162:165], v[194:197], v[124:127]
	v_mfma_f32_16x16x32_bf16 v[120:123], v[170:173], v[194:197], v[120:123]
	v_mfma_f32_16x16x32_bf16 v[108:111], v[162:165], v[202:205], v[108:111]
	v_mfma_f32_16x16x32_bf16 v[104:107], v[170:173], v[202:205], v[104:107]
	v_mfma_f32_16x16x32_bf16 v[92:95], v[162:165], v[210:213], v[92:95]
	v_mfma_f32_16x16x32_bf16 v[88:91], v[170:173], v[210:213], v[88:91]
	v_mfma_f32_16x16x32_bf16 v[76:79], v[162:165], v[218:221], v[76:79]
	v_mfma_f32_16x16x32_bf16 v[72:75], v[170:173], v[218:221], v[72:75]
	v_mfma_f32_16x16x32_bf16 v[116:119], v[174:177], v[190:193], v[116:119]
	v_mfma_f32_16x16x32_bf16 v[112:115], v[182:185], v[190:193], v[112:115]
	v_mfma_f32_16x16x32_bf16 v[100:103], v[174:177], v[198:201], v[100:103]
	v_mfma_f32_16x16x32_bf16 v[96:99], v[182:185], v[198:201], v[96:99]
	v_mfma_f32_16x16x32_bf16 v[84:87], v[174:177], v[206:209], v[84:87]
	v_mfma_f32_16x16x32_bf16 v[80:83], v[182:185], v[206:209], v[80:83]
	v_mfma_f32_16x16x32_bf16 v[68:71], v[174:177], v[214:217], v[68:71]
	v_mfma_f32_16x16x32_bf16 v[64:67], v[182:185], v[214:217], v[64:67]
	v_mfma_f32_16x16x32_bf16 v[116:119], v[178:181], v[194:197], v[116:119]
	v_mfma_f32_16x16x32_bf16 v[112:115], v[186:189], v[194:197], v[112:115]
	v_mfma_f32_16x16x32_bf16 v[100:103], v[178:181], v[202:205], v[100:103]
	v_mfma_f32_16x16x32_bf16 v[96:99], v[186:189], v[202:205], v[96:99]
	v_mfma_f32_16x16x32_bf16 v[84:87], v[178:181], v[210:213], v[84:87]
	v_mfma_f32_16x16x32_bf16 v[80:83], v[186:189], v[210:213], v[80:83]
	v_mfma_f32_16x16x32_bf16 v[68:71], v[178:181], v[218:221], v[68:71]
	v_mfma_f32_16x16x32_bf16 v[64:67], v[186:189], v[218:221], v[64:67]
	s_barrier
	s_add_u32 s98, s40, s12
	s_addc_u32 s99, s41, s13
	s_add_u32 s100, s84, s12
	s_addc_u32 s101, s85, s13
	s_add_i32 s68, s62, s33
	s_mov_b32 m0, s68
	ds_read_b128 v[190:193], v160 offset:16384
	ds_read_b128 v[194:197], v160 offset:17408
	ds_read_b128 v[198:201], v160 offset:18432
	ds_read_b128 v[202:205], v160 offset:19456
	ds_read_b128 v[206:209], v160 offset:20480
	ds_read_b128 v[210:213], v160 offset:21504
	ds_read_b128 v[214:217], v160 offset:22528
	ds_read_b128 v[218:221], v160 offset:23552
	global_load_lds_dwordx4 v132, s[40:41]
	s_add_i32 m0, s68, 0x2000
	s_add_u32 s68, s40, 0x100000
	s_addc_u32 s69, s41, 0
	s_add_i32 s70, s63, s33
	global_load_lds_dwordx4 v128, s[40:41]
	s_mov_b32 m0, s70
	s_nop 0
	global_load_lds_dwordx4 v132, s[68:69]
	s_add_i32 m0, s70, 0x2000
	s_nop 0
	global_load_lds_dwordx4 v128, s[68:69]
	s_mov_b32 m0, s53
	s_nop 0
	global_load_lds_dwordx4 v134, s[84:85]
	s_mov_b32 m0, s54
	s_nop 0
	global_load_lds_dwordx4 v130, s[84:85]
	s_waitcnt vmcnt(8)
	s_waitcnt lgkmcnt(0)
	s_barrier
	v_mfma_f32_16x16x32_bf16 v[60:63], v[150:153], v[190:193], v[60:63]
	v_mfma_f32_16x16x32_bf16 v[56:59], v[166:169], v[190:193], v[56:59]
	v_mfma_f32_16x16x32_bf16 v[44:47], v[150:153], v[198:201], v[44:47]
	v_mfma_f32_16x16x32_bf16 v[40:43], v[166:169], v[198:201], v[40:43]
	v_mfma_f32_16x16x32_bf16 v[28:31], v[150:153], v[206:209], v[28:31]
	v_mfma_f32_16x16x32_bf16 v[24:27], v[166:169], v[206:209], v[24:27]
	v_mfma_f32_16x16x32_bf16 v[12:15], v[150:153], v[214:217], v[12:15]
	v_mfma_f32_16x16x32_bf16 v[8:11], v[166:169], v[214:217], v[8:11]
	v_mfma_f32_16x16x32_bf16 v[60:63], v[162:165], v[194:197], v[60:63]
	v_mfma_f32_16x16x32_bf16 v[56:59], v[170:173], v[194:197], v[56:59]
	v_mfma_f32_16x16x32_bf16 v[44:47], v[162:165], v[202:205], v[44:47]
	v_mfma_f32_16x16x32_bf16 v[40:43], v[170:173], v[202:205], v[40:43]
	v_mfma_f32_16x16x32_bf16 v[28:31], v[162:165], v[210:213], v[28:31]
	v_mfma_f32_16x16x32_bf16 v[24:27], v[170:173], v[210:213], v[24:27]
	v_mfma_f32_16x16x32_bf16 v[12:15], v[162:165], v[218:221], v[12:15]
	v_mfma_f32_16x16x32_bf16 v[8:11], v[170:173], v[218:221], v[8:11]
	v_mfma_f32_16x16x32_bf16 v[52:55], v[174:177], v[190:193], v[52:55]
	v_mfma_f32_16x16x32_bf16 v[48:51], v[182:185], v[190:193], v[48:51]
	v_mfma_f32_16x16x32_bf16 v[36:39], v[174:177], v[198:201], v[36:39]
	v_mfma_f32_16x16x32_bf16 v[32:35], v[182:185], v[198:201], v[32:35]
	v_mfma_f32_16x16x32_bf16 v[20:23], v[174:177], v[206:209], v[20:23]
	v_mfma_f32_16x16x32_bf16 v[16:19], v[182:185], v[206:209], v[16:19]
	v_mfma_f32_16x16x32_bf16 v[4:7], v[174:177], v[214:217], v[4:7]
	v_mfma_f32_16x16x32_bf16 v[0:3], v[182:185], v[214:217], v[0:3]
	v_mfma_f32_16x16x32_bf16 v[52:55], v[178:181], v[194:197], v[52:55]
	v_mfma_f32_16x16x32_bf16 v[48:51], v[186:189], v[194:197], v[48:51]
	v_mfma_f32_16x16x32_bf16 v[36:39], v[178:181], v[202:205], v[36:39]
	v_mfma_f32_16x16x32_bf16 v[32:35], v[186:189], v[202:205], v[32:35]
	v_mfma_f32_16x16x32_bf16 v[20:23], v[178:181], v[210:213], v[20:23]
	v_mfma_f32_16x16x32_bf16 v[16:19], v[186:189], v[210:213], v[16:19]
	v_mfma_f32_16x16x32_bf16 v[4:7], v[178:181], v[218:221], v[4:7]
	v_mfma_f32_16x16x32_bf16 v[0:3], v[186:189], v[218:221], v[0:3]
	s_barrier
; #define PG8_STAGE(bufoff, gbase, voff) do { _Pragma("unroll") for (int _i = 0; _i < 2; ++_i) \
;         __builtin_amdgcn_global_load_lds((const unsigned*)((const char*)(gbase) + (voff)[_i]), (PG8_LAS unsigned*)(lds + (bufoff) + ldsw + _i * 8192), 16, 0, 0); } while (0)
; #define PG8_LDA(dst, b, h) do { _Pragma("unroll") for (int m = 0; m < 4; ++m) _Pragma("unroll") for (int k = 0; k < 2; ++k) dst[m][k] = *(const PG8_LAS bf16x8*)(lds + PG8_SA(b, h) + aoff + m * 2048 + k * 1024); } while (0)
; #define PG8_LDB(dst, b, h) do { _Pragma("unroll") for (int n = 0; n < 2; ++n) _Pragma("unroll") for (int k = 0; k < 2; ++k) dst[n][k] = *(const PG8_LAS bf16x8*)(lds + PG8_SB(b, h) + boff + n * 2048 + k * 1024); } while (0)
; #define PG8_MMA(ai, bj, At, Bt) do { __builtin_amdgcn_s_setprio(1); _Pragma("unroll") for (int m = 0; m < 4; ++m) _Pragma("unroll") for (int n = 0; n < 2; ++n) _Pragma("unroll") for (int k = 0; k < 2; ++k) \
;         acc[ai][bj][m][n] = __builtin_amdgcn_mfma_f32_16x16x32_bf16(Bt[n][k], At[m][k], acc[ai][bj][m][n], 0, 0, 0); __builtin_amdgcn_s_setprio(0); } while (0)
; #define PG8_WAIT_V(n) asm volatile("s_waitcnt vmcnt(" #n ")" ::: "memory")
; #define PG8_WAIT_L(n) asm volatile("s_waitcnt lgkmcnt(" #n ")" ::: "memory")
; #define PG8_BAR __builtin_amdgcn_s_barrier()
; #define PG8_SCHED __builtin_amdgcn_sched_barrier(0)
; template <class Epi, class Sched, bool ALIGN_EPI = false, bool SP2 = false>
; __device__ __forceinline__ void gemm_phase(PG8_LAS unsigned char* lds, const Gemm g, const Sched& S, const Epi& E) {
;     ...
;             PG8_LDB(B0, 1, 0); PG8_LDB(B1, 1, 1); PG8_SCHED; PG8_LDA(At, 1, 0); PG8_STAGE(PG8_SA(0, 1), a2 + hstepA, voffA);
;             PG8_WAIT_V(8); PG8_WAIT_L(0); PG8_BAR; PG8_MMA(0, 0, At, B0); PG8_MMA(0, 1, At, B1); PG8_BAR; PG8_SCHED;
;             PG8_LDA(At, 1, 1); PG8_STAGE(PG8_SB(1, 0), b3, voffB); PG8_STAGE(PG8_SB(1, 1), b3 + hstep, voffB); PG8_STAGE(PG8_SA(1, 0), a3, voffA);
;             PG8_WAIT_V(8); PG8_WAIT_L(0); PG8_BAR; PG8_MMA(1, 0, At, B0); PG8_MMA(1, 1, At, B1); PG8_BAR; PG8_SCHED;
;     ...
;         if constexpr (ALIGN_EPI) { if (wr == 0) PG8_BAR; }
	s_add_i32 s70, 0, 0x18000
	s_add_i32 s71, 0, 0x1c000
	ds_read_b128 v[150:153], v154
	ds_read_b128 v[162:165], v154 offset:1024
	ds_read_b128 v[166:169], v154 offset:2048
	ds_read_b128 v[170:173], v154 offset:3072
	ds_read_b128 v[174:177], v155
	ds_read_b128 v[178:181], v155 offset:1024
	ds_read_b128 v[182:185], v155 offset:2048
	ds_read_b128 v[186:189], v155 offset:3072
	s_add_u32 s68, s84, 0x100000
	s_addc_u32 s69, s85, 0
	s_mov_b32 m0, s55
	ds_read_b128 v[190:193], v160 offset:32768
	ds_read_b128 v[194:197], v160 offset:33792
	ds_read_b128 v[198:201], v160 offset:34816
	ds_read_b128 v[202:205], v160 offset:35840
	ds_read_b128 v[206:209], v160 offset:36864
	ds_read_b128 v[210:213], v160 offset:37888
	ds_read_b128 v[214:217], v160 offset:38912
	ds_read_b128 v[218:221], v160 offset:39936
	global_load_lds_dwordx4 v134, s[68:69]
	s_mov_b32 m0, s56
	s_nop 0
	global_load_lds_dwordx4 v130, s[68:69]
	s_waitcnt vmcnt(8)
	s_waitcnt lgkmcnt(0)
	s_barrier
	v_mfma_f32_16x16x32_bf16 v[124:127], v[150:153], v[190:193], v[124:127]
	v_mfma_f32_16x16x32_bf16 v[120:123], v[166:169], v[190:193], v[120:123]
	v_mfma_f32_16x16x32_bf16 v[108:111], v[150:153], v[198:201], v[108:111]
	v_mfma_f32_16x16x32_bf16 v[104:107], v[166:169], v[198:201], v[104:107]
	v_mfma_f32_16x16x32_bf16 v[92:95], v[150:153], v[206:209], v[92:95]
	v_mfma_f32_16x16x32_bf16 v[88:91], v[166:169], v[206:209], v[88:91]
	v_mfma_f32_16x16x32_bf16 v[76:79], v[150:153], v[214:217], v[76:79]
	v_mfma_f32_16x16x32_bf16 v[72:75], v[166:169], v[214:217], v[72:75]
	v_mfma_f32_16x16x32_bf16 v[124:127], v[162:165], v[194:197], v[124:127]
	v_mfma_f32_16x16x32_bf16 v[120:123], v[170:173], v[194:197], v[120:123]
	v_mfma_f32_16x16x32_bf16 v[108:111], v[162:165], v[202:205], v[108:111]
	v_mfma_f32_16x16x32_bf16 v[104:107], v[170:173], v[202:205], v[104:107]
	v_mfma_f32_16x16x32_bf16 v[92:95], v[162:165], v[210:213], v[92:95]
	v_mfma_f32_16x16x32_bf16 v[88:91], v[170:173], v[210:213], v[88:91]
	v_mfma_f32_16x16x32_bf16 v[76:79], v[162:165], v[218:221], v[76:79]
	v_mfma_f32_16x16x32_bf16 v[72:75], v[170:173], v[218:221], v[72:75]
	v_mfma_f32_16x16x32_bf16 v[116:119], v[174:177], v[190:193], v[116:119]
	v_mfma_f32_16x16x32_bf16 v[112:115], v[182:185], v[190:193], v[112:115]
	v_mfma_f32_16x16x32_bf16 v[100:103], v[174:177], v[198:201], v[100:103]
	v_mfma_f32_16x16x32_bf16 v[96:99], v[182:185], v[198:201], v[96:99]
	v_mfma_f32_16x16x32_bf16 v[84:87], v[174:177], v[206:209], v[84:87]
	v_mfma_f32_16x16x32_bf16 v[80:83], v[182:185], v[206:209], v[80:83]
	v_mfma_f32_16x16x32_bf16 v[68:71], v[174:177], v[214:217], v[68:71]
	v_mfma_f32_16x16x32_bf16 v[64:67], v[182:185], v[214:217], v[64:67]
	v_mfma_f32_16x16x32_bf16 v[116:119], v[178:181], v[194:197], v[116:119]
	v_mfma_f32_16x16x32_bf16 v[112:115], v[186:189], v[194:197], v[112:115]
	v_mfma_f32_16x16x32_bf16 v[100:103], v[178:181], v[202:205], v[100:103]
	v_mfma_f32_16x16x32_bf16 v[96:99], v[186:189], v[202:205], v[96:99]
	v_mfma_f32_16x16x32_bf16 v[84:87], v[178:181], v[210:213], v[84:87]
	v_mfma_f32_16x16x32_bf16 v[80:83], v[186:189], v[210:213], v[80:83]
	v_mfma_f32_16x16x32_bf16 v[68:71], v[178:181], v[218:221], v[68:71]
	v_mfma_f32_16x16x32_bf16 v[64:67], v[186:189], v[218:221], v[64:67]
	s_barrier
	s_add_i32 s68, s70, s33
	s_mov_b32 m0, s68
	ds_read_b128 v[190:193], v160 offset:49152
	ds_read_b128 v[194:197], v160 offset:50176
	ds_read_b128 v[198:201], v160 offset:51200
	ds_read_b128 v[202:205], v160 offset:52224
	ds_read_b128 v[206:209], v160 offset:53248
	ds_read_b128 v[210:213], v160 offset:54272
	ds_read_b128 v[214:217], v160 offset:55296
	ds_read_b128 v[218:221], v160 offset:56320
	global_load_lds_dwordx4 v132, s[98:99]
	s_add_i32 m0, s68, 0x2000
	s_add_u32 s40, s40, 0x100080
	s_addc_u32 s41, s41, 0
	s_add_i32 s68, s71, s33
	global_load_lds_dwordx4 v128, s[98:99]
	s_mov_b32 m0, s68
	s_nop 0
	global_load_lds_dwordx4 v132, s[40:41]
	s_add_i32 m0, s68, 0x2000
	s_nop 0
	global_load_lds_dwordx4 v128, s[40:41]
	s_mov_b32 m0, s60
	s_nop 0
	global_load_lds_dwordx4 v134, s[100:101]
	s_mov_b32 m0, s61
	s_nop 0
	global_load_lds_dwordx4 v130, s[100:101]
	s_waitcnt vmcnt(8)
	s_waitcnt lgkmcnt(0)
	s_barrier
	v_mfma_f32_16x16x32_bf16 v[60:63], v[150:153], v[190:193], v[60:63]
	v_mfma_f32_16x16x32_bf16 v[56:59], v[166:169], v[190:193], v[56:59]
	v_mfma_f32_16x16x32_bf16 v[44:47], v[150:153], v[198:201], v[44:47]
	v_mfma_f32_16x16x32_bf16 v[40:43], v[166:169], v[198:201], v[40:43]
	v_mfma_f32_16x16x32_bf16 v[28:31], v[150:153], v[206:209], v[28:31]
	v_mfma_f32_16x16x32_bf16 v[24:27], v[166:169], v[206:209], v[24:27]
	v_mfma_f32_16x16x32_bf16 v[12:15], v[150:153], v[214:217], v[12:15]
	v_mfma_f32_16x16x32_bf16 v[8:11], v[166:169], v[214:217], v[8:11]
	v_mfma_f32_16x16x32_bf16 v[60:63], v[162:165], v[194:197], v[60:63]
	v_mfma_f32_16x16x32_bf16 v[56:59], v[170:173], v[194:197], v[56:59]
	v_mfma_f32_16x16x32_bf16 v[44:47], v[162:165], v[202:205], v[44:47]
	v_mfma_f32_16x16x32_bf16 v[40:43], v[170:173], v[202:205], v[40:43]
	v_mfma_f32_16x16x32_bf16 v[28:31], v[162:165], v[210:213], v[28:31]
	v_mfma_f32_16x16x32_bf16 v[24:27], v[170:173], v[210:213], v[24:27]
	v_mfma_f32_16x16x32_bf16 v[12:15], v[162:165], v[218:221], v[12:15]
	v_mfma_f32_16x16x32_bf16 v[8:11], v[170:173], v[218:221], v[8:11]
	v_mfma_f32_16x16x32_bf16 v[52:55], v[174:177], v[190:193], v[52:55]
	v_mfma_f32_16x16x32_bf16 v[48:51], v[182:185], v[190:193], v[48:51]
	v_mfma_f32_16x16x32_bf16 v[36:39], v[174:177], v[198:201], v[36:39]
	v_mfma_f32_16x16x32_bf16 v[32:35], v[182:185], v[198:201], v[32:35]
	v_mfma_f32_16x16x32_bf16 v[20:23], v[174:177], v[206:209], v[20:23]
	v_mfma_f32_16x16x32_bf16 v[16:19], v[182:185], v[206:209], v[16:19]
	v_mfma_f32_16x16x32_bf16 v[4:7], v[174:177], v[214:217], v[4:7]
	v_mfma_f32_16x16x32_bf16 v[0:3], v[182:185], v[214:217], v[0:3]
	v_mfma_f32_16x16x32_bf16 v[52:55], v[178:181], v[194:197], v[52:55]
	v_mfma_f32_16x16x32_bf16 v[48:51], v[186:189], v[194:197], v[48:51]
	v_mfma_f32_16x16x32_bf16 v[36:39], v[178:181], v[202:205], v[36:39]
	v_mfma_f32_16x16x32_bf16 v[32:35], v[186:189], v[202:205], v[32:35]
	v_mfma_f32_16x16x32_bf16 v[20:23], v[178:181], v[210:213], v[20:23]
	v_mfma_f32_16x16x32_bf16 v[16:19], v[186:189], v[210:213], v[16:19]
	v_mfma_f32_16x16x32_bf16 v[4:7], v[178:181], v[218:221], v[4:7]
	v_mfma_f32_16x16x32_bf16 v[0:3], v[186:189], v[218:221], v[0:3]
	s_barrier
	s_add_i32 s67, s67, 2
	s_add_u32 s34, s34, 0x100
	s_addc_u32 s35, s35, 0
	s_add_u32 s65, s65, 0x100
	s_addc_u32 s66, s66, 0
	s_cmp_gt_u32 s67, 61
	s_cbranch_scc0 .LBB0_1741
	s_and_b64 vcc, exec, s[14:15]
	s_cbranch_vccz .LBB0_1744
	s_barrier

; #define PG8_STAGE(bufoff, gbase, voff) do { _Pragma("unroll") for (int _i = 0; _i < 2; ++_i) \
;         __builtin_amdgcn_global_load_lds((const unsigned*)((const char*)(gbase) + (voff)[_i]), (PG8_LAS unsigned*)(lds + (bufoff) + ldsw + _i * 8192), 16, 0, 0); } while (0)
; #define PG8_LDA(dst, b, h) do { _Pragma("unroll") for (int m = 0; m < 4; ++m) _Pragma("unroll") for (int k = 0; k < 2; ++k) dst[m][k] = *(const PG8_LAS bf16x8*)(lds + PG8_SA(b, h) + aoff + m * 2048 + k * 1024); } while (0)
; #define PG8_LDB(dst, b, h) do { _Pragma("unroll") for (int n = 0; n < 2; ++n) _Pragma("unroll") for (int k = 0; k < 2; ++k) dst[n][k] = *(const PG8_LAS bf16x8*)(lds + PG8_SB(b, h) + boff + n * 2048 + k * 1024); } while (0)
; #define PG8_SCHED __builtin_amdgcn_sched_barrier(0)
; template <class Epi, class Sched, bool ALIGN_EPI = false, bool SP2 = false>
; __device__ __forceinline__ void gemm_phase(PG8_LAS unsigned char* lds, const Gemm g, const Sched& S, const Epi& E) {
;     ...
;         const bool has_next = S.next(ui + 1, nxt);
;         const char* nA = has_next ? (const char*)g.A + (size_t)nxt.pm * tstep : cA; const char* nB = has_next ? (const char*)g.Bt + (size_t)nxt.pn * tstep : cB;
;     ...
;             PG8_LDB(B0, 0, 0); PG8_LDB(B1, 0, 1); PG8_SCHED; PG8_LDA(At, 0, 0); PG8_STAGE(PG8_SA(1, 1), a1 + hstepA, voffA);
;     ...
;         for (int a = 0; a < 2; ++a)
; #pragma unroll
;             for (int b = 0; b < 2; ++b)
; #pragma unroll
;                 for (int m = 0; m < 4; ++m)
; #pragma unroll
;                     for (int n = 0; n < 2; ++n) acc[a][b][m][n] = (f32x4){0.f, 0.f, 0.f, 0.f};
.LBB0_2769:
	s_ashr_i32 s31, s30, 31
	s_lshl_b64 s[34:35], s[30:31], 21
	s_add_u32 s34, s3, s34
	s_addc_u32 s35, s29, s35
	s_and_b64 s[40:41], s[4:5], exec
	s_cselect_b32 s31, s35, s47
	s_cselect_b32 s43, s34, s46
	s_ashr_i32 s27, s26, 31
	s_lshl_b64 s[40:41], s[26:27], 21
	s_add_u32 s40, s10, s40
	s_addc_u32 s41, s11, s41
	s_and_b64 s[50:51], s[4:5], exec
	s_cselect_b32 s27, s41, s49
	s_cselect_b32 s66, s40, s48
	s_add_u32 s46, s46, 0x100080
	s_addc_u32 s47, s47, 0
	s_add_u32 s67, s48, 0x100
	v_mov_b32_e32 v0, 0
	s_addc_u32 s68, s49, 0
	s_mov_b32 s69, -2
	s_waitcnt lgkmcnt(0)
	v_mov_b32_e32 v1, v0
	v_mov_b32_e32 v2, v0
	v_mov_b32_e32 v3, v0
	v_mov_b32_e32 v4, v0
	v_mov_b32_e32 v5, v0
	v_mov_b32_e32 v6, v0
	v_mov_b32_e32 v7, v0
	v_mov_b32_e32 v16, v0
	v_mov_b32_e32 v17, v0
	v_mov_b32_e32 v18, v0
	v_mov_b32_e32 v19, v0
	v_mov_b32_e32 v20, v0
	v_mov_b32_e32 v21, v0
	v_mov_b32_e32 v22, v0
	v_mov_b32_e32 v23, v0
	v_mov_b32_e32 v32, v0
	v_mov_b32_e32 v33, v0
	v_mov_b32_e32 v34, v0
	v_mov_b32_e32 v35, v0
	s_waitcnt vmcnt(0)
	v_mov_b32_e32 v36, v0
	v_mov_b32_e32 v37, v0
	v_mov_b32_e32 v38, v0
	v_mov_b32_e32 v39, v0
	v_mov_b32_e32 v48, v0
	v_mov_b32_e32 v49, v0
	v_mov_b32_e32 v50, v0
	v_mov_b32_e32 v51, v0
	v_mov_b32_e32 v52, v0
	v_mov_b32_e32 v53, v0
	v_mov_b32_e32 v54, v0
	v_mov_b32_e32 v55, v0
	v_mov_b32_e32 v8, v0
	v_mov_b32_e32 v9, v0
	v_mov_b32_e32 v10, v0
	v_mov_b32_e32 v11, v0
	v_mov_b32_e32 v12, v0
	v_mov_b32_e32 v13, v0
	v_mov_b32_e32 v14, v0
	v_mov_b32_e32 v15, v0
	v_mov_b32_e32 v24, v0
	v_mov_b32_e32 v25, v0
	v_mov_b32_e32 v26, v0
	v_mov_b32_e32 v27, v0
	v_mov_b32_e32 v28, v0
	v_mov_b32_e32 v29, v0
	v_mov_b32_e32 v30, v0
	v_mov_b32_e32 v31, v0
	v_mov_b32_e32 v40, v0
	v_mov_b32_e32 v41, v0
	v_mov_b32_e32 v42, v0
	v_mov_b32_e32 v43, v0
	v_mov_b32_e32 v44, v0
	v_mov_b32_e32 v45, v0
	v_mov_b32_e32 v46, v0
	v_mov_b32_e32 v47, v0
	v_mov_b32_e32 v56, v0
	v_mov_b32_e32 v57, v0
	v_mov_b32_e32 v58, v0
	v_mov_b32_e32 v59, v0
	v_mov_b32_e32 v60, v0
	v_mov_b32_e32 v61, v0
	v_mov_b32_e32 v62, v0
	v_mov_b32_e32 v63, v0
	v_mov_b32_e32 v64, v0
	v_mov_b32_e32 v65, v0
	v_mov_b32_e32 v66, v0
	v_mov_b32_e32 v67, v0
	v_mov_b32_e32 v68, v0
	v_mov_b32_e32 v69, v0
	v_mov_b32_e32 v70, v0
	v_mov_b32_e32 v71, v0
	v_mov_b32_e32 v80, v0
	v_mov_b32_e32 v81, v0
	v_mov_b32_e32 v82, v0
	v_mov_b32_e32 v83, v0
	v_mov_b32_e32 v84, v0
	v_mov_b32_e32 v85, v0
	v_mov_b32_e32 v86, v0
	v_mov_b32_e32 v87, v0
	v_mov_b32_e32 v96, v0
	v_mov_b32_e32 v97, v0
	v_mov_b32_e32 v98, v0
	v_mov_b32_e32 v99, v0
	v_mov_b32_e32 v100, v0
	v_mov_b32_e32 v101, v0
	v_mov_b32_e32 v102, v0
	v_mov_b32_e32 v103, v0
	v_mov_b32_e32 v112, v0
	v_mov_b32_e32 v113, v0
	v_mov_b32_e32 v114, v0
	v_mov_b32_e32 v115, v0
	v_mov_b32_e32 v116, v0
	v_mov_b32_e32 v117, v0
	v_mov_b32_e32 v118, v0
	v_mov_b32_e32 v119, v0
	v_mov_b32_e32 v72, v0
	v_mov_b32_e32 v73, v0
	v_mov_b32_e32 v74, v0
	v_mov_b32_e32 v75, v0
	v_mov_b32_e32 v76, v0
	v_mov_b32_e32 v77, v0
	v_mov_b32_e32 v78, v0
	v_mov_b32_e32 v79, v0
	v_mov_b32_e32 v88, v0
	v_mov_b32_e32 v89, v0
	v_mov_b32_e32 v90, v0
	v_mov_b32_e32 v91, v0
	v_mov_b32_e32 v92, v0
	v_mov_b32_e32 v93, v0
	v_mov_b32_e32 v94, v0
	v_mov_b32_e32 v95, v0
	v_mov_b32_e32 v104, v0
	v_mov_b32_e32 v105, v0
	v_mov_b32_e32 v106, v0
	v_mov_b32_e32 v107, v0
	v_mov_b32_e32 v108, v0
	v_mov_b32_e32 v109, v0
	v_mov_b32_e32 v110, v0
	v_mov_b32_e32 v111, v0
	v_mov_b32_e32 v120, v0
	v_mov_b32_e32 v121, v0
	v_mov_b32_e32 v122, v0
	v_mov_b32_e32 v123, v0
	v_mov_b32_e32 v124, v0
	v_mov_b32_e32 v125, v0
	v_mov_b32_e32 v126, v0
	v_mov_b32_e32 v127, v0
	v_add_u32_e32 v148, 0x18000, v151
	v_add_u32_e32 v149, 0x1c000, v151
.LBB0_2770:
	ds_read_b128 v[144:147], v153
	ds_read_b128 v[158:161], v153 offset:1024
	ds_read_b128 v[162:165], v153 offset:2048
	ds_read_b128 v[166:169], v153 offset:3072
	ds_read_b128 v[170:173], v154
	ds_read_b128 v[174:177], v154 offset:1024
	ds_read_b128 v[178:181], v154 offset:2048
	ds_read_b128 v[182:185], v154 offset:3072
	s_add_u32 s48, s46, 0xfff00080
	s_addc_u32 s49, s47, -1
	s_cmp_eq_u32 s69, 60
	s_cselect_b32 s51, s31, s49
	s_cselect_b32 s50, s43, s48
	s_cselect_b32 s49, s27, s68
	s_cselect_b32 s48, s66, s67
	s_add_i32 m0, s45, 0xc000
	ds_read_b128 v[186:189], v155
	ds_read_b128 v[190:193], v155 offset:1024
	ds_read_b128 v[194:197], v155 offset:2048
	ds_read_b128 v[198:201], v155 offset:3072
	ds_read_b128 v[202:205], v155 offset:4096
	ds_read_b128 v[206:209], v155 offset:5120
	ds_read_b128 v[210:213], v155 offset:6144
	ds_read_b128 v[214:217], v155 offset:7168
	global_load_lds_dwordx4 v136, s[46:47]
	s_add_i32 m0, s45, 0xe000
	s_nop 0
	global_load_lds_dwordx4 v138, s[46:47]
	s_waitcnt vmcnt(8)
	s_waitcnt lgkmcnt(0)
	s_barrier
; #define PG8_STAGE(bufoff, gbase, voff) do { _Pragma("unroll") for (int _i = 0; _i < 2; ++_i) \
;         __builtin_amdgcn_global_load_lds((const unsigned*)((const char*)(gbase) + (voff)[_i]), (PG8_LAS unsigned*)(lds + (bufoff) + ldsw + _i * 8192), 16, 0, 0); } while (0)
; #define PG8_LDA(dst, b, h) do { _Pragma("unroll") for (int m = 0; m < 4; ++m) _Pragma("unroll") for (int k = 0; k < 2; ++k) dst[m][k] = *(const PG8_LAS bf16x8*)(lds + PG8_SA(b, h) + aoff + m * 2048 + k * 1024); } while (0)
; #define PG8_MMA(ai, bj, At, Bt) do { __builtin_amdgcn_s_setprio(1); _Pragma("unroll") for (int m = 0; m < 4; ++m) _Pragma("unroll") for (int n = 0; n < 2; ++n) _Pragma("unroll") for (int k = 0; k < 2; ++k) \
;         acc[ai][bj][m][n] = __builtin_amdgcn_mfma_f32_16x16x32_bf16(Bt[n][k], At[m][k], acc[ai][bj][m][n], 0, 0, 0); __builtin_amdgcn_s_setprio(0); } while (0)
; #define PG8_WAIT_V(n) asm volatile("s_waitcnt vmcnt(" #n ")" ::: "memory")
; #define PG8_WAIT_L(n) asm volatile("s_waitcnt lgkmcnt(" #n ")" ::: "memory")
; #define PG8_BAR __builtin_amdgcn_s_barrier()
; #define PG8_SCHED __builtin_amdgcn_sched_barrier(0)
; template <class Epi, class Sched, bool ALIGN_EPI = false, bool SP2 = false>
; __device__ __forceinline__ void gemm_phase(PG8_LAS unsigned char* lds, const Gemm g, const Sched& S, const Epi& E) {
;     ...
;             PG8_WAIT_V(8); PG8_WAIT_L(0); PG8_BAR; PG8_MMA(0, 0, At, B0); PG8_MMA(0, 1, At, B1); PG8_BAR; PG8_SCHED;
;             PG8_LDA(At, 0, 1); PG8_STAGE(PG8_SB(0, 0), b2, voffB); PG8_STAGE(PG8_SB(0, 1), b2 + hstep, voffB); PG8_STAGE(PG8_SA(0, 0), a2, voffA);
;             PG8_WAIT_V(8); PG8_WAIT_L(0); PG8_BAR; PG8_MMA(1, 0, At, B0); PG8_MMA(1, 1, At, B1); PG8_BAR; PG8_SCHED;
	v_mfma_f32_16x16x32_bf16 v[124:127], v[144:147], v[186:189], v[124:127]
	v_mfma_f32_16x16x32_bf16 v[120:123], v[162:165], v[186:189], v[120:123]
	v_mfma_f32_16x16x32_bf16 v[108:111], v[144:147], v[194:197], v[108:111]
	v_mfma_f32_16x16x32_bf16 v[104:107], v[162:165], v[194:197], v[104:107]
	v_mfma_f32_16x16x32_bf16 v[92:95], v[144:147], v[202:205], v[92:95]
	v_mfma_f32_16x16x32_bf16 v[88:91], v[162:165], v[202:205], v[88:91]
	v_mfma_f32_16x16x32_bf16 v[76:79], v[144:147], v[210:213], v[76:79]
	v_mfma_f32_16x16x32_bf16 v[72:75], v[162:165], v[210:213], v[72:75]
	v_mfma_f32_16x16x32_bf16 v[124:127], v[158:161], v[190:193], v[124:127]
	v_mfma_f32_16x16x32_bf16 v[120:123], v[166:169], v[190:193], v[120:123]
	v_mfma_f32_16x16x32_bf16 v[108:111], v[158:161], v[198:201], v[108:111]
	v_mfma_f32_16x16x32_bf16 v[104:107], v[166:169], v[198:201], v[104:107]
	v_mfma_f32_16x16x32_bf16 v[92:95], v[158:161], v[206:209], v[92:95]
	v_mfma_f32_16x16x32_bf16 v[88:91], v[166:169], v[206:209], v[88:91]
	v_mfma_f32_16x16x32_bf16 v[76:79], v[158:161], v[214:217], v[76:79]
	v_mfma_f32_16x16x32_bf16 v[72:75], v[166:169], v[214:217], v[72:75]
	v_mfma_f32_16x16x32_bf16 v[116:119], v[170:173], v[186:189], v[116:119]
	v_mfma_f32_16x16x32_bf16 v[112:115], v[178:181], v[186:189], v[112:115]
	v_mfma_f32_16x16x32_bf16 v[100:103], v[170:173], v[194:197], v[100:103]
	v_mfma_f32_16x16x32_bf16 v[96:99], v[178:181], v[194:197], v[96:99]
	v_mfma_f32_16x16x32_bf16 v[84:87], v[170:173], v[202:205], v[84:87]
	v_mfma_f32_16x16x32_bf16 v[80:83], v[178:181], v[202:205], v[80:83]
	v_mfma_f32_16x16x32_bf16 v[68:71], v[170:173], v[210:213], v[68:71]
	v_mfma_f32_16x16x32_bf16 v[64:67], v[178:181], v[210:213], v[64:67]
	v_mfma_f32_16x16x32_bf16 v[116:119], v[174:177], v[190:193], v[116:119]
	v_mfma_f32_16x16x32_bf16 v[112:115], v[182:185], v[190:193], v[112:115]
	v_mfma_f32_16x16x32_bf16 v[100:103], v[174:177], v[198:201], v[100:103]
	v_mfma_f32_16x16x32_bf16 v[96:99], v[182:185], v[198:201], v[96:99]
	v_mfma_f32_16x16x32_bf16 v[84:87], v[174:177], v[206:209], v[84:87]
	v_mfma_f32_16x16x32_bf16 v[80:83], v[182:185], v[206:209], v[80:83]
	v_mfma_f32_16x16x32_bf16 v[68:71], v[174:177], v[214:217], v[68:71]
	v_mfma_f32_16x16x32_bf16 v[64:67], v[182:185], v[214:217], v[64:67]
	s_barrier
	s_add_u32 s98, s48, s16
	s_addc_u32 s99, s49, s17
	s_add_u32 s100, s50, s16
	s_addc_u32 s101, s51, s17
	s_add_i32 s70, s60, s33
	s_mov_b32 m0, s70
	ds_read_b128 v[186:189], v155 offset:16384
	ds_read_b128 v[190:193], v155 offset:17408
	ds_read_b128 v[194:197], v155 offset:18432
	ds_read_b128 v[198:201], v155 offset:19456
	ds_read_b128 v[202:205], v155 offset:20480
	ds_read_b128 v[206:209], v155 offset:21504
	ds_read_b128 v[210:213], v155 offset:22528
	ds_read_b128 v[214:217], v155 offset:23552
	global_load_lds_dwordx4 v130, s[48:49]
	s_add_i32 m0, s70, 0x2000
	s_add_u32 s70, s48, 0x100000
	s_addc_u32 s71, s49, 0
	s_add_i32 s72, s61, s33
	global_load_lds_dwordx4 v134, s[48:49]
	s_mov_b32 m0, s72
	s_nop 0
	global_load_lds_dwordx4 v130, s[70:71]
	s_add_i32 m0, s72, 0x2000
	s_nop 0
	global_load_lds_dwordx4 v134, s[70:71]
	s_mov_b32 m0, s45
	s_nop 0
	global_load_lds_dwordx4 v128, s[50:51]
	s_mov_b32 m0, s52
	s_nop 0
	global_load_lds_dwordx4 v132, s[50:51]
	s_waitcnt vmcnt(8)
	s_waitcnt lgkmcnt(0)
	s_barrier
	v_mfma_f32_16x16x32_bf16 v[60:63], v[144:147], v[186:189], v[60:63]
	v_mfma_f32_16x16x32_bf16 v[56:59], v[162:165], v[186:189], v[56:59]
	v_mfma_f32_16x16x32_bf16 v[44:47], v[144:147], v[194:197], v[44:47]
	v_mfma_f32_16x16x32_bf16 v[40:43], v[162:165], v[194:197], v[40:43]
	v_mfma_f32_16x16x32_bf16 v[28:31], v[144:147], v[202:205], v[28:31]
	v_mfma_f32_16x16x32_bf16 v[24:27], v[162:165], v[202:205], v[24:27]
	v_mfma_f32_16x16x32_bf16 v[12:15], v[144:147], v[210:213], v[12:15]
	v_mfma_f32_16x16x32_bf16 v[8:11], v[162:165], v[210:213], v[8:11]
	v_mfma_f32_16x16x32_bf16 v[60:63], v[158:161], v[190:193], v[60:63]
	v_mfma_f32_16x16x32_bf16 v[56:59], v[166:169], v[190:193], v[56:59]
	v_mfma_f32_16x16x32_bf16 v[44:47], v[158:161], v[198:201], v[44:47]
	v_mfma_f32_16x16x32_bf16 v[40:43], v[166:169], v[198:201], v[40:43]
	v_mfma_f32_16x16x32_bf16 v[28:31], v[158:161], v[206:209], v[28:31]
	v_mfma_f32_16x16x32_bf16 v[24:27], v[166:169], v[206:209], v[24:27]
	v_mfma_f32_16x16x32_bf16 v[12:15], v[158:161], v[214:217], v[12:15]
	v_mfma_f32_16x16x32_bf16 v[8:11], v[166:169], v[214:217], v[8:11]
	v_mfma_f32_16x16x32_bf16 v[52:55], v[170:173], v[186:189], v[52:55]
	v_mfma_f32_16x16x32_bf16 v[48:51], v[178:181], v[186:189], v[48:51]
	v_mfma_f32_16x16x32_bf16 v[36:39], v[170:173], v[194:197], v[36:39]
	v_mfma_f32_16x16x32_bf16 v[32:35], v[178:181], v[194:197], v[32:35]
	v_mfma_f32_16x16x32_bf16 v[20:23], v[170:173], v[202:205], v[20:23]
	v_mfma_f32_16x16x32_bf16 v[16:19], v[178:181], v[202:205], v[16:19]
	v_mfma_f32_16x16x32_bf16 v[4:7], v[170:173], v[210:213], v[4:7]
	v_mfma_f32_16x16x32_bf16 v[0:3], v[178:181], v[210:213], v[0:3]
	v_mfma_f32_16x16x32_bf16 v[52:55], v[174:177], v[190:193], v[52:55]
	v_mfma_f32_16x16x32_bf16 v[48:51], v[182:185], v[190:193], v[48:51]
	v_mfma_f32_16x16x32_bf16 v[36:39], v[174:177], v[198:201], v[36:39]
	v_mfma_f32_16x16x32_bf16 v[32:35], v[182:185], v[198:201], v[32:35]
	v_mfma_f32_16x16x32_bf16 v[20:23], v[174:177], v[206:209], v[20:23]
	v_mfma_f32_16x16x32_bf16 v[16:19], v[182:185], v[206:209], v[16:19]
	v_mfma_f32_16x16x32_bf16 v[4:7], v[174:177], v[214:217], v[4:7]
	v_mfma_f32_16x16x32_bf16 v[0:3], v[182:185], v[214:217], v[0:3]
	s_barrier
; #define PG8_STAGE(bufoff, gbase, voff) do { _Pragma("unroll") for (int _i = 0; _i < 2; ++_i) \
;         __builtin_amdgcn_global_load_lds((const unsigned*)((const char*)(gbase) + (voff)[_i]), (PG8_LAS unsigned*)(lds + (bufoff) + ldsw + _i * 8192), 16, 0, 0); } while (0)
; #define PG8_LDA(dst, b, h) do { _Pragma("unroll") for (int m = 0; m < 4; ++m) _Pragma("unroll") for (int k = 0; k < 2; ++k) dst[m][k] = *(const PG8_LAS bf16x8*)(lds + PG8_SA(b, h) + aoff + m * 2048 + k * 1024); } while (0)
; #define PG8_LDB(dst, b, h) do { _Pragma("unroll") for (int n = 0; n < 2; ++n) _Pragma("unroll") for (int k = 0; k < 2; ++k) dst[n][k] = *(const PG8_LAS bf16x8*)(lds + PG8_SB(b, h) + boff + n * 2048 + k * 1024); } while (0)
; #define PG8_MMA(ai, bj, At, Bt) do { __builtin_amdgcn_s_setprio(1); _Pragma("unroll") for (int m = 0; m < 4; ++m) _Pragma("unroll") for (int n = 0; n < 2; ++n) _Pragma("unroll") for (int k = 0; k < 2; ++k) \
;         acc[ai][bj][m][n] = __builtin_amdgcn_mfma_f32_16x16x32_bf16(Bt[n][k], At[m][k], acc[ai][bj][m][n], 0, 0, 0); __builtin_amdgcn_s_setprio(0); } while (0)
; #define PG8_WAIT_V(n) asm volatile("s_waitcnt vmcnt(" #n ")" ::: "memory")
; #define PG8_WAIT_L(n) asm volatile("s_waitcnt lgkmcnt(" #n ")" ::: "memory")
; #define PG8_BAR __builtin_amdgcn_s_barrier()
; #define PG8_SCHED __builtin_amdgcn_sched_barrier(0)
; template <class Epi, class Sched, bool ALIGN_EPI = false, bool SP2 = false>
; __device__ __forceinline__ void gemm_phase(PG8_LAS unsigned char* lds, const Gemm g, const Sched& S, const Epi& E) {
;     ...
;             PG8_LDB(B0, 1, 0); PG8_LDB(B1, 1, 1); PG8_SCHED; PG8_LDA(At, 1, 0); PG8_STAGE(PG8_SA(0, 1), a2 + hstepA, voffA);
;             PG8_WAIT_V(8); PG8_WAIT_L(0); PG8_BAR; PG8_MMA(0, 0, At, B0); PG8_MMA(0, 1, At, B1); PG8_BAR; PG8_SCHED;
;             PG8_LDA(At, 1, 1); PG8_STAGE(PG8_SB(1, 0), b3, voffB); PG8_STAGE(PG8_SB(1, 1), b3 + hstep, voffB); PG8_STAGE(PG8_SA(1, 0), a3, voffA);
;             PG8_WAIT_V(8); PG8_WAIT_L(0); PG8_BAR; PG8_MMA(1, 0, At, B0); PG8_MMA(1, 1, At, B1); PG8_BAR; PG8_SCHED;
;     ...
;         if constexpr (ALIGN_EPI) { if (wr == 0) PG8_BAR; }
	s_add_i32 s70, 0, 0x18000
	s_add_i32 s71, 0, 0x1c000
	ds_read_b128 v[144:147], v148
	ds_read_b128 v[158:161], v148 offset:1024
	ds_read_b128 v[162:165], v148 offset:2048
	ds_read_b128 v[166:169], v148 offset:3072
	ds_read_b128 v[170:173], v149
	ds_read_b128 v[174:177], v149 offset:1024
	ds_read_b128 v[178:181], v149 offset:2048
	ds_read_b128 v[182:185], v149 offset:3072
	s_add_u32 s50, s50, 0x100000
	s_addc_u32 s51, s51, 0
	s_mov_b32 m0, s53
	ds_read_b128 v[186:189], v155 offset:32768
	ds_read_b128 v[190:193], v155 offset:33792
	ds_read_b128 v[194:197], v155 offset:34816
	ds_read_b128 v[198:201], v155 offset:35840
	ds_read_b128 v[202:205], v155 offset:36864
	ds_read_b128 v[206:209], v155 offset:37888
	ds_read_b128 v[210:213], v155 offset:38912
	ds_read_b128 v[214:217], v155 offset:39936
	global_load_lds_dwordx4 v128, s[50:51]
	s_mov_b32 m0, s54
	s_nop 0
	global_load_lds_dwordx4 v132, s[50:51]
	s_waitcnt vmcnt(8)
	s_waitcnt lgkmcnt(0)
	s_barrier
	v_mfma_f32_16x16x32_bf16 v[124:127], v[144:147], v[186:189], v[124:127]
	v_mfma_f32_16x16x32_bf16 v[120:123], v[162:165], v[186:189], v[120:123]
	v_mfma_f32_16x16x32_bf16 v[108:111], v[144:147], v[194:197], v[108:111]
	v_mfma_f32_16x16x32_bf16 v[104:107], v[162:165], v[194:197], v[104:107]
	v_mfma_f32_16x16x32_bf16 v[92:95], v[144:147], v[202:205], v[92:95]
	v_mfma_f32_16x16x32_bf16 v[88:91], v[162:165], v[202:205], v[88:91]
	v_mfma_f32_16x16x32_bf16 v[76:79], v[144:147], v[210:213], v[76:79]
	v_mfma_f32_16x16x32_bf16 v[72:75], v[162:165], v[210:213], v[72:75]
	v_mfma_f32_16x16x32_bf16 v[124:127], v[158:161], v[190:193], v[124:127]
	v_mfma_f32_16x16x32_bf16 v[120:123], v[166:169], v[190:193], v[120:123]
	v_mfma_f32_16x16x32_bf16 v[108:111], v[158:161], v[198:201], v[108:111]
	v_mfma_f32_16x16x32_bf16 v[104:107], v[166:169], v[198:201], v[104:107]
	v_mfma_f32_16x16x32_bf16 v[92:95], v[158:161], v[206:209], v[92:95]
	v_mfma_f32_16x16x32_bf16 v[88:91], v[166:169], v[206:209], v[88:91]
	v_mfma_f32_16x16x32_bf16 v[76:79], v[158:161], v[214:217], v[76:79]
	v_mfma_f32_16x16x32_bf16 v[72:75], v[166:169], v[214:217], v[72:75]
	v_mfma_f32_16x16x32_bf16 v[116:119], v[170:173], v[186:189], v[116:119]
	v_mfma_f32_16x16x32_bf16 v[112:115], v[178:181], v[186:189], v[112:115]
	v_mfma_f32_16x16x32_bf16 v[100:103], v[170:173], v[194:197], v[100:103]
	v_mfma_f32_16x16x32_bf16 v[96:99], v[178:181], v[194:197], v[96:99]
	v_mfma_f32_16x16x32_bf16 v[84:87], v[170:173], v[202:205], v[84:87]
	v_mfma_f32_16x16x32_bf16 v[80:83], v[178:181], v[202:205], v[80:83]
	v_mfma_f32_16x16x32_bf16 v[68:71], v[170:173], v[210:213], v[68:71]
	v_mfma_f32_16x16x32_bf16 v[64:67], v[178:181], v[210:213], v[64:67]
	v_mfma_f32_16x16x32_bf16 v[116:119], v[174:177], v[190:193], v[116:119]
	v_mfma_f32_16x16x32_bf16 v[112:115], v[182:185], v[190:193], v[112:115]
	v_mfma_f32_16x16x32_bf16 v[100:103], v[174:177], v[198:201], v[100:103]
	v_mfma_f32_16x16x32_bf16 v[96:99], v[182:185], v[198:201], v[96:99]
	v_mfma_f32_16x16x32_bf16 v[84:87], v[174:177], v[206:209], v[84:87]
	v_mfma_f32_16x16x32_bf16 v[80:83], v[182:185], v[206:209], v[80:83]
	v_mfma_f32_16x16x32_bf16 v[68:71], v[174:177], v[214:217], v[68:71]
	v_mfma_f32_16x16x32_bf16 v[64:67], v[182:185], v[214:217], v[64:67]
	s_barrier
	s_add_i32 s50, s70, s33
	s_mov_b32 m0, s50
	ds_read_b128 v[186:189], v155 offset:49152
	ds_read_b128 v[190:193], v155 offset:50176
	ds_read_b128 v[194:197], v155 offset:51200
	ds_read_b128 v[198:201], v155 offset:52224
	ds_read_b128 v[202:205], v155 offset:53248
	ds_read_b128 v[206:209], v155 offset:54272
	ds_read_b128 v[210:213], v155 offset:55296
	ds_read_b128 v[214:217], v155 offset:56320
	global_load_lds_dwordx4 v130, s[98:99]
	s_add_i32 m0, s50, 0x2000
	s_add_u32 s48, s48, 0x100080
	s_addc_u32 s49, s49, 0
	s_add_i32 s50, s71, s33
	global_load_lds_dwordx4 v134, s[98:99]
	s_mov_b32 m0, s50
	s_nop 0
	global_load_lds_dwordx4 v130, s[48:49]
	s_add_i32 m0, s50, 0x2000
	s_nop 0
	global_load_lds_dwordx4 v134, s[48:49]
	s_mov_b32 m0, s56
	s_nop 0
	global_load_lds_dwordx4 v128, s[100:101]
	s_mov_b32 m0, s57
	s_nop 0
	global_load_lds_dwordx4 v132, s[100:101]
	s_waitcnt vmcnt(8)
	s_waitcnt lgkmcnt(0)
	s_barrier
	v_mfma_f32_16x16x32_bf16 v[60:63], v[144:147], v[186:189], v[60:63]
	v_mfma_f32_16x16x32_bf16 v[56:59], v[162:165], v[186:189], v[56:59]
	v_mfma_f32_16x16x32_bf16 v[44:47], v[144:147], v[194:197], v[44:47]
	v_mfma_f32_16x16x32_bf16 v[40:43], v[162:165], v[194:197], v[40:43]
	v_mfma_f32_16x16x32_bf16 v[28:31], v[144:147], v[202:205], v[28:31]
	v_mfma_f32_16x16x32_bf16 v[24:27], v[162:165], v[202:205], v[24:27]
	v_mfma_f32_16x16x32_bf16 v[12:15], v[144:147], v[210:213], v[12:15]
	v_mfma_f32_16x16x32_bf16 v[8:11], v[162:165], v[210:213], v[8:11]
	v_mfma_f32_16x16x32_bf16 v[60:63], v[158:161], v[190:193], v[60:63]
	v_mfma_f32_16x16x32_bf16 v[56:59], v[166:169], v[190:193], v[56:59]
	v_mfma_f32_16x16x32_bf16 v[44:47], v[158:161], v[198:201], v[44:47]
	v_mfma_f32_16x16x32_bf16 v[40:43], v[166:169], v[198:201], v[40:43]
	v_mfma_f32_16x16x32_bf16 v[28:31], v[158:161], v[206:209], v[28:31]
	v_mfma_f32_16x16x32_bf16 v[24:27], v[166:169], v[206:209], v[24:27]
	v_mfma_f32_16x16x32_bf16 v[12:15], v[158:161], v[214:217], v[12:15]
	v_mfma_f32_16x16x32_bf16 v[8:11], v[166:169], v[214:217], v[8:11]
	v_mfma_f32_16x16x32_bf16 v[52:55], v[170:173], v[186:189], v[52:55]
	v_mfma_f32_16x16x32_bf16 v[48:51], v[178:181], v[186:189], v[48:51]
	v_mfma_f32_16x16x32_bf16 v[36:39], v[170:173], v[194:197], v[36:39]
	v_mfma_f32_16x16x32_bf16 v[32:35], v[178:181], v[194:197], v[32:35]
	v_mfma_f32_16x16x32_bf16 v[20:23], v[170:173], v[202:205], v[20:23]
	v_mfma_f32_16x16x32_bf16 v[16:19], v[178:181], v[202:205], v[16:19]
	v_mfma_f32_16x16x32_bf16 v[4:7], v[170:173], v[210:213], v[4:7]
	v_mfma_f32_16x16x32_bf16 v[0:3], v[178:181], v[210:213], v[0:3]
	v_mfma_f32_16x16x32_bf16 v[52:55], v[174:177], v[190:193], v[52:55]
	v_mfma_f32_16x16x32_bf16 v[48:51], v[182:185], v[190:193], v[48:51]
	v_mfma_f32_16x16x32_bf16 v[36:39], v[174:177], v[198:201], v[36:39]
	v_mfma_f32_16x16x32_bf16 v[32:35], v[182:185], v[198:201], v[32:35]
	v_mfma_f32_16x16x32_bf16 v[20:23], v[174:177], v[206:209], v[20:23]
	v_mfma_f32_16x16x32_bf16 v[16:19], v[182:185], v[206:209], v[16:19]
	v_mfma_f32_16x16x32_bf16 v[4:7], v[174:177], v[214:217], v[4:7]
	v_mfma_f32_16x16x32_bf16 v[0:3], v[182:185], v[214:217], v[0:3]
	s_barrier
	s_add_i32 s69, s69, 2
	s_add_u32 s46, s46, 0x100
	s_addc_u32 s47, s47, 0
	s_add_u32 s67, s67, 0x100
	s_addc_u32 s68, s68, 0
	s_cmp_gt_u32 s69, 61
	s_cbranch_scc0 .LBB0_2770
	s_and_b64 vcc, exec, s[18:19]
	s_cbranch_vccz .LBB0_2773
	s_barrier

; #define PG8_STAGE(bufoff, gbase, voff) do { _Pragma("unroll") for (int _i = 0; _i < 2; ++_i) \
;         __builtin_amdgcn_global_load_lds((const unsigned*)((const char*)(gbase) + (voff)[_i]), (PG8_LAS unsigned*)(lds + (bufoff) + ldsw + _i * 8192), 16, 0, 0); } while (0)
; #define PG8_LDA(dst, b, h) do { _Pragma("unroll") for (int m = 0; m < 4; ++m) _Pragma("unroll") for (int k = 0; k < 2; ++k) dst[m][k] = *(const PG8_LAS bf16x8*)(lds + PG8_SA(b, h) + aoff + m * 2048 + k * 1024); } while (0)
; #define PG8_LDB(dst, b, h) do { _Pragma("unroll") for (int n = 0; n < 2; ++n) _Pragma("unroll") for (int k = 0; k < 2; ++k) dst[n][k] = *(const PG8_LAS bf16x8*)(lds + PG8_SB(b, h) + boff + n * 2048 + k * 1024); } while (0)
; #define PG8_SCHED __builtin_amdgcn_sched_barrier(0)
; template <class Epi, class Sched, bool ALIGN_EPI = false, bool SP2 = false>
; __device__ __forceinline__ void gemm_phase(PG8_LAS unsigned char* lds, const Gemm g, const Sched& S, const Epi& E) {
;     ...
;         const bool has_next = S.next(ui + 1, nxt);
;         const char* nA = has_next ? (const char*)g.A + (size_t)nxt.pm * tstep : cA; const char* nB = has_next ? (const char*)g.Bt + (size_t)nxt.pn * tstep : cB;
;     ...
;             PG8_LDB(B0, 0, 0); PG8_LDB(B1, 0, 1); PG8_SCHED; PG8_LDA(At, 0, 0); PG8_STAGE(PG8_SA(1, 1), a1 + hstepA, voffA);
;     ...
;         for (int a = 0; a < 2; ++a)
; #pragma unroll
;             for (int b = 0; b < 2; ++b)
; #pragma unroll
;                 for (int m = 0; m < 4; ++m)
; #pragma unroll
;                     for (int n = 0; n < 2; ++n) acc[a][b][m][n] = (f32x4){0.f, 0.f, 0.f, 0.f};
.LBB0_2881:
	s_ashr_i32 s51, s50, 31
	s_lshl_b64 s[52:53], s[50:51], 21
	s_add_u32 s52, s96, s52
	s_addc_u32 s53, s97, s53
	s_and_b64 s[54:55], s[4:5], exec
	s_cselect_b32 s7, s53, s9
	s_cselect_b32 s51, s52, s8
	s_ashr_i32 s49, s48, 31
	s_lshl_b64 s[54:55], s[48:49], 21
	s_add_u32 s54, s29, s54
	s_addc_u32 s55, s33, s55
	s_and_b64 s[58:59], s[4:5], exec
	s_cselect_b32 s49, s55, s11
	s_cselect_b32 s85, s54, s10
	s_add_u32 s86, s10, 0x100
	v_mov_b32_e32 v0, 0
	s_addc_u32 s87, s11, 0
	s_mov_b32 s88, -2
	v_mov_b32_e32 v1, v0
	v_mov_b32_e32 v2, v0
	v_mov_b32_e32 v3, v0
	v_mov_b32_e32 v4, v0
	v_mov_b32_e32 v5, v0
	v_mov_b32_e32 v6, v0
	v_mov_b32_e32 v7, v0
	v_mov_b32_e32 v16, v0
	v_mov_b32_e32 v17, v0
	v_mov_b32_e32 v18, v0
	v_mov_b32_e32 v19, v0
	v_mov_b32_e32 v20, v0
	v_mov_b32_e32 v21, v0
	v_mov_b32_e32 v22, v0
	v_mov_b32_e32 v23, v0
	v_mov_b32_e32 v32, v0
	v_mov_b32_e32 v33, v0
	v_mov_b32_e32 v34, v0
	v_mov_b32_e32 v35, v0
	s_waitcnt vmcnt(0)
	v_mov_b32_e32 v36, v0
	v_mov_b32_e32 v37, v0
	v_mov_b32_e32 v38, v0
	v_mov_b32_e32 v39, v0
	v_mov_b32_e32 v48, v0
	v_mov_b32_e32 v49, v0
	v_mov_b32_e32 v50, v0
	v_mov_b32_e32 v51, v0
	v_mov_b32_e32 v52, v0
	v_mov_b32_e32 v53, v0
	v_mov_b32_e32 v54, v0
	v_mov_b32_e32 v55, v0
	v_mov_b32_e32 v8, v0
	v_mov_b32_e32 v9, v0
	v_mov_b32_e32 v10, v0
	v_mov_b32_e32 v11, v0
	v_mov_b32_e32 v12, v0
	v_mov_b32_e32 v13, v0
	v_mov_b32_e32 v14, v0
	v_mov_b32_e32 v15, v0
	v_mov_b32_e32 v24, v0
	v_mov_b32_e32 v25, v0
	v_mov_b32_e32 v26, v0
	v_mov_b32_e32 v27, v0
	v_mov_b32_e32 v28, v0
	v_mov_b32_e32 v29, v0
	v_mov_b32_e32 v30, v0
	v_mov_b32_e32 v31, v0
	v_mov_b32_e32 v40, v0
	v_mov_b32_e32 v41, v0
	v_mov_b32_e32 v42, v0
	v_mov_b32_e32 v43, v0
	v_mov_b32_e32 v44, v0
	v_mov_b32_e32 v45, v0
	v_mov_b32_e32 v46, v0
	v_mov_b32_e32 v47, v0
	v_mov_b32_e32 v56, v0
	v_mov_b32_e32 v57, v0
	v_mov_b32_e32 v58, v0
	v_mov_b32_e32 v59, v0
	v_mov_b32_e32 v60, v0
	v_mov_b32_e32 v61, v0
	v_mov_b32_e32 v62, v0
	v_mov_b32_e32 v63, v0
	v_mov_b32_e32 v64, v0
	v_mov_b32_e32 v65, v0
	v_mov_b32_e32 v66, v0
	v_mov_b32_e32 v67, v0
	v_mov_b32_e32 v68, v0
	v_mov_b32_e32 v69, v0
	v_mov_b32_e32 v70, v0
	v_mov_b32_e32 v71, v0
	v_mov_b32_e32 v80, v0
	v_mov_b32_e32 v81, v0
	v_mov_b32_e32 v82, v0
	v_mov_b32_e32 v83, v0
	v_mov_b32_e32 v84, v0
	v_mov_b32_e32 v85, v0
	v_mov_b32_e32 v86, v0
	v_mov_b32_e32 v87, v0
	v_mov_b32_e32 v96, v0
	v_mov_b32_e32 v97, v0
	v_mov_b32_e32 v98, v0
	v_mov_b32_e32 v99, v0
	v_mov_b32_e32 v100, v0
	v_mov_b32_e32 v101, v0
	v_mov_b32_e32 v102, v0
	v_mov_b32_e32 v103, v0
	v_mov_b32_e32 v112, v0
	v_mov_b32_e32 v113, v0
	v_mov_b32_e32 v114, v0
	v_mov_b32_e32 v115, v0
	v_mov_b32_e32 v116, v0
	v_mov_b32_e32 v117, v0
	v_mov_b32_e32 v118, v0
	v_mov_b32_e32 v119, v0
	v_mov_b32_e32 v72, v0
	v_mov_b32_e32 v73, v0
	v_mov_b32_e32 v74, v0
	v_mov_b32_e32 v75, v0
	v_mov_b32_e32 v76, v0
	v_mov_b32_e32 v77, v0
	v_mov_b32_e32 v78, v0
	v_mov_b32_e32 v79, v0
	v_mov_b32_e32 v88, v0
	v_mov_b32_e32 v89, v0
	v_mov_b32_e32 v90, v0
	v_mov_b32_e32 v91, v0
	v_mov_b32_e32 v92, v0
	v_mov_b32_e32 v93, v0
	v_mov_b32_e32 v94, v0
	v_mov_b32_e32 v95, v0
	v_mov_b32_e32 v104, v0
	v_mov_b32_e32 v105, v0
	v_mov_b32_e32 v106, v0
	v_mov_b32_e32 v107, v0
	v_mov_b32_e32 v108, v0
	v_mov_b32_e32 v109, v0
	v_mov_b32_e32 v110, v0
	v_mov_b32_e32 v111, v0
	v_mov_b32_e32 v120, v0
	v_mov_b32_e32 v121, v0
	v_mov_b32_e32 v122, v0
	v_mov_b32_e32 v123, v0
	v_mov_b32_e32 v124, v0
	v_mov_b32_e32 v125, v0
	v_mov_b32_e32 v126, v0
	v_mov_b32_e32 v127, v0
	v_add_u32_e32 v214, 0x18000, v234
	v_add_u32_e32 v215, 0x1c000, v234
.LBB0_2882:
	ds_read_b128 v[128:131], v236
	ds_read_b128 v[132:135], v236 offset:1024
	ds_read_b128 v[136:139], v236 offset:2048
	ds_read_b128 v[140:143], v236 offset:3072
	ds_read_b128 v[144:147], v237
	ds_read_b128 v[148:151], v237 offset:1024
	ds_read_b128 v[152:155], v237 offset:2048
	ds_read_b128 v[156:159], v237 offset:3072
	s_add_u32 s10, s8, 0x100
	s_addc_u32 s11, s9, 0
	s_cmp_eq_u32 s88, 60
	s_cselect_b32 s61, s7, s11
	s_cselect_b32 s60, s51, s10
	s_cselect_b32 s59, s49, s87
	s_cselect_b32 s58, s85, s86
	v_lshl_add_u64 v[164:165], s[8:9], 0, v[178:179]
	s_add_i32 m0, s57, 0xc000
	ds_read_b128 v[160:163], v238
	ds_read_b128 v[186:189], v238 offset:1024
	ds_read_b128 v[190:193], v238 offset:2048
	ds_read_b128 v[194:197], v238 offset:3072
	ds_read_b128 v[198:201], v238 offset:4096
	ds_read_b128 v[202:205], v238 offset:5120
	ds_read_b128 v[206:209], v238 offset:6144
	ds_read_b128 v[210:213], v238 offset:7168
	global_load_lds_dwordx4 v[164:165], off
	v_lshl_add_u64 v[164:165], s[8:9], 0, v[180:181]
	s_add_i32 m0, s57, 0xe000
	s_nop 0
	global_load_lds_dwordx4 v[164:165], off
	s_waitcnt vmcnt(8)
	s_waitcnt lgkmcnt(0)
	s_barrier
; #define PG8_STAGE(bufoff, gbase, voff) do { _Pragma("unroll") for (int _i = 0; _i < 2; ++_i) \
;         __builtin_amdgcn_global_load_lds((const unsigned*)((const char*)(gbase) + (voff)[_i]), (PG8_LAS unsigned*)(lds + (bufoff) + ldsw + _i * 8192), 16, 0, 0); } while (0)
; #define PG8_LDA(dst, b, h) do { _Pragma("unroll") for (int m = 0; m < 4; ++m) _Pragma("unroll") for (int k = 0; k < 2; ++k) dst[m][k] = *(const PG8_LAS bf16x8*)(lds + PG8_SA(b, h) + aoff + m * 2048 + k * 1024); } while (0)
; #define PG8_MMA(ai, bj, At, Bt) do { __builtin_amdgcn_s_setprio(1); _Pragma("unroll") for (int m = 0; m < 4; ++m) _Pragma("unroll") for (int n = 0; n < 2; ++n) _Pragma("unroll") for (int k = 0; k < 2; ++k) \
;         acc[ai][bj][m][n] = __builtin_amdgcn_mfma_f32_16x16x32_bf16(Bt[n][k], At[m][k], acc[ai][bj][m][n], 0, 0, 0); __builtin_amdgcn_s_setprio(0); } while (0)
; #define PG8_WAIT_V(n) asm volatile("s_waitcnt vmcnt(" #n ")" ::: "memory")
; #define PG8_WAIT_L(n) asm volatile("s_waitcnt lgkmcnt(" #n ")" ::: "memory")
; #define PG8_BAR __builtin_amdgcn_s_barrier()
; #define PG8_SCHED __builtin_amdgcn_sched_barrier(0)
; template <class Epi, class Sched, bool ALIGN_EPI = false, bool SP2 = false>
; __device__ __forceinline__ void gemm_phase(PG8_LAS unsigned char* lds, const Gemm g, const Sched& S, const Epi& E) {
;     ...
;             PG8_WAIT_V(8); PG8_WAIT_L(0); PG8_BAR; PG8_MMA(0, 0, At, B0); PG8_MMA(0, 1, At, B1); PG8_BAR; PG8_SCHED;
;             PG8_LDA(At, 0, 1); PG8_STAGE(PG8_SB(0, 0), b2, voffB); PG8_STAGE(PG8_SB(0, 1), b2 + hstep, voffB); PG8_STAGE(PG8_SA(0, 0), a2, voffA);
;             PG8_WAIT_V(8); PG8_WAIT_L(0); PG8_BAR; PG8_MMA(1, 0, At, B0); PG8_MMA(1, 1, At, B1); PG8_BAR; PG8_SCHED;
	v_mfma_f32_16x16x32_bf16 v[124:127], v[128:131], v[160:163], v[124:127]
	v_mfma_f32_16x16x32_bf16 v[120:123], v[136:139], v[160:163], v[120:123]
	v_mfma_f32_16x16x32_bf16 v[108:111], v[128:131], v[190:193], v[108:111]
	v_mfma_f32_16x16x32_bf16 v[104:107], v[136:139], v[190:193], v[104:107]
	v_mfma_f32_16x16x32_bf16 v[92:95], v[128:131], v[198:201], v[92:95]
	v_mfma_f32_16x16x32_bf16 v[88:91], v[136:139], v[198:201], v[88:91]
	v_mfma_f32_16x16x32_bf16 v[76:79], v[128:131], v[206:209], v[76:79]
	v_mfma_f32_16x16x32_bf16 v[72:75], v[136:139], v[206:209], v[72:75]
	v_mfma_f32_16x16x32_bf16 v[124:127], v[132:135], v[186:189], v[124:127]
	v_mfma_f32_16x16x32_bf16 v[120:123], v[140:143], v[186:189], v[120:123]
	v_mfma_f32_16x16x32_bf16 v[108:111], v[132:135], v[194:197], v[108:111]
	v_mfma_f32_16x16x32_bf16 v[104:107], v[140:143], v[194:197], v[104:107]
	v_mfma_f32_16x16x32_bf16 v[92:95], v[132:135], v[202:205], v[92:95]
	v_mfma_f32_16x16x32_bf16 v[88:91], v[140:143], v[202:205], v[88:91]
	v_mfma_f32_16x16x32_bf16 v[76:79], v[132:135], v[210:213], v[76:79]
	v_mfma_f32_16x16x32_bf16 v[72:75], v[140:143], v[210:213], v[72:75]
	v_mfma_f32_16x16x32_bf16 v[116:119], v[144:147], v[160:163], v[116:119]
	v_mfma_f32_16x16x32_bf16 v[112:115], v[152:155], v[160:163], v[112:115]
	v_mfma_f32_16x16x32_bf16 v[100:103], v[144:147], v[190:193], v[100:103]
	v_mfma_f32_16x16x32_bf16 v[96:99], v[152:155], v[190:193], v[96:99]
	v_mfma_f32_16x16x32_bf16 v[84:87], v[144:147], v[198:201], v[84:87]
	v_mfma_f32_16x16x32_bf16 v[80:83], v[152:155], v[198:201], v[80:83]
	v_mfma_f32_16x16x32_bf16 v[68:71], v[144:147], v[206:209], v[68:71]
	v_mfma_f32_16x16x32_bf16 v[64:67], v[152:155], v[206:209], v[64:67]
	v_mfma_f32_16x16x32_bf16 v[116:119], v[148:151], v[186:189], v[116:119]
	v_mfma_f32_16x16x32_bf16 v[112:115], v[156:159], v[186:189], v[112:115]
	v_mfma_f32_16x16x32_bf16 v[100:103], v[148:151], v[194:197], v[100:103]
	v_mfma_f32_16x16x32_bf16 v[96:99], v[156:159], v[194:197], v[96:99]
	v_mfma_f32_16x16x32_bf16 v[84:87], v[148:151], v[202:205], v[84:87]
	v_mfma_f32_16x16x32_bf16 v[80:83], v[156:159], v[202:205], v[80:83]
	v_mfma_f32_16x16x32_bf16 v[68:71], v[148:151], v[210:213], v[68:71]
	v_mfma_f32_16x16x32_bf16 v[64:67], v[156:159], v[210:213], v[64:67]
	s_barrier
	s_add_u32 s98, s58, s16
	s_addc_u32 s99, s59, s17
	s_add_u32 s100, s60, s16
	s_addc_u32 s101, s61, s17
	s_add_i32 s8, s72, s63
	s_mov_b32 m0, s8
	ds_read_b128 v[160:163], v238 offset:16384
	ds_read_b128 v[186:189], v238 offset:17408
	ds_read_b128 v[190:193], v238 offset:18432
	ds_read_b128 v[194:197], v238 offset:19456
	ds_read_b128 v[198:201], v238 offset:20480
	ds_read_b128 v[202:205], v238 offset:21504
	ds_read_b128 v[206:209], v238 offset:22528
	ds_read_b128 v[210:213], v238 offset:23552
	global_load_lds_dwordx4 v168, s[58:59]
	s_add_i32 m0, s8, 0x2000
	s_add_u32 s8, s58, 0x100000
	s_addc_u32 s9, s59, 0
	s_add_i32 s89, s73, s63
	global_load_lds_dwordx4 v172, s[58:59]
	s_mov_b32 m0, s89
	s_nop 0
	global_load_lds_dwordx4 v168, s[8:9]
	s_add_i32 m0, s89, 0x2000
	s_nop 0
	global_load_lds_dwordx4 v172, s[8:9]
	s_mov_b32 m0, s57
	s_nop 0
	global_load_lds_dwordx4 v166, s[60:61]
	s_mov_b32 m0, s64
	s_nop 0
	global_load_lds_dwordx4 v170, s[60:61]
	s_waitcnt vmcnt(8)
	s_waitcnt lgkmcnt(0)
	s_barrier
	v_mfma_f32_16x16x32_bf16 v[60:63], v[128:131], v[160:163], v[60:63]
	v_mfma_f32_16x16x32_bf16 v[56:59], v[136:139], v[160:163], v[56:59]
	v_mfma_f32_16x16x32_bf16 v[44:47], v[128:131], v[190:193], v[44:47]
	v_mfma_f32_16x16x32_bf16 v[40:43], v[136:139], v[190:193], v[40:43]
	v_mfma_f32_16x16x32_bf16 v[28:31], v[128:131], v[198:201], v[28:31]
	v_mfma_f32_16x16x32_bf16 v[24:27], v[136:139], v[198:201], v[24:27]
	v_mfma_f32_16x16x32_bf16 v[12:15], v[128:131], v[206:209], v[12:15]
	v_mfma_f32_16x16x32_bf16 v[8:11], v[136:139], v[206:209], v[8:11]
	v_mfma_f32_16x16x32_bf16 v[60:63], v[132:135], v[186:189], v[60:63]
	v_mfma_f32_16x16x32_bf16 v[56:59], v[140:143], v[186:189], v[56:59]
	v_mfma_f32_16x16x32_bf16 v[44:47], v[132:135], v[194:197], v[44:47]
	v_mfma_f32_16x16x32_bf16 v[40:43], v[140:143], v[194:197], v[40:43]
	v_mfma_f32_16x16x32_bf16 v[28:31], v[132:135], v[202:205], v[28:31]
	v_mfma_f32_16x16x32_bf16 v[24:27], v[140:143], v[202:205], v[24:27]
	v_mfma_f32_16x16x32_bf16 v[12:15], v[132:135], v[210:213], v[12:15]
	v_mfma_f32_16x16x32_bf16 v[8:11], v[140:143], v[210:213], v[8:11]
	v_mfma_f32_16x16x32_bf16 v[52:55], v[144:147], v[160:163], v[52:55]
	v_mfma_f32_16x16x32_bf16 v[48:51], v[152:155], v[160:163], v[48:51]
	v_mfma_f32_16x16x32_bf16 v[36:39], v[144:147], v[190:193], v[36:39]
	v_mfma_f32_16x16x32_bf16 v[32:35], v[152:155], v[190:193], v[32:35]
	v_mfma_f32_16x16x32_bf16 v[20:23], v[144:147], v[198:201], v[20:23]
	v_mfma_f32_16x16x32_bf16 v[16:19], v[152:155], v[198:201], v[16:19]
	v_mfma_f32_16x16x32_bf16 v[4:7], v[144:147], v[206:209], v[4:7]
	v_mfma_f32_16x16x32_bf16 v[0:3], v[152:155], v[206:209], v[0:3]
	v_mfma_f32_16x16x32_bf16 v[52:55], v[148:151], v[186:189], v[52:55]
	v_mfma_f32_16x16x32_bf16 v[48:51], v[156:159], v[186:189], v[48:51]
	v_mfma_f32_16x16x32_bf16 v[36:39], v[148:151], v[194:197], v[36:39]
	v_mfma_f32_16x16x32_bf16 v[32:35], v[156:159], v[194:197], v[32:35]
	v_mfma_f32_16x16x32_bf16 v[20:23], v[148:151], v[202:205], v[20:23]
	v_mfma_f32_16x16x32_bf16 v[16:19], v[156:159], v[202:205], v[16:19]
	v_mfma_f32_16x16x32_bf16 v[4:7], v[148:151], v[210:213], v[4:7]
	v_mfma_f32_16x16x32_bf16 v[0:3], v[156:159], v[210:213], v[0:3]
	s_barrier
; #define PG8_STAGE(bufoff, gbase, voff) do { _Pragma("unroll") for (int _i = 0; _i < 2; ++_i) \
;         __builtin_amdgcn_global_load_lds((const unsigned*)((const char*)(gbase) + (voff)[_i]), (PG8_LAS unsigned*)(lds + (bufoff) + ldsw + _i * 8192), 16, 0, 0); } while (0)
; #define PG8_LDA(dst, b, h) do { _Pragma("unroll") for (int m = 0; m < 4; ++m) _Pragma("unroll") for (int k = 0; k < 2; ++k) dst[m][k] = *(const PG8_LAS bf16x8*)(lds + PG8_SA(b, h) + aoff + m * 2048 + k * 1024); } while (0)
; #define PG8_LDB(dst, b, h) do { _Pragma("unroll") for (int n = 0; n < 2; ++n) _Pragma("unroll") for (int k = 0; k < 2; ++k) dst[n][k] = *(const PG8_LAS bf16x8*)(lds + PG8_SB(b, h) + boff + n * 2048 + k * 1024); } while (0)
; #define PG8_MMA(ai, bj, At, Bt) do { __builtin_amdgcn_s_setprio(1); _Pragma("unroll") for (int m = 0; m < 4; ++m) _Pragma("unroll") for (int n = 0; n < 2; ++n) _Pragma("unroll") for (int k = 0; k < 2; ++k) \
;         acc[ai][bj][m][n] = __builtin_amdgcn_mfma_f32_16x16x32_bf16(Bt[n][k], At[m][k], acc[ai][bj][m][n], 0, 0, 0); __builtin_amdgcn_s_setprio(0); } while (0)
; #define PG8_WAIT_V(n) asm volatile("s_waitcnt vmcnt(" #n ")" ::: "memory")
; #define PG8_WAIT_L(n) asm volatile("s_waitcnt lgkmcnt(" #n ")" ::: "memory")
; #define PG8_BAR __builtin_amdgcn_s_barrier()
; #define PG8_SCHED __builtin_amdgcn_sched_barrier(0)
; template <class Epi, class Sched, bool ALIGN_EPI = false, bool SP2 = false>
; __device__ __forceinline__ void gemm_phase(PG8_LAS unsigned char* lds, const Gemm g, const Sched& S, const Epi& E) {
;     ...
;             PG8_LDB(B0, 1, 0); PG8_LDB(B1, 1, 1); PG8_SCHED; PG8_LDA(At, 1, 0); PG8_STAGE(PG8_SA(0, 1), a2 + hstepA, voffA);
;             PG8_WAIT_V(8); PG8_WAIT_L(0); PG8_BAR; PG8_MMA(0, 0, At, B0); PG8_MMA(0, 1, At, B1); PG8_BAR; PG8_SCHED;
;             PG8_LDA(At, 1, 1); PG8_STAGE(PG8_SB(1, 0), b3, voffB); PG8_STAGE(PG8_SB(1, 1), b3 + hstep, voffB); PG8_STAGE(PG8_SA(1, 0), a3, voffA);
;             PG8_WAIT_V(8); PG8_WAIT_L(0); PG8_BAR; PG8_MMA(1, 0, At, B0); PG8_MMA(1, 1, At, B1); PG8_BAR; PG8_SCHED;
;     ...
;         if constexpr (ALIGN_EPI) { if (wr == 0) PG8_BAR; }
	s_add_i32 s89, 0, 0x18000
	s_add_i32 s90, 0, 0x1c000
	ds_read_b128 v[128:131], v214
	ds_read_b128 v[132:135], v214 offset:1024
	ds_read_b128 v[136:139], v214 offset:2048
	ds_read_b128 v[140:143], v214 offset:3072
	ds_read_b128 v[144:147], v215
	ds_read_b128 v[148:151], v215 offset:1024
	ds_read_b128 v[152:155], v215 offset:2048
	ds_read_b128 v[156:159], v215 offset:3072
	s_add_u32 s8, s60, 0x100000
	s_addc_u32 s9, s61, 0
	s_mov_b32 m0, s65
	ds_read_b128 v[160:163], v238 offset:32768
	ds_read_b128 v[186:189], v238 offset:33792
	ds_read_b128 v[190:193], v238 offset:34816
	ds_read_b128 v[194:197], v238 offset:35840
	ds_read_b128 v[198:201], v238 offset:36864
	ds_read_b128 v[202:205], v238 offset:37888
	ds_read_b128 v[206:209], v238 offset:38912
	ds_read_b128 v[210:213], v238 offset:39936
	global_load_lds_dwordx4 v166, s[8:9]
	s_mov_b32 m0, s66
	s_nop 0
	global_load_lds_dwordx4 v170, s[8:9]
	s_waitcnt vmcnt(8)
	s_waitcnt lgkmcnt(0)
	s_barrier
	v_mfma_f32_16x16x32_bf16 v[124:127], v[128:131], v[160:163], v[124:127]
	v_mfma_f32_16x16x32_bf16 v[120:123], v[136:139], v[160:163], v[120:123]
	v_mfma_f32_16x16x32_bf16 v[108:111], v[128:131], v[190:193], v[108:111]
	v_mfma_f32_16x16x32_bf16 v[104:107], v[136:139], v[190:193], v[104:107]
	v_mfma_f32_16x16x32_bf16 v[92:95], v[128:131], v[198:201], v[92:95]
	v_mfma_f32_16x16x32_bf16 v[88:91], v[136:139], v[198:201], v[88:91]
	v_mfma_f32_16x16x32_bf16 v[76:79], v[128:131], v[206:209], v[76:79]
	v_mfma_f32_16x16x32_bf16 v[72:75], v[136:139], v[206:209], v[72:75]
	v_mfma_f32_16x16x32_bf16 v[124:127], v[132:135], v[186:189], v[124:127]
	v_mfma_f32_16x16x32_bf16 v[120:123], v[140:143], v[186:189], v[120:123]
	v_mfma_f32_16x16x32_bf16 v[108:111], v[132:135], v[194:197], v[108:111]
	v_mfma_f32_16x16x32_bf16 v[104:107], v[140:143], v[194:197], v[104:107]
	v_mfma_f32_16x16x32_bf16 v[92:95], v[132:135], v[202:205], v[92:95]
	v_mfma_f32_16x16x32_bf16 v[88:91], v[140:143], v[202:205], v[88:91]
	v_mfma_f32_16x16x32_bf16 v[76:79], v[132:135], v[210:213], v[76:79]
	v_mfma_f32_16x16x32_bf16 v[72:75], v[140:143], v[210:213], v[72:75]
	v_mfma_f32_16x16x32_bf16 v[116:119], v[144:147], v[160:163], v[116:119]
	v_mfma_f32_16x16x32_bf16 v[112:115], v[152:155], v[160:163], v[112:115]
	v_mfma_f32_16x16x32_bf16 v[100:103], v[144:147], v[190:193], v[100:103]
	v_mfma_f32_16x16x32_bf16 v[96:99], v[152:155], v[190:193], v[96:99]
	v_mfma_f32_16x16x32_bf16 v[84:87], v[144:147], v[198:201], v[84:87]
	v_mfma_f32_16x16x32_bf16 v[80:83], v[152:155], v[198:201], v[80:83]
	v_mfma_f32_16x16x32_bf16 v[68:71], v[144:147], v[206:209], v[68:71]
	v_mfma_f32_16x16x32_bf16 v[64:67], v[152:155], v[206:209], v[64:67]
	v_mfma_f32_16x16x32_bf16 v[116:119], v[148:151], v[186:189], v[116:119]
	v_mfma_f32_16x16x32_bf16 v[112:115], v[156:159], v[186:189], v[112:115]
	v_mfma_f32_16x16x32_bf16 v[100:103], v[148:151], v[194:197], v[100:103]
	v_mfma_f32_16x16x32_bf16 v[96:99], v[156:159], v[194:197], v[96:99]
	v_mfma_f32_16x16x32_bf16 v[84:87], v[148:151], v[202:205], v[84:87]
	v_mfma_f32_16x16x32_bf16 v[80:83], v[156:159], v[202:205], v[80:83]
	v_mfma_f32_16x16x32_bf16 v[68:71], v[148:151], v[210:213], v[68:71]
	v_mfma_f32_16x16x32_bf16 v[64:67], v[156:159], v[210:213], v[64:67]
	s_barrier
	s_add_i32 s8, s89, s63
	s_mov_b32 m0, s8
	ds_read_b128 v[160:163], v238 offset:49152
	ds_read_b128 v[186:189], v238 offset:50176
	ds_read_b128 v[190:193], v238 offset:51200
	ds_read_b128 v[194:197], v238 offset:52224
	ds_read_b128 v[198:201], v238 offset:53248
	ds_read_b128 v[202:205], v238 offset:54272
	ds_read_b128 v[206:209], v238 offset:55296
	ds_read_b128 v[210:213], v238 offset:56320
	global_load_lds_dwordx4 v168, s[98:99]
	s_add_i32 m0, s8, 0x2000
	s_add_u32 s8, s58, 0x100080
	s_addc_u32 s9, s59, 0
	s_add_i32 s58, s90, s63
	global_load_lds_dwordx4 v172, s[98:99]
	s_mov_b32 m0, s58
	s_nop 0
	global_load_lds_dwordx4 v168, s[8:9]
	s_add_i32 m0, s58, 0x2000
	s_nop 0
	global_load_lds_dwordx4 v172, s[8:9]
	s_mov_b32 m0, s70
	s_nop 0
	global_load_lds_dwordx4 v166, s[100:101]
	s_mov_b32 m0, s71
	s_nop 0
	global_load_lds_dwordx4 v170, s[100:101]
	s_waitcnt vmcnt(8)
	s_waitcnt lgkmcnt(0)
	s_barrier
	v_mfma_f32_16x16x32_bf16 v[60:63], v[128:131], v[160:163], v[60:63]
	v_mfma_f32_16x16x32_bf16 v[56:59], v[136:139], v[160:163], v[56:59]
	v_mfma_f32_16x16x32_bf16 v[44:47], v[128:131], v[190:193], v[44:47]
	v_mfma_f32_16x16x32_bf16 v[40:43], v[136:139], v[190:193], v[40:43]
	v_mfma_f32_16x16x32_bf16 v[28:31], v[128:131], v[198:201], v[28:31]
	v_mfma_f32_16x16x32_bf16 v[24:27], v[136:139], v[198:201], v[24:27]
	v_mfma_f32_16x16x32_bf16 v[12:15], v[128:131], v[206:209], v[12:15]
	v_mfma_f32_16x16x32_bf16 v[8:11], v[136:139], v[206:209], v[8:11]
	v_mfma_f32_16x16x32_bf16 v[60:63], v[132:135], v[186:189], v[60:63]
	v_mfma_f32_16x16x32_bf16 v[56:59], v[140:143], v[186:189], v[56:59]
	v_mfma_f32_16x16x32_bf16 v[44:47], v[132:135], v[194:197], v[44:47]
	v_mfma_f32_16x16x32_bf16 v[40:43], v[140:143], v[194:197], v[40:43]
	v_mfma_f32_16x16x32_bf16 v[28:31], v[132:135], v[202:205], v[28:31]
	v_mfma_f32_16x16x32_bf16 v[24:27], v[140:143], v[202:205], v[24:27]
	v_mfma_f32_16x16x32_bf16 v[12:15], v[132:135], v[210:213], v[12:15]
	v_mfma_f32_16x16x32_bf16 v[8:11], v[140:143], v[210:213], v[8:11]
	v_mfma_f32_16x16x32_bf16 v[52:55], v[144:147], v[160:163], v[52:55]
	v_mfma_f32_16x16x32_bf16 v[48:51], v[152:155], v[160:163], v[48:51]
	v_mfma_f32_16x16x32_bf16 v[36:39], v[144:147], v[190:193], v[36:39]
	v_mfma_f32_16x16x32_bf16 v[32:35], v[152:155], v[190:193], v[32:35]
	v_mfma_f32_16x16x32_bf16 v[20:23], v[144:147], v[198:201], v[20:23]
	v_mfma_f32_16x16x32_bf16 v[16:19], v[152:155], v[198:201], v[16:19]
	v_mfma_f32_16x16x32_bf16 v[4:7], v[144:147], v[206:209], v[4:7]
	v_mfma_f32_16x16x32_bf16 v[0:3], v[152:155], v[206:209], v[0:3]
	v_mfma_f32_16x16x32_bf16 v[52:55], v[148:151], v[186:189], v[52:55]
	v_mfma_f32_16x16x32_bf16 v[48:51], v[156:159], v[186:189], v[48:51]
	v_mfma_f32_16x16x32_bf16 v[36:39], v[148:151], v[194:197], v[36:39]
	v_mfma_f32_16x16x32_bf16 v[32:35], v[156:159], v[194:197], v[32:35]
	v_mfma_f32_16x16x32_bf16 v[20:23], v[148:151], v[202:205], v[20:23]
	v_mfma_f32_16x16x32_bf16 v[16:19], v[156:159], v[202:205], v[16:19]
	v_mfma_f32_16x16x32_bf16 v[4:7], v[148:151], v[210:213], v[4:7]
	v_mfma_f32_16x16x32_bf16 v[0:3], v[156:159], v[210:213], v[0:3]
	s_barrier
	s_add_i32 s88, s88, 2
	s_add_u32 s86, s86, 0x100
	s_addc_u32 s87, s87, 0
	s_cmp_gt_u32 s88, 61
	s_mov_b64 s[8:9], s[10:11]
	s_cbranch_scc0 .LBB0_2882
	s_and_b64 vcc, exec, s[18:19]
	s_cbranch_vccz .LBB0_2885
	s_barrier

; #define PG8_STAGE(bufoff, gbase, voff) do { _Pragma("unroll") for (int _i = 0; _i < 2; ++_i) \
;         __builtin_amdgcn_global_load_lds((const unsigned*)((const char*)(gbase) + (voff)[_i]), (PG8_LAS unsigned*)(lds + (bufoff) + ldsw + _i * 8192), 16, 0, 0); } while (0)
; #define PG8_LDA(dst, b, h) do { _Pragma("unroll") for (int m = 0; m < 4; ++m) _Pragma("unroll") for (int k = 0; k < 2; ++k) dst[m][k] = *(const PG8_LAS bf16x8*)(lds + PG8_SA(b, h) + aoff + m * 2048 + k * 1024); } while (0)
; #define PG8_LDB(dst, b, h) do { _Pragma("unroll") for (int n = 0; n < 2; ++n) _Pragma("unroll") for (int k = 0; k < 2; ++k) dst[n][k] = *(const PG8_LAS bf16x8*)(lds + PG8_SB(b, h) + boff + n * 2048 + k * 1024); } while (0)
; #define PG8_MMA(ai, bj, At, Bt) do { __builtin_amdgcn_s_setprio(1); _Pragma("unroll") for (int m = 0; m < 4; ++m) _Pragma("unroll") for (int n = 0; n < 2; ++n) _Pragma("unroll") for (int k = 0; k < 2; ++k) \
;         acc[ai][bj][m][n] = __builtin_amdgcn_mfma_f32_16x16x32_bf16(Bt[n][k], At[m][k], acc[ai][bj][m][n], 0, 0, 0); __builtin_amdgcn_s_setprio(0); } while (0)
; #define PG8_WAIT_V(n) asm volatile("s_waitcnt vmcnt(" #n ")" ::: "memory")
; #define PG8_WAIT_L(n) asm volatile("s_waitcnt lgkmcnt(" #n ")" ::: "memory")
; #define PG8_BAR __builtin_amdgcn_s_barrier()
; #define PG8_SCHED __builtin_amdgcn_sched_barrier(0)
; template <class Epi, class Sched, bool ALIGN_EPI = false, bool SP2 = false>
; __device__ __forceinline__ void gemm_phase(PG8_LAS unsigned char* lds, const Gemm g, const Sched& S, const Epi& E) {
;     ...
;             PG8_LDB(B0, 0, 0); PG8_LDB(B1, 0, 1); PG8_SCHED; PG8_LDA(At, 0, 0); PG8_STAGE(PG8_SA(1, 1), a1 + hstepA, voffA);
;             PG8_WAIT_V(8); PG8_WAIT_L(0); PG8_BAR; PG8_MMA(0, 0, At, B0); PG8_MMA(0, 1, At, B1); PG8_BAR; PG8_SCHED;
;     ...
;         for (int a = 0; a < 2; ++a)
; #pragma unroll
;             for (int b = 0; b < 2; ++b)
; #pragma unroll
;                 for (int m = 0; m < 4; ++m)
; #pragma unroll
;                     for (int n = 0; n < 2; ++n) acc[a][b][m][n] = (f32x4){0.f, 0.f, 0.f, 0.f};
.LBB0_3086:
	s_add_u32 s63, s34, 0x100
	s_addc_u32 s64, s35, 0
	s_add_u32 s34, s36, 0xc000
	v_mov_b32_e32 v0, 0
	s_addc_u32 s35, s37, 0
	s_mov_b32 s65, -2
	s_waitcnt lgkmcnt(0)
	v_mov_b32_e32 v1, v0
	v_mov_b32_e32 v2, v0
	v_mov_b32_e32 v3, v0
	v_mov_b32_e32 v4, v0
	v_mov_b32_e32 v5, v0
	v_mov_b32_e32 v6, v0
	v_mov_b32_e32 v7, v0
	v_mov_b32_e32 v16, v0
	v_mov_b32_e32 v17, v0
	v_mov_b32_e32 v18, v0
	v_mov_b32_e32 v19, v0
	v_mov_b32_e32 v20, v0
	v_mov_b32_e32 v21, v0
	v_mov_b32_e32 v22, v0
	v_mov_b32_e32 v23, v0
	v_mov_b32_e32 v32, v0
	v_mov_b32_e32 v33, v0
	v_mov_b32_e32 v34, v0
	v_mov_b32_e32 v35, v0
	s_waitcnt vmcnt(0)
	v_mov_b32_e32 v36, v0
	v_mov_b32_e32 v37, v0
	v_mov_b32_e32 v38, v0
	v_mov_b32_e32 v39, v0
	v_mov_b32_e32 v48, v0
	v_mov_b32_e32 v49, v0
	v_mov_b32_e32 v50, v0
	v_mov_b32_e32 v51, v0
	v_mov_b32_e32 v52, v0
	v_mov_b32_e32 v53, v0
	v_mov_b32_e32 v54, v0
	v_mov_b32_e32 v55, v0
	v_mov_b32_e32 v8, v0
	v_mov_b32_e32 v9, v0
	v_mov_b32_e32 v10, v0
	v_mov_b32_e32 v11, v0
	v_mov_b32_e32 v12, v0
	v_mov_b32_e32 v13, v0
	v_mov_b32_e32 v14, v0
	v_mov_b32_e32 v15, v0
	v_mov_b32_e32 v24, v0
	v_mov_b32_e32 v25, v0
	v_mov_b32_e32 v26, v0
	v_mov_b32_e32 v27, v0
	v_mov_b32_e32 v28, v0
	v_mov_b32_e32 v29, v0
	v_mov_b32_e32 v30, v0
	v_mov_b32_e32 v31, v0
	v_mov_b32_e32 v40, v0
	v_mov_b32_e32 v41, v0
	v_mov_b32_e32 v42, v0
	v_mov_b32_e32 v43, v0
	v_mov_b32_e32 v44, v0
	v_mov_b32_e32 v45, v0
	v_mov_b32_e32 v46, v0
	v_mov_b32_e32 v47, v0
	v_mov_b32_e32 v56, v0
	v_mov_b32_e32 v57, v0
	v_mov_b32_e32 v58, v0
	v_mov_b32_e32 v59, v0
	v_mov_b32_e32 v60, v0
	v_mov_b32_e32 v61, v0
	v_mov_b32_e32 v62, v0
	v_mov_b32_e32 v63, v0
	v_mov_b32_e32 v64, v0
	v_mov_b32_e32 v65, v0
	v_mov_b32_e32 v66, v0
	v_mov_b32_e32 v67, v0
	v_mov_b32_e32 v68, v0
	v_mov_b32_e32 v69, v0
	v_mov_b32_e32 v70, v0
	v_mov_b32_e32 v71, v0
	v_mov_b32_e32 v80, v0
	v_mov_b32_e32 v81, v0
	v_mov_b32_e32 v82, v0
	v_mov_b32_e32 v83, v0
	v_mov_b32_e32 v84, v0
	v_mov_b32_e32 v85, v0
	v_mov_b32_e32 v86, v0
	v_mov_b32_e32 v87, v0
	v_mov_b32_e32 v96, v0
	v_mov_b32_e32 v97, v0
	v_mov_b32_e32 v98, v0
	v_mov_b32_e32 v99, v0
	v_mov_b32_e32 v100, v0
	v_mov_b32_e32 v101, v0
	v_mov_b32_e32 v102, v0
	v_mov_b32_e32 v103, v0
	v_mov_b32_e32 v112, v0
	v_mov_b32_e32 v113, v0
	v_mov_b32_e32 v114, v0
	v_mov_b32_e32 v115, v0
	v_mov_b32_e32 v116, v0
	v_mov_b32_e32 v117, v0
	v_mov_b32_e32 v118, v0
	v_mov_b32_e32 v119, v0
	v_mov_b32_e32 v72, v0
	v_mov_b32_e32 v73, v0
	v_mov_b32_e32 v74, v0
	v_mov_b32_e32 v75, v0
	v_mov_b32_e32 v76, v0
	v_mov_b32_e32 v77, v0
	v_mov_b32_e32 v78, v0
	v_mov_b32_e32 v79, v0
	v_mov_b32_e32 v88, v0
	v_mov_b32_e32 v89, v0
	v_mov_b32_e32 v90, v0
	v_mov_b32_e32 v91, v0
	v_mov_b32_e32 v92, v0
	v_mov_b32_e32 v93, v0
	v_mov_b32_e32 v94, v0
	v_mov_b32_e32 v95, v0
	v_mov_b32_e32 v104, v0
	v_mov_b32_e32 v105, v0
	v_mov_b32_e32 v106, v0
	v_mov_b32_e32 v107, v0
	v_mov_b32_e32 v108, v0
	v_mov_b32_e32 v109, v0
	v_mov_b32_e32 v110, v0
	v_mov_b32_e32 v111, v0
	v_mov_b32_e32 v120, v0
	v_mov_b32_e32 v121, v0
	v_mov_b32_e32 v122, v0
	v_mov_b32_e32 v123, v0
	v_mov_b32_e32 v124, v0
	v_mov_b32_e32 v125, v0
	v_mov_b32_e32 v126, v0
	v_mov_b32_e32 v127, v0
	v_add_u32_e32 v148, 0x18000, v151
	v_add_u32_e32 v149, 0x1c000, v151
.LBB0_3087:
	ds_read_b128 v[144:147], v153
	ds_read_b128 v[158:161], v153 offset:1024
	ds_read_b128 v[162:165], v153 offset:2048
	ds_read_b128 v[166:169], v153 offset:3072
	ds_read_b128 v[170:173], v154
	ds_read_b128 v[174:177], v154 offset:1024
	ds_read_b128 v[178:181], v154 offset:2048
	ds_read_b128 v[182:185], v154 offset:3072
	s_add_u32 s36, s34, 0x4000
	s_addc_u32 s37, s35, 0
	s_cmpk_eq_i32 s65, 0xa8
	s_cselect_b32 s42, s6, s36
	s_cselect_b32 s43, s7, s37
	s_cselect_b32 s40, s30, s63
	s_cselect_b32 s41, s31, s64
	s_add_u32 s36, s42, 0x8000
	s_addc_u32 s37, s43, 0
	s_add_i32 m0, s44, 0xc000
	ds_read_b128 v[186:189], v155
	ds_read_b128 v[190:193], v155 offset:1024
	ds_read_b128 v[194:197], v155 offset:2048
	ds_read_b128 v[198:201], v155 offset:3072
	ds_read_b128 v[202:205], v155 offset:4096
	ds_read_b128 v[206:209], v155 offset:5120
	ds_read_b128 v[210:213], v155 offset:6144
	ds_read_b128 v[214:217], v155 offset:7168
	global_load_lds_dwordx4 v136, s[34:35]
	s_add_i32 m0, s44, 0xe000
	s_nop 0
	global_load_lds_dwordx4 v138, s[34:35]
	s_waitcnt vmcnt(8)
	s_waitcnt lgkmcnt(0)
	s_barrier
	v_mfma_f32_16x16x32_bf16 v[124:127], v[144:147], v[186:189], v[124:127]
	v_mfma_f32_16x16x32_bf16 v[120:123], v[162:165], v[186:189], v[120:123]
	v_mfma_f32_16x16x32_bf16 v[108:111], v[144:147], v[194:197], v[108:111]
	v_mfma_f32_16x16x32_bf16 v[104:107], v[162:165], v[194:197], v[104:107]
	v_mfma_f32_16x16x32_bf16 v[92:95], v[144:147], v[202:205], v[92:95]
	v_mfma_f32_16x16x32_bf16 v[88:91], v[162:165], v[202:205], v[88:91]
	v_mfma_f32_16x16x32_bf16 v[76:79], v[144:147], v[210:213], v[76:79]
	v_mfma_f32_16x16x32_bf16 v[72:75], v[162:165], v[210:213], v[72:75]
	v_mfma_f32_16x16x32_bf16 v[124:127], v[158:161], v[190:193], v[124:127]
	v_mfma_f32_16x16x32_bf16 v[120:123], v[166:169], v[190:193], v[120:123]
	v_mfma_f32_16x16x32_bf16 v[108:111], v[158:161], v[198:201], v[108:111]
	v_mfma_f32_16x16x32_bf16 v[104:107], v[166:169], v[198:201], v[104:107]
	v_mfma_f32_16x16x32_bf16 v[92:95], v[158:161], v[206:209], v[92:95]
	v_mfma_f32_16x16x32_bf16 v[88:91], v[166:169], v[206:209], v[88:91]
	v_mfma_f32_16x16x32_bf16 v[76:79], v[158:161], v[214:217], v[76:79]
	v_mfma_f32_16x16x32_bf16 v[72:75], v[166:169], v[214:217], v[72:75]
	v_mfma_f32_16x16x32_bf16 v[116:119], v[170:173], v[186:189], v[116:119]
	v_mfma_f32_16x16x32_bf16 v[112:115], v[178:181], v[186:189], v[112:115]
	v_mfma_f32_16x16x32_bf16 v[100:103], v[170:173], v[194:197], v[100:103]
	v_mfma_f32_16x16x32_bf16 v[96:99], v[178:181], v[194:197], v[96:99]
	v_mfma_f32_16x16x32_bf16 v[84:87], v[170:173], v[202:205], v[84:87]
	v_mfma_f32_16x16x32_bf16 v[80:83], v[178:181], v[202:205], v[80:83]
	v_mfma_f32_16x16x32_bf16 v[68:71], v[170:173], v[210:213], v[68:71]
	v_mfma_f32_16x16x32_bf16 v[64:67], v[178:181], v[210:213], v[64:67]
	v_mfma_f32_16x16x32_bf16 v[116:119], v[174:177], v[190:193], v[116:119]
	v_mfma_f32_16x16x32_bf16 v[112:115], v[182:185], v[190:193], v[112:115]
	v_mfma_f32_16x16x32_bf16 v[100:103], v[174:177], v[198:201], v[100:103]
	v_mfma_f32_16x16x32_bf16 v[96:99], v[182:185], v[198:201], v[96:99]
	v_mfma_f32_16x16x32_bf16 v[84:87], v[174:177], v[206:209], v[84:87]
	v_mfma_f32_16x16x32_bf16 v[80:83], v[182:185], v[206:209], v[80:83]
	v_mfma_f32_16x16x32_bf16 v[68:71], v[174:177], v[214:217], v[68:71]
	v_mfma_f32_16x16x32_bf16 v[64:67], v[182:185], v[214:217], v[64:67]
	s_barrier
; #define PG8_STAGE(bufoff, gbase, voff) do { _Pragma("unroll") for (int _i = 0; _i < 2; ++_i) \
;         __builtin_amdgcn_global_load_lds((const unsigned*)((const char*)(gbase) + (voff)[_i]), (PG8_LAS unsigned*)(lds + (bufoff) + ldsw + _i * 8192), 16, 0, 0); } while (0)
; #define PG8_LDA(dst, b, h) do { _Pragma("unroll") for (int m = 0; m < 4; ++m) _Pragma("unroll") for (int k = 0; k < 2; ++k) dst[m][k] = *(const PG8_LAS bf16x8*)(lds + PG8_SA(b, h) + aoff + m * 2048 + k * 1024); } while (0)
; #define PG8_LDB(dst, b, h) do { _Pragma("unroll") for (int n = 0; n < 2; ++n) _Pragma("unroll") for (int k = 0; k < 2; ++k) dst[n][k] = *(const PG8_LAS bf16x8*)(lds + PG8_SB(b, h) + boff + n * 2048 + k * 1024); } while (0)
; #define PG8_MMA(ai, bj, At, Bt) do { __builtin_amdgcn_s_setprio(1); _Pragma("unroll") for (int m = 0; m < 4; ++m) _Pragma("unroll") for (int n = 0; n < 2; ++n) _Pragma("unroll") for (int k = 0; k < 2; ++k) \
;         acc[ai][bj][m][n] = __builtin_amdgcn_mfma_f32_16x16x32_bf16(Bt[n][k], At[m][k], acc[ai][bj][m][n], 0, 0, 0); __builtin_amdgcn_s_setprio(0); } while (0)
; #define PG8_WAIT_V(n) asm volatile("s_waitcnt vmcnt(" #n ")" ::: "memory")
; #define PG8_WAIT_L(n) asm volatile("s_waitcnt lgkmcnt(" #n ")" ::: "memory")
; #define PG8_BAR __builtin_amdgcn_s_barrier()
; #define PG8_SCHED __builtin_amdgcn_sched_barrier(0)
; template <class Epi, class Sched, bool ALIGN_EPI = false, bool SP2 = false>
; __device__ __forceinline__ void gemm_phase(PG8_LAS unsigned char* lds, const Gemm g, const Sched& S, const Epi& E) {
;     ...
;             PG8_LDA(At, 0, 1); PG8_STAGE(PG8_SB(0, 0), b2, voffB); PG8_STAGE(PG8_SB(0, 1), b2 + hstep, voffB); PG8_STAGE(PG8_SA(0, 0), a2, voffA);
;             PG8_WAIT_V(8); PG8_WAIT_L(0); PG8_BAR; PG8_MMA(1, 0, At, B0); PG8_MMA(1, 1, At, B1); PG8_BAR; PG8_SCHED;
;             PG8_LDB(B0, 1, 0); PG8_LDB(B1, 1, 1); PG8_SCHED; PG8_LDA(At, 1, 0); PG8_STAGE(PG8_SA(0, 1), a2 + hstepA, voffA);
;             PG8_WAIT_V(8); PG8_WAIT_L(0); PG8_BAR; PG8_MMA(0, 0, At, B0); PG8_MMA(0, 1, At, B1); PG8_BAR; PG8_SCHED;
	s_add_u32 s98, s40, s16
	s_addc_u32 s99, s41, s17
	s_add_i32 s66, s53, s33
	s_mov_b32 m0, s66
	ds_read_b128 v[186:189], v155 offset:16384
	ds_read_b128 v[190:193], v155 offset:17408
	ds_read_b128 v[194:197], v155 offset:18432
	ds_read_b128 v[198:201], v155 offset:19456
	ds_read_b128 v[202:205], v155 offset:20480
	ds_read_b128 v[206:209], v155 offset:21504
	ds_read_b128 v[210:213], v155 offset:22528
	ds_read_b128 v[214:217], v155 offset:23552
	global_load_lds_dwordx4 v130, s[40:41]
	s_add_i32 m0, s66, 0x2000
	s_add_u32 s66, s40, 0x2b0000
	s_addc_u32 s67, s41, 0
	s_add_i32 s68, s54, s33
	global_load_lds_dwordx4 v134, s[40:41]
	s_mov_b32 m0, s68
	s_nop 0
	global_load_lds_dwordx4 v130, s[66:67]
	s_add_i32 m0, s68, 0x2000
	s_nop 0
	global_load_lds_dwordx4 v134, s[66:67]
	s_mov_b32 m0, s44
	s_nop 0
	global_load_lds_dwordx4 v128, s[42:43]
	s_mov_b32 m0, s45
	s_nop 0
	global_load_lds_dwordx4 v132, s[42:43]
	s_waitcnt vmcnt(8)
	s_waitcnt lgkmcnt(0)
	s_barrier
	v_mfma_f32_16x16x32_bf16 v[60:63], v[144:147], v[186:189], v[60:63]
	v_mfma_f32_16x16x32_bf16 v[56:59], v[162:165], v[186:189], v[56:59]
	v_mfma_f32_16x16x32_bf16 v[44:47], v[144:147], v[194:197], v[44:47]
	v_mfma_f32_16x16x32_bf16 v[40:43], v[162:165], v[194:197], v[40:43]
	v_mfma_f32_16x16x32_bf16 v[28:31], v[144:147], v[202:205], v[28:31]
	v_mfma_f32_16x16x32_bf16 v[24:27], v[162:165], v[202:205], v[24:27]
	v_mfma_f32_16x16x32_bf16 v[12:15], v[144:147], v[210:213], v[12:15]
	v_mfma_f32_16x16x32_bf16 v[8:11], v[162:165], v[210:213], v[8:11]
	v_mfma_f32_16x16x32_bf16 v[60:63], v[158:161], v[190:193], v[60:63]
	v_mfma_f32_16x16x32_bf16 v[56:59], v[166:169], v[190:193], v[56:59]
	v_mfma_f32_16x16x32_bf16 v[44:47], v[158:161], v[198:201], v[44:47]
	v_mfma_f32_16x16x32_bf16 v[40:43], v[166:169], v[198:201], v[40:43]
	v_mfma_f32_16x16x32_bf16 v[28:31], v[158:161], v[206:209], v[28:31]
	v_mfma_f32_16x16x32_bf16 v[24:27], v[166:169], v[206:209], v[24:27]
	v_mfma_f32_16x16x32_bf16 v[12:15], v[158:161], v[214:217], v[12:15]
	v_mfma_f32_16x16x32_bf16 v[8:11], v[166:169], v[214:217], v[8:11]
	v_mfma_f32_16x16x32_bf16 v[52:55], v[170:173], v[186:189], v[52:55]
	v_mfma_f32_16x16x32_bf16 v[48:51], v[178:181], v[186:189], v[48:51]
	v_mfma_f32_16x16x32_bf16 v[36:39], v[170:173], v[194:197], v[36:39]
	v_mfma_f32_16x16x32_bf16 v[32:35], v[178:181], v[194:197], v[32:35]
	v_mfma_f32_16x16x32_bf16 v[20:23], v[170:173], v[202:205], v[20:23]
	v_mfma_f32_16x16x32_bf16 v[16:19], v[178:181], v[202:205], v[16:19]
	v_mfma_f32_16x16x32_bf16 v[4:7], v[170:173], v[210:213], v[4:7]
	v_mfma_f32_16x16x32_bf16 v[0:3], v[178:181], v[210:213], v[0:3]
	v_mfma_f32_16x16x32_bf16 v[52:55], v[174:177], v[190:193], v[52:55]
	v_mfma_f32_16x16x32_bf16 v[48:51], v[182:185], v[190:193], v[48:51]
	v_mfma_f32_16x16x32_bf16 v[36:39], v[174:177], v[198:201], v[36:39]
	v_mfma_f32_16x16x32_bf16 v[32:35], v[182:185], v[198:201], v[32:35]
	v_mfma_f32_16x16x32_bf16 v[20:23], v[174:177], v[206:209], v[20:23]
	v_mfma_f32_16x16x32_bf16 v[16:19], v[182:185], v[206:209], v[16:19]
	v_mfma_f32_16x16x32_bf16 v[4:7], v[174:177], v[214:217], v[4:7]
	v_mfma_f32_16x16x32_bf16 v[0:3], v[182:185], v[214:217], v[0:3]
	s_barrier
	s_add_i32 s66, 0, 0x18000
	s_add_i32 s67, 0, 0x1c000
	ds_read_b128 v[144:147], v148
	ds_read_b128 v[158:161], v148 offset:1024
	ds_read_b128 v[162:165], v148 offset:2048
	ds_read_b128 v[166:169], v148 offset:3072
	ds_read_b128 v[170:173], v149
	ds_read_b128 v[174:177], v149 offset:1024
	ds_read_b128 v[178:181], v149 offset:2048
	ds_read_b128 v[182:185], v149 offset:3072
	s_add_u32 s42, s42, 0x4000
	s_addc_u32 s43, s43, 0
	s_mov_b32 m0, s46
	ds_read_b128 v[186:189], v155 offset:32768
	ds_read_b128 v[190:193], v155 offset:33792
	ds_read_b128 v[194:197], v155 offset:34816
	ds_read_b128 v[198:201], v155 offset:35840
	ds_read_b128 v[202:205], v155 offset:36864
	ds_read_b128 v[206:209], v155 offset:37888
	ds_read_b128 v[210:213], v155 offset:38912
	ds_read_b128 v[214:217], v155 offset:39936
	global_load_lds_dwordx4 v128, s[42:43]
	s_mov_b32 m0, s47
	s_nop 0
	global_load_lds_dwordx4 v132, s[42:43]
	s_waitcnt vmcnt(8)
	s_waitcnt lgkmcnt(0)
	s_barrier
; #define PG8_STAGE(bufoff, gbase, voff) do { _Pragma("unroll") for (int _i = 0; _i < 2; ++_i) \
;         __builtin_amdgcn_global_load_lds((const unsigned*)((const char*)(gbase) + (voff)[_i]), (PG8_LAS unsigned*)(lds + (bufoff) + ldsw + _i * 8192), 16, 0, 0); } while (0)
; #define PG8_LDA(dst, b, h) do { _Pragma("unroll") for (int m = 0; m < 4; ++m) _Pragma("unroll") for (int k = 0; k < 2; ++k) dst[m][k] = *(const PG8_LAS bf16x8*)(lds + PG8_SA(b, h) + aoff + m * 2048 + k * 1024); } while (0)
; #define PG8_MMA(ai, bj, At, Bt) do { __builtin_amdgcn_s_setprio(1); _Pragma("unroll") for (int m = 0; m < 4; ++m) _Pragma("unroll") for (int n = 0; n < 2; ++n) _Pragma("unroll") for (int k = 0; k < 2; ++k) \
;         acc[ai][bj][m][n] = __builtin_amdgcn_mfma_f32_16x16x32_bf16(Bt[n][k], At[m][k], acc[ai][bj][m][n], 0, 0, 0); __builtin_amdgcn_s_setprio(0); } while (0)
; #define PG8_WAIT_V(n) asm volatile("s_waitcnt vmcnt(" #n ")" ::: "memory")
; #define PG8_WAIT_L(n) asm volatile("s_waitcnt lgkmcnt(" #n ")" ::: "memory")
; #define PG8_BAR __builtin_amdgcn_s_barrier()
; #define PG8_SCHED __builtin_amdgcn_sched_barrier(0)
; template <class Epi, class Sched, bool ALIGN_EPI = false, bool SP2 = false>
; __device__ __forceinline__ void gemm_phase(PG8_LAS unsigned char* lds, const Gemm g, const Sched& S, const Epi& E) {
;     ...
;             PG8_WAIT_V(8); PG8_WAIT_L(0); PG8_BAR; PG8_MMA(0, 0, At, B0); PG8_MMA(0, 1, At, B1); PG8_BAR; PG8_SCHED;
;             PG8_LDA(At, 1, 1); PG8_STAGE(PG8_SB(1, 0), b3, voffB); PG8_STAGE(PG8_SB(1, 1), b3 + hstep, voffB); PG8_STAGE(PG8_SA(1, 0), a3, voffA);
;             PG8_WAIT_V(8); PG8_WAIT_L(0); PG8_BAR; PG8_MMA(1, 0, At, B0); PG8_MMA(1, 1, At, B1); PG8_BAR; PG8_SCHED;
;     ...
;         if constexpr (ALIGN_EPI) { if (wr == 0) PG8_BAR; }
	v_mfma_f32_16x16x32_bf16 v[124:127], v[144:147], v[186:189], v[124:127]
	v_mfma_f32_16x16x32_bf16 v[120:123], v[162:165], v[186:189], v[120:123]
	v_mfma_f32_16x16x32_bf16 v[108:111], v[144:147], v[194:197], v[108:111]
	v_mfma_f32_16x16x32_bf16 v[104:107], v[162:165], v[194:197], v[104:107]
	v_mfma_f32_16x16x32_bf16 v[92:95], v[144:147], v[202:205], v[92:95]
	v_mfma_f32_16x16x32_bf16 v[88:91], v[162:165], v[202:205], v[88:91]
	v_mfma_f32_16x16x32_bf16 v[76:79], v[144:147], v[210:213], v[76:79]
	v_mfma_f32_16x16x32_bf16 v[72:75], v[162:165], v[210:213], v[72:75]
	v_mfma_f32_16x16x32_bf16 v[124:127], v[158:161], v[190:193], v[124:127]
	v_mfma_f32_16x16x32_bf16 v[120:123], v[166:169], v[190:193], v[120:123]
	v_mfma_f32_16x16x32_bf16 v[108:111], v[158:161], v[198:201], v[108:111]
	v_mfma_f32_16x16x32_bf16 v[104:107], v[166:169], v[198:201], v[104:107]
	v_mfma_f32_16x16x32_bf16 v[92:95], v[158:161], v[206:209], v[92:95]
	v_mfma_f32_16x16x32_bf16 v[88:91], v[166:169], v[206:209], v[88:91]
	v_mfma_f32_16x16x32_bf16 v[76:79], v[158:161], v[214:217], v[76:79]
	v_mfma_f32_16x16x32_bf16 v[72:75], v[166:169], v[214:217], v[72:75]
	v_mfma_f32_16x16x32_bf16 v[116:119], v[170:173], v[186:189], v[116:119]
	v_mfma_f32_16x16x32_bf16 v[112:115], v[178:181], v[186:189], v[112:115]
	v_mfma_f32_16x16x32_bf16 v[100:103], v[170:173], v[194:197], v[100:103]
	v_mfma_f32_16x16x32_bf16 v[96:99], v[178:181], v[194:197], v[96:99]
	v_mfma_f32_16x16x32_bf16 v[84:87], v[170:173], v[202:205], v[84:87]
	v_mfma_f32_16x16x32_bf16 v[80:83], v[178:181], v[202:205], v[80:83]
	v_mfma_f32_16x16x32_bf16 v[68:71], v[170:173], v[210:213], v[68:71]
	v_mfma_f32_16x16x32_bf16 v[64:67], v[178:181], v[210:213], v[64:67]
	v_mfma_f32_16x16x32_bf16 v[116:119], v[174:177], v[190:193], v[116:119]
	v_mfma_f32_16x16x32_bf16 v[112:115], v[182:185], v[190:193], v[112:115]
	v_mfma_f32_16x16x32_bf16 v[100:103], v[174:177], v[198:201], v[100:103]
	v_mfma_f32_16x16x32_bf16 v[96:99], v[182:185], v[198:201], v[96:99]
	v_mfma_f32_16x16x32_bf16 v[84:87], v[174:177], v[206:209], v[84:87]
	v_mfma_f32_16x16x32_bf16 v[80:83], v[182:185], v[206:209], v[80:83]
	v_mfma_f32_16x16x32_bf16 v[68:71], v[174:177], v[214:217], v[68:71]
	v_mfma_f32_16x16x32_bf16 v[64:67], v[182:185], v[214:217], v[64:67]
	s_barrier
	s_add_i32 s42, s66, s33
	s_mov_b32 m0, s42
	ds_read_b128 v[186:189], v155 offset:49152
	ds_read_b128 v[190:193], v155 offset:50176
	ds_read_b128 v[194:197], v155 offset:51200
	ds_read_b128 v[198:201], v155 offset:52224
	ds_read_b128 v[202:205], v155 offset:53248
	ds_read_b128 v[206:209], v155 offset:54272
	ds_read_b128 v[210:213], v155 offset:55296
	ds_read_b128 v[214:217], v155 offset:56320
	global_load_lds_dwordx4 v130, s[98:99]
	s_add_i32 m0, s42, 0x2000
	s_add_u32 s40, s40, 0x2b0080
	s_addc_u32 s41, s41, 0
	s_add_i32 s42, s67, s33
	global_load_lds_dwordx4 v134, s[98:99]
	s_mov_b32 m0, s42
	s_nop 0
	global_load_lds_dwordx4 v130, s[40:41]
	s_add_i32 m0, s42, 0x2000
	s_nop 0
	global_load_lds_dwordx4 v134, s[40:41]
	s_mov_b32 m0, s49
	s_nop 0
	global_load_lds_dwordx4 v128, s[36:37]
	s_mov_b32 m0, s50
	s_nop 0
	global_load_lds_dwordx4 v132, s[36:37]
	s_waitcnt vmcnt(8)
	s_waitcnt lgkmcnt(0)
	s_barrier
	v_mfma_f32_16x16x32_bf16 v[60:63], v[144:147], v[186:189], v[60:63]
	v_mfma_f32_16x16x32_bf16 v[56:59], v[162:165], v[186:189], v[56:59]
	v_mfma_f32_16x16x32_bf16 v[44:47], v[144:147], v[194:197], v[44:47]
	v_mfma_f32_16x16x32_bf16 v[40:43], v[162:165], v[194:197], v[40:43]
	v_mfma_f32_16x16x32_bf16 v[28:31], v[144:147], v[202:205], v[28:31]
	v_mfma_f32_16x16x32_bf16 v[24:27], v[162:165], v[202:205], v[24:27]
	v_mfma_f32_16x16x32_bf16 v[12:15], v[144:147], v[210:213], v[12:15]
	v_mfma_f32_16x16x32_bf16 v[8:11], v[162:165], v[210:213], v[8:11]
	v_mfma_f32_16x16x32_bf16 v[60:63], v[158:161], v[190:193], v[60:63]
	v_mfma_f32_16x16x32_bf16 v[56:59], v[166:169], v[190:193], v[56:59]
	v_mfma_f32_16x16x32_bf16 v[44:47], v[158:161], v[198:201], v[44:47]
	v_mfma_f32_16x16x32_bf16 v[40:43], v[166:169], v[198:201], v[40:43]
	v_mfma_f32_16x16x32_bf16 v[28:31], v[158:161], v[206:209], v[28:31]
	v_mfma_f32_16x16x32_bf16 v[24:27], v[166:169], v[206:209], v[24:27]
	v_mfma_f32_16x16x32_bf16 v[12:15], v[158:161], v[214:217], v[12:15]
	v_mfma_f32_16x16x32_bf16 v[8:11], v[166:169], v[214:217], v[8:11]
	v_mfma_f32_16x16x32_bf16 v[52:55], v[170:173], v[186:189], v[52:55]
	v_mfma_f32_16x16x32_bf16 v[48:51], v[178:181], v[186:189], v[48:51]
	v_mfma_f32_16x16x32_bf16 v[36:39], v[170:173], v[194:197], v[36:39]
	v_mfma_f32_16x16x32_bf16 v[32:35], v[178:181], v[194:197], v[32:35]
	v_mfma_f32_16x16x32_bf16 v[20:23], v[170:173], v[202:205], v[20:23]
	v_mfma_f32_16x16x32_bf16 v[16:19], v[178:181], v[202:205], v[16:19]
	v_mfma_f32_16x16x32_bf16 v[4:7], v[170:173], v[210:213], v[4:7]
	v_mfma_f32_16x16x32_bf16 v[0:3], v[178:181], v[210:213], v[0:3]
	v_mfma_f32_16x16x32_bf16 v[52:55], v[174:177], v[190:193], v[52:55]
	v_mfma_f32_16x16x32_bf16 v[48:51], v[182:185], v[190:193], v[48:51]
	v_mfma_f32_16x16x32_bf16 v[36:39], v[174:177], v[198:201], v[36:39]
	v_mfma_f32_16x16x32_bf16 v[32:35], v[182:185], v[198:201], v[32:35]
	v_mfma_f32_16x16x32_bf16 v[20:23], v[174:177], v[206:209], v[20:23]
	v_mfma_f32_16x16x32_bf16 v[16:19], v[182:185], v[206:209], v[16:19]
	v_mfma_f32_16x16x32_bf16 v[4:7], v[174:177], v[214:217], v[4:7]
	v_mfma_f32_16x16x32_bf16 v[0:3], v[182:185], v[214:217], v[0:3]
	s_barrier
	s_add_i32 s65, s65, 2
	s_add_u32 s63, s63, 0x100
	s_addc_u32 s64, s64, 0
	s_add_u32 s34, s34, 0x10000
	s_addc_u32 s35, s35, 0
	s_cmpk_gt_u32 s65, 0xa9
	s_cbranch_scc0 .LBB0_3087
	s_and_b64 vcc, exec, s[18:19]
	s_cbranch_vccz .LBB0_3090
	s_barrier

; #define PG8_STAGE(bufoff, gbase, voff) do { _Pragma("unroll") for (int _i = 0; _i < 2; ++_i) \
;         __builtin_amdgcn_global_load_lds((const unsigned*)((const char*)(gbase) + (voff)[_i]), (PG8_LAS unsigned*)(lds + (bufoff) + ldsw + _i * 8192), 16, 0, 0); } while (0)
; #define PG8_LDA(dst, b, h) do { _Pragma("unroll") for (int m = 0; m < 4; ++m) _Pragma("unroll") for (int k = 0; k < 2; ++k) dst[m][k] = *(const PG8_LAS bf16x8*)(lds + PG8_SA(b, h) + aoff + m * 2048 + k * 1024); } while (0)
; #define PG8_LDB(dst, b, h) do { _Pragma("unroll") for (int n = 0; n < 2; ++n) _Pragma("unroll") for (int k = 0; k < 2; ++k) dst[n][k] = *(const PG8_LAS bf16x8*)(lds + PG8_SB(b, h) + boff + n * 2048 + k * 1024); } while (0)
; #define PG8_SCHED __builtin_amdgcn_sched_barrier(0)
; template <class Epi, class Sched, bool ALIGN_EPI = false, bool SP2 = false>
; __device__ __forceinline__ void gemm_phase(PG8_LAS unsigned char* lds, const Gemm g, const Sched& S, const Epi& E) {
;     ...
;         const bool has_next = S.next(ui + 1, nxt);
;         const char* nA = has_next ? (const char*)g.A + (size_t)nxt.pm * tstep : cA; const char* nB = has_next ? (const char*)g.Bt + (size_t)nxt.pn * tstep : cB;
;     ...
;             PG8_LDB(B0, 0, 0); PG8_LDB(B1, 0, 1); PG8_SCHED; PG8_LDA(At, 0, 0); PG8_STAGE(PG8_SA(1, 1), a1 + hstepA, voffA);
;     ...
;         for (int a = 0; a < 2; ++a)
; #pragma unroll
;             for (int b = 0; b < 2; ++b)
; #pragma unroll
;                 for (int m = 0; m < 4; ++m)
; #pragma unroll
;                     for (int n = 0; n < 2; ++n) acc[a][b][m][n] = (f32x4){0.f, 0.f, 0.f, 0.f};
.LBB0_3202:
	s_ashr_i32 s47, s46, 31
	s_lshl_b64 s[48:49], s[46:47], 21
	s_add_u32 s48, s96, s48
	s_addc_u32 s49, s97, s49
	s_and_b64 s[50:51], s[4:5], exec
	s_cselect_b32 s47, s49, s57
	s_cselect_b32 s53, s48, s56
	s_ashr_i32 s45, s44, 31
	s_lshl_b64 s[50:51], s[44:45], 21
	s_add_u32 s50, s14, s50
	s_addc_u32 s51, s15, s51
	s_and_b64 s[60:61], s[4:5], exec
	s_cselect_b32 s45, s51, s59
	s_cselect_b32 s71, s50, s58
	s_add_u32 s56, s56, 0x100080
	s_addc_u32 s57, s57, 0
	s_add_u32 s72, s58, 0x100
	v_mov_b32_e32 v0, 0
	s_addc_u32 s73, s59, 0
	s_mov_b32 s74, -2
	s_waitcnt lgkmcnt(0)
	v_mov_b32_e32 v1, v0
	v_mov_b32_e32 v2, v0
	v_mov_b32_e32 v3, v0
	v_mov_b32_e32 v4, v0
	v_mov_b32_e32 v5, v0
	v_mov_b32_e32 v6, v0
	v_mov_b32_e32 v7, v0
	v_mov_b32_e32 v16, v0
	v_mov_b32_e32 v17, v0
	v_mov_b32_e32 v18, v0
	v_mov_b32_e32 v19, v0
	v_mov_b32_e32 v20, v0
	v_mov_b32_e32 v21, v0
	v_mov_b32_e32 v22, v0
	v_mov_b32_e32 v23, v0
	v_mov_b32_e32 v32, v0
	v_mov_b32_e32 v33, v0
	v_mov_b32_e32 v34, v0
	v_mov_b32_e32 v35, v0
	s_waitcnt vmcnt(0)
	v_mov_b32_e32 v36, v0
	v_mov_b32_e32 v37, v0
	v_mov_b32_e32 v38, v0
	v_mov_b32_e32 v39, v0
	v_mov_b32_e32 v48, v0
	v_mov_b32_e32 v49, v0
	v_mov_b32_e32 v50, v0
	v_mov_b32_e32 v51, v0
	v_mov_b32_e32 v52, v0
	v_mov_b32_e32 v53, v0
	v_mov_b32_e32 v54, v0
	v_mov_b32_e32 v55, v0
	v_mov_b32_e32 v8, v0
	v_mov_b32_e32 v9, v0
	v_mov_b32_e32 v10, v0
	v_mov_b32_e32 v11, v0
	v_mov_b32_e32 v12, v0
	v_mov_b32_e32 v13, v0
	v_mov_b32_e32 v14, v0
	v_mov_b32_e32 v15, v0
	v_mov_b32_e32 v24, v0
	v_mov_b32_e32 v25, v0
	v_mov_b32_e32 v26, v0
	v_mov_b32_e32 v27, v0
	v_mov_b32_e32 v28, v0
	v_mov_b32_e32 v29, v0
	v_mov_b32_e32 v30, v0
	v_mov_b32_e32 v31, v0
	v_mov_b32_e32 v40, v0
	v_mov_b32_e32 v41, v0
	v_mov_b32_e32 v42, v0
	v_mov_b32_e32 v43, v0
	v_mov_b32_e32 v44, v0
	v_mov_b32_e32 v45, v0
	v_mov_b32_e32 v46, v0
	v_mov_b32_e32 v47, v0
	v_mov_b32_e32 v56, v0
	v_mov_b32_e32 v57, v0
	v_mov_b32_e32 v58, v0
	v_mov_b32_e32 v59, v0
	v_mov_b32_e32 v60, v0
	v_mov_b32_e32 v61, v0
	v_mov_b32_e32 v62, v0
	v_mov_b32_e32 v63, v0
	v_mov_b32_e32 v64, v0
	v_mov_b32_e32 v65, v0
	v_mov_b32_e32 v66, v0
	v_mov_b32_e32 v67, v0
	v_mov_b32_e32 v76, v0
	v_mov_b32_e32 v77, v0
	v_mov_b32_e32 v78, v0
	v_mov_b32_e32 v79, v0
	v_mov_b32_e32 v100, v0
	v_mov_b32_e32 v101, v0
	v_mov_b32_e32 v102, v0
	v_mov_b32_e32 v103, v0
	v_mov_b32_e32 v104, v0
	v_mov_b32_e32 v105, v0
	v_mov_b32_e32 v106, v0
	v_mov_b32_e32 v107, v0
	v_mov_b32_e32 v80, v0
	v_mov_b32_e32 v81, v0
	v_mov_b32_e32 v82, v0
	v_mov_b32_e32 v83, v0
	v_mov_b32_e32 v112, v0
	v_mov_b32_e32 v113, v0
	v_mov_b32_e32 v114, v0
	v_mov_b32_e32 v115, v0
	v_mov_b32_e32 v84, v0
	v_mov_b32_e32 v85, v0
	v_mov_b32_e32 v86, v0
	v_mov_b32_e32 v87, v0
	v_mov_b32_e32 v120, v0
	v_mov_b32_e32 v121, v0
	v_mov_b32_e32 v122, v0
	v_mov_b32_e32 v123, v0
	v_mov_b32_e32 v88, v0
	v_mov_b32_e32 v89, v0
	v_mov_b32_e32 v90, v0
	v_mov_b32_e32 v91, v0
	v_mov_b32_e32 v92, v0
	v_mov_b32_e32 v93, v0
	v_mov_b32_e32 v94, v0
	v_mov_b32_e32 v95, v0
	v_mov_b32_e32 v96, v0
	v_mov_b32_e32 v97, v0
	v_mov_b32_e32 v98, v0
	v_mov_b32_e32 v99, v0
	v_mov_b32_e32 v108, v0
	v_mov_b32_e32 v109, v0
	v_mov_b32_e32 v110, v0
	v_mov_b32_e32 v111, v0
	v_mov_b32_e32 v68, v0
	v_mov_b32_e32 v69, v0
	v_mov_b32_e32 v70, v0
	v_mov_b32_e32 v71, v0
	v_mov_b32_e32 v116, v0
	v_mov_b32_e32 v117, v0
	v_mov_b32_e32 v118, v0
	v_mov_b32_e32 v119, v0
	v_mov_b32_e32 v72, v0
	v_mov_b32_e32 v73, v0
	v_mov_b32_e32 v74, v0
	v_mov_b32_e32 v75, v0
	v_mov_b32_e32 v124, v0
	v_mov_b32_e32 v125, v0
	v_mov_b32_e32 v126, v0
	v_mov_b32_e32 v127, v0
	v_add_u32_e32 v216, 0x18000, v153
	v_add_u32_e32 v217, 0x1c000, v153
.LBB0_3203:
	ds_read_b128 v[144:147], v155
	ds_read_b128 v[148:151], v155 offset:1024
	ds_read_b128 v[160:163], v155 offset:2048
	ds_read_b128 v[164:167], v155 offset:3072
	ds_read_b128 v[168:171], v156
	ds_read_b128 v[172:175], v156 offset:1024
	ds_read_b128 v[176:179], v156 offset:2048
	ds_read_b128 v[180:183], v156 offset:3072
	s_add_u32 s58, s56, 0xfff00080
	s_addc_u32 s59, s57, -1
	s_cmp_eq_u32 s74, 60
	s_cselect_b32 s61, s47, s59
	s_cselect_b32 s60, s53, s58
	s_cselect_b32 s59, s45, s73
	s_cselect_b32 s58, s71, s72
	s_add_i32 m0, s29, 0xc000
	ds_read_b128 v[184:187], v157
	ds_read_b128 v[188:191], v157 offset:1024
	ds_read_b128 v[192:195], v157 offset:2048
	ds_read_b128 v[196:199], v157 offset:3072
	ds_read_b128 v[200:203], v157 offset:4096
	ds_read_b128 v[204:207], v157 offset:5120
	ds_read_b128 v[208:211], v157 offset:6144
	ds_read_b128 v[212:215], v157 offset:7168
	global_load_lds_dwordx4 v136, s[56:57]
	s_add_i32 m0, s29, 0xe000
	s_nop 0
	global_load_lds_dwordx4 v138, s[56:57]
	s_waitcnt vmcnt(8)
	s_waitcnt lgkmcnt(0)
	s_barrier
; #define PG8_STAGE(bufoff, gbase, voff) do { _Pragma("unroll") for (int _i = 0; _i < 2; ++_i) \
;         __builtin_amdgcn_global_load_lds((const unsigned*)((const char*)(gbase) + (voff)[_i]), (PG8_LAS unsigned*)(lds + (bufoff) + ldsw + _i * 8192), 16, 0, 0); } while (0)
; #define PG8_LDA(dst, b, h) do { _Pragma("unroll") for (int m = 0; m < 4; ++m) _Pragma("unroll") for (int k = 0; k < 2; ++k) dst[m][k] = *(const PG8_LAS bf16x8*)(lds + PG8_SA(b, h) + aoff + m * 2048 + k * 1024); } while (0)
; #define PG8_MMA(ai, bj, At, Bt) do { __builtin_amdgcn_s_setprio(1); _Pragma("unroll") for (int m = 0; m < 4; ++m) _Pragma("unroll") for (int n = 0; n < 2; ++n) _Pragma("unroll") for (int k = 0; k < 2; ++k) \
;         acc[ai][bj][m][n] = __builtin_amdgcn_mfma_f32_16x16x32_bf16(Bt[n][k], At[m][k], acc[ai][bj][m][n], 0, 0, 0); __builtin_amdgcn_s_setprio(0); } while (0)
; #define PG8_WAIT_V(n) asm volatile("s_waitcnt vmcnt(" #n ")" ::: "memory")
; #define PG8_WAIT_L(n) asm volatile("s_waitcnt lgkmcnt(" #n ")" ::: "memory")
; #define PG8_BAR __builtin_amdgcn_s_barrier()
; #define PG8_SCHED __builtin_amdgcn_sched_barrier(0)
; template <class Epi, class Sched, bool ALIGN_EPI = false, bool SP2 = false>
; __device__ __forceinline__ void gemm_phase(PG8_LAS unsigned char* lds, const Gemm g, const Sched& S, const Epi& E) {
;     ...
;             PG8_WAIT_V(8); PG8_WAIT_L(0); PG8_BAR; PG8_MMA(0, 0, At, B0); PG8_MMA(0, 1, At, B1); PG8_BAR; PG8_SCHED;
;             PG8_LDA(At, 0, 1); PG8_STAGE(PG8_SB(0, 0), b2, voffB); PG8_STAGE(PG8_SB(0, 1), b2 + hstep, voffB); PG8_STAGE(PG8_SA(0, 0), a2, voffA);
;             PG8_WAIT_V(8); PG8_WAIT_L(0); PG8_BAR; PG8_MMA(1, 0, At, B0); PG8_MMA(1, 1, At, B1); PG8_BAR; PG8_SCHED;
	v_mfma_f32_16x16x32_bf16 v[124:127], v[144:147], v[184:187], v[124:127]
	v_mfma_f32_16x16x32_bf16 v[72:75], v[160:163], v[184:187], v[72:75]
	v_mfma_f32_16x16x32_bf16 v[116:119], v[144:147], v[192:195], v[116:119]
	v_mfma_f32_16x16x32_bf16 v[68:71], v[160:163], v[192:195], v[68:71]
	v_mfma_f32_16x16x32_bf16 v[108:111], v[144:147], v[200:203], v[108:111]
	v_mfma_f32_16x16x32_bf16 v[96:99], v[160:163], v[200:203], v[96:99]
	v_mfma_f32_16x16x32_bf16 v[92:95], v[144:147], v[208:211], v[92:95]
	v_mfma_f32_16x16x32_bf16 v[88:91], v[160:163], v[208:211], v[88:91]
	v_mfma_f32_16x16x32_bf16 v[124:127], v[148:151], v[188:191], v[124:127]
	v_mfma_f32_16x16x32_bf16 v[72:75], v[164:167], v[188:191], v[72:75]
	v_mfma_f32_16x16x32_bf16 v[116:119], v[148:151], v[196:199], v[116:119]
	v_mfma_f32_16x16x32_bf16 v[68:71], v[164:167], v[196:199], v[68:71]
	v_mfma_f32_16x16x32_bf16 v[108:111], v[148:151], v[204:207], v[108:111]
	v_mfma_f32_16x16x32_bf16 v[96:99], v[164:167], v[204:207], v[96:99]
	v_mfma_f32_16x16x32_bf16 v[92:95], v[148:151], v[212:215], v[92:95]
	v_mfma_f32_16x16x32_bf16 v[88:91], v[164:167], v[212:215], v[88:91]
	v_mfma_f32_16x16x32_bf16 v[120:123], v[168:171], v[184:187], v[120:123]
	v_mfma_f32_16x16x32_bf16 v[84:87], v[176:179], v[184:187], v[84:87]
	v_mfma_f32_16x16x32_bf16 v[112:115], v[168:171], v[192:195], v[112:115]
	v_mfma_f32_16x16x32_bf16 v[80:83], v[176:179], v[192:195], v[80:83]
	v_mfma_f32_16x16x32_bf16 v[104:107], v[168:171], v[200:203], v[104:107]
	v_mfma_f32_16x16x32_bf16 v[100:103], v[176:179], v[200:203], v[100:103]
	v_mfma_f32_16x16x32_bf16 v[76:79], v[168:171], v[208:211], v[76:79]
	v_mfma_f32_16x16x32_bf16 v[64:67], v[176:179], v[208:211], v[64:67]
	v_mfma_f32_16x16x32_bf16 v[120:123], v[172:175], v[188:191], v[120:123]
	v_mfma_f32_16x16x32_bf16 v[84:87], v[180:183], v[188:191], v[84:87]
	v_mfma_f32_16x16x32_bf16 v[112:115], v[172:175], v[196:199], v[112:115]
	v_mfma_f32_16x16x32_bf16 v[80:83], v[180:183], v[196:199], v[80:83]
	v_mfma_f32_16x16x32_bf16 v[104:107], v[172:175], v[204:207], v[104:107]
	v_mfma_f32_16x16x32_bf16 v[100:103], v[180:183], v[204:207], v[100:103]
	v_mfma_f32_16x16x32_bf16 v[76:79], v[172:175], v[212:215], v[76:79]
	v_mfma_f32_16x16x32_bf16 v[64:67], v[180:183], v[212:215], v[64:67]
	s_barrier
	s_add_u32 s98, s58, s20
	s_addc_u32 s99, s59, s21
	s_add_u32 s100, s60, s20
	s_addc_u32 s101, s61, s21
	s_add_i32 s75, s68, s3
	s_mov_b32 m0, s75
	ds_read_b128 v[184:187], v157 offset:16384
	ds_read_b128 v[188:191], v157 offset:17408
	ds_read_b128 v[192:195], v157 offset:18432
	ds_read_b128 v[196:199], v157 offset:19456
	ds_read_b128 v[200:203], v157 offset:20480
	ds_read_b128 v[204:207], v157 offset:21504
	ds_read_b128 v[208:211], v157 offset:22528
	ds_read_b128 v[212:215], v157 offset:23552
	global_load_lds_dwordx4 v130, s[58:59]
	s_add_i32 m0, s75, 0x2000
	s_add_u32 s84, s58, 0x100000
	s_addc_u32 s85, s59, 0
	s_add_i32 s75, s69, s3
	global_load_lds_dwordx4 v134, s[58:59]
	s_mov_b32 m0, s75
	s_nop 0
	global_load_lds_dwordx4 v130, s[84:85]
	s_add_i32 m0, s75, 0x2000
	s_nop 0
	global_load_lds_dwordx4 v134, s[84:85]
	s_mov_b32 m0, s29
	s_nop 0
	global_load_lds_dwordx4 v128, s[60:61]
	s_mov_b32 m0, s33
	s_nop 0
	global_load_lds_dwordx4 v132, s[60:61]
	s_waitcnt vmcnt(8)
	s_waitcnt lgkmcnt(0)
	s_barrier
	v_mfma_f32_16x16x32_bf16 v[60:63], v[144:147], v[184:187], v[60:63]
	v_mfma_f32_16x16x32_bf16 v[56:59], v[160:163], v[184:187], v[56:59]
	v_mfma_f32_16x16x32_bf16 v[44:47], v[144:147], v[192:195], v[44:47]
	v_mfma_f32_16x16x32_bf16 v[40:43], v[160:163], v[192:195], v[40:43]
	v_mfma_f32_16x16x32_bf16 v[28:31], v[144:147], v[200:203], v[28:31]
	v_mfma_f32_16x16x32_bf16 v[24:27], v[160:163], v[200:203], v[24:27]
	v_mfma_f32_16x16x32_bf16 v[12:15], v[144:147], v[208:211], v[12:15]
	v_mfma_f32_16x16x32_bf16 v[8:11], v[160:163], v[208:211], v[8:11]
	v_mfma_f32_16x16x32_bf16 v[60:63], v[148:151], v[188:191], v[60:63]
	v_mfma_f32_16x16x32_bf16 v[56:59], v[164:167], v[188:191], v[56:59]
	v_mfma_f32_16x16x32_bf16 v[44:47], v[148:151], v[196:199], v[44:47]
	v_mfma_f32_16x16x32_bf16 v[40:43], v[164:167], v[196:199], v[40:43]
	v_mfma_f32_16x16x32_bf16 v[28:31], v[148:151], v[204:207], v[28:31]
	v_mfma_f32_16x16x32_bf16 v[24:27], v[164:167], v[204:207], v[24:27]
	v_mfma_f32_16x16x32_bf16 v[12:15], v[148:151], v[212:215], v[12:15]
	v_mfma_f32_16x16x32_bf16 v[8:11], v[164:167], v[212:215], v[8:11]
	v_mfma_f32_16x16x32_bf16 v[52:55], v[168:171], v[184:187], v[52:55]
	v_mfma_f32_16x16x32_bf16 v[48:51], v[176:179], v[184:187], v[48:51]
	v_mfma_f32_16x16x32_bf16 v[36:39], v[168:171], v[192:195], v[36:39]
	v_mfma_f32_16x16x32_bf16 v[32:35], v[176:179], v[192:195], v[32:35]
	v_mfma_f32_16x16x32_bf16 v[20:23], v[168:171], v[200:203], v[20:23]
	v_mfma_f32_16x16x32_bf16 v[16:19], v[176:179], v[200:203], v[16:19]
	v_mfma_f32_16x16x32_bf16 v[4:7], v[168:171], v[208:211], v[4:7]
	v_mfma_f32_16x16x32_bf16 v[0:3], v[176:179], v[208:211], v[0:3]
	v_mfma_f32_16x16x32_bf16 v[52:55], v[172:175], v[188:191], v[52:55]
	v_mfma_f32_16x16x32_bf16 v[48:51], v[180:183], v[188:191], v[48:51]
	v_mfma_f32_16x16x32_bf16 v[36:39], v[172:175], v[196:199], v[36:39]
	v_mfma_f32_16x16x32_bf16 v[32:35], v[180:183], v[196:199], v[32:35]
	v_mfma_f32_16x16x32_bf16 v[20:23], v[172:175], v[204:207], v[20:23]
	v_mfma_f32_16x16x32_bf16 v[16:19], v[180:183], v[204:207], v[16:19]
	v_mfma_f32_16x16x32_bf16 v[4:7], v[172:175], v[212:215], v[4:7]
	v_mfma_f32_16x16x32_bf16 v[0:3], v[180:183], v[212:215], v[0:3]
	s_barrier
; #define PG8_STAGE(bufoff, gbase, voff) do { _Pragma("unroll") for (int _i = 0; _i < 2; ++_i) \
;         __builtin_amdgcn_global_load_lds((const unsigned*)((const char*)(gbase) + (voff)[_i]), (PG8_LAS unsigned*)(lds + (bufoff) + ldsw + _i * 8192), 16, 0, 0); } while (0)
; #define PG8_LDA(dst, b, h) do { _Pragma("unroll") for (int m = 0; m < 4; ++m) _Pragma("unroll") for (int k = 0; k < 2; ++k) dst[m][k] = *(const PG8_LAS bf16x8*)(lds + PG8_SA(b, h) + aoff + m * 2048 + k * 1024); } while (0)
; #define PG8_LDB(dst, b, h) do { _Pragma("unroll") for (int n = 0; n < 2; ++n) _Pragma("unroll") for (int k = 0; k < 2; ++k) dst[n][k] = *(const PG8_LAS bf16x8*)(lds + PG8_SB(b, h) + boff + n * 2048 + k * 1024); } while (0)
; #define PG8_MMA(ai, bj, At, Bt) do { __builtin_amdgcn_s_setprio(1); _Pragma("unroll") for (int m = 0; m < 4; ++m) _Pragma("unroll") for (int n = 0; n < 2; ++n) _Pragma("unroll") for (int k = 0; k < 2; ++k) \
;         acc[ai][bj][m][n] = __builtin_amdgcn_mfma_f32_16x16x32_bf16(Bt[n][k], At[m][k], acc[ai][bj][m][n], 0, 0, 0); __builtin_amdgcn_s_setprio(0); } while (0)
; #define PG8_WAIT_V(n) asm volatile("s_waitcnt vmcnt(" #n ")" ::: "memory")
; #define PG8_WAIT_L(n) asm volatile("s_waitcnt lgkmcnt(" #n ")" ::: "memory")
; #define PG8_BAR __builtin_amdgcn_s_barrier()
; #define PG8_SCHED __builtin_amdgcn_sched_barrier(0)
; template <class Epi, class Sched, bool ALIGN_EPI = false, bool SP2 = false>
; __device__ __forceinline__ void gemm_phase(PG8_LAS unsigned char* lds, const Gemm g, const Sched& S, const Epi& E) {
;     ...
;         for (int t = 0; t < nt; t += 2) {
;             const bool last = (t == nt - 2);
;     ...
;             PG8_LDB(B0, 1, 0); PG8_LDB(B1, 1, 1); PG8_SCHED; PG8_LDA(At, 1, 0); PG8_STAGE(PG8_SA(0, 1), a2 + hstepA, voffA);
;             PG8_WAIT_V(8); PG8_WAIT_L(0); PG8_BAR; PG8_MMA(0, 0, At, B0); PG8_MMA(0, 1, At, B1); PG8_BAR; PG8_SCHED;
;             PG8_LDA(At, 1, 1); PG8_STAGE(PG8_SB(1, 0), b3, voffB); PG8_STAGE(PG8_SB(1, 1), b3 + hstep, voffB); PG8_STAGE(PG8_SA(1, 0), a3, voffA);
;             PG8_WAIT_V(8); PG8_WAIT_L(0); PG8_BAR; PG8_MMA(1, 0, At, B0); PG8_MMA(1, 1, At, B1); PG8_BAR; PG8_SCHED;
	s_add_i32 s75, 0, 0x18000
	s_add_i32 s84, 0, 0x1c000
	ds_read_b128 v[144:147], v216
	ds_read_b128 v[148:151], v216 offset:1024
	ds_read_b128 v[160:163], v216 offset:2048
	ds_read_b128 v[164:167], v216 offset:3072
	ds_read_b128 v[168:171], v217
	ds_read_b128 v[172:175], v217 offset:1024
	ds_read_b128 v[176:179], v217 offset:2048
	ds_read_b128 v[180:183], v217 offset:3072
	s_add_u32 s60, s60, 0x100000
	s_addc_u32 s61, s61, 0
	s_mov_b32 m0, s55
	ds_read_b128 v[184:187], v157 offset:32768
	ds_read_b128 v[188:191], v157 offset:33792
	ds_read_b128 v[192:195], v157 offset:34816
	ds_read_b128 v[196:199], v157 offset:35840
	ds_read_b128 v[200:203], v157 offset:36864
	ds_read_b128 v[204:207], v157 offset:37888
	ds_read_b128 v[208:211], v157 offset:38912
	ds_read_b128 v[212:215], v157 offset:39936
	global_load_lds_dwordx4 v128, s[60:61]
	s_mov_b32 m0, s62
	s_nop 0
	global_load_lds_dwordx4 v132, s[60:61]
	s_waitcnt vmcnt(8)
	s_waitcnt lgkmcnt(0)
	s_barrier
	v_mfma_f32_16x16x32_bf16 v[124:127], v[144:147], v[184:187], v[124:127]
	v_mfma_f32_16x16x32_bf16 v[72:75], v[160:163], v[184:187], v[72:75]
	v_mfma_f32_16x16x32_bf16 v[116:119], v[144:147], v[192:195], v[116:119]
	v_mfma_f32_16x16x32_bf16 v[68:71], v[160:163], v[192:195], v[68:71]
	v_mfma_f32_16x16x32_bf16 v[108:111], v[144:147], v[200:203], v[108:111]
	v_mfma_f32_16x16x32_bf16 v[96:99], v[160:163], v[200:203], v[96:99]
	v_mfma_f32_16x16x32_bf16 v[92:95], v[144:147], v[208:211], v[92:95]
	v_mfma_f32_16x16x32_bf16 v[88:91], v[160:163], v[208:211], v[88:91]
	v_mfma_f32_16x16x32_bf16 v[124:127], v[148:151], v[188:191], v[124:127]
	v_mfma_f32_16x16x32_bf16 v[72:75], v[164:167], v[188:191], v[72:75]
	v_mfma_f32_16x16x32_bf16 v[116:119], v[148:151], v[196:199], v[116:119]
	v_mfma_f32_16x16x32_bf16 v[68:71], v[164:167], v[196:199], v[68:71]
	v_mfma_f32_16x16x32_bf16 v[108:111], v[148:151], v[204:207], v[108:111]
	v_mfma_f32_16x16x32_bf16 v[96:99], v[164:167], v[204:207], v[96:99]
	v_mfma_f32_16x16x32_bf16 v[92:95], v[148:151], v[212:215], v[92:95]
	v_mfma_f32_16x16x32_bf16 v[88:91], v[164:167], v[212:215], v[88:91]
	v_mfma_f32_16x16x32_bf16 v[120:123], v[168:171], v[184:187], v[120:123]
	v_mfma_f32_16x16x32_bf16 v[84:87], v[176:179], v[184:187], v[84:87]
	v_mfma_f32_16x16x32_bf16 v[112:115], v[168:171], v[192:195], v[112:115]
	v_mfma_f32_16x16x32_bf16 v[80:83], v[176:179], v[192:195], v[80:83]
	v_mfma_f32_16x16x32_bf16 v[104:107], v[168:171], v[200:203], v[104:107]
	v_mfma_f32_16x16x32_bf16 v[100:103], v[176:179], v[200:203], v[100:103]
	v_mfma_f32_16x16x32_bf16 v[76:79], v[168:171], v[208:211], v[76:79]
	v_mfma_f32_16x16x32_bf16 v[64:67], v[176:179], v[208:211], v[64:67]
	v_mfma_f32_16x16x32_bf16 v[120:123], v[172:175], v[188:191], v[120:123]
	v_mfma_f32_16x16x32_bf16 v[84:87], v[180:183], v[188:191], v[84:87]
	v_mfma_f32_16x16x32_bf16 v[112:115], v[172:175], v[196:199], v[112:115]
	v_mfma_f32_16x16x32_bf16 v[80:83], v[180:183], v[196:199], v[80:83]
	v_mfma_f32_16x16x32_bf16 v[104:107], v[172:175], v[204:207], v[104:107]
	v_mfma_f32_16x16x32_bf16 v[100:103], v[180:183], v[204:207], v[100:103]
	v_mfma_f32_16x16x32_bf16 v[76:79], v[172:175], v[212:215], v[76:79]
	v_mfma_f32_16x16x32_bf16 v[64:67], v[180:183], v[212:215], v[64:67]
	s_barrier
	s_add_i32 s60, s75, s3
	s_mov_b32 m0, s60
	ds_read_b128 v[184:187], v157 offset:49152
	ds_read_b128 v[188:191], v157 offset:50176
	ds_read_b128 v[192:195], v157 offset:51200
	ds_read_b128 v[196:199], v157 offset:52224
	ds_read_b128 v[200:203], v157 offset:53248
	ds_read_b128 v[204:207], v157 offset:54272
	ds_read_b128 v[208:211], v157 offset:55296
	ds_read_b128 v[212:215], v157 offset:56320
	global_load_lds_dwordx4 v130, s[98:99]
	s_add_i32 m0, s60, 0x2000
	s_add_u32 s58, s58, 0x100080
	s_addc_u32 s59, s59, 0
	s_add_i32 s60, s84, s3
	global_load_lds_dwordx4 v134, s[98:99]
	s_mov_b32 m0, s60
	s_nop 0
	global_load_lds_dwordx4 v130, s[58:59]
	s_add_i32 m0, s60, 0x2000
	s_nop 0
	global_load_lds_dwordx4 v134, s[58:59]
	s_mov_b32 m0, s64
	s_nop 0
	global_load_lds_dwordx4 v128, s[100:101]
	s_mov_b32 m0, s65
	s_nop 0
	global_load_lds_dwordx4 v132, s[100:101]
	s_waitcnt vmcnt(8)
	s_waitcnt lgkmcnt(0)
	s_barrier
	v_mfma_f32_16x16x32_bf16 v[60:63], v[144:147], v[184:187], v[60:63]
	v_mfma_f32_16x16x32_bf16 v[56:59], v[160:163], v[184:187], v[56:59]
	v_mfma_f32_16x16x32_bf16 v[44:47], v[144:147], v[192:195], v[44:47]
	v_mfma_f32_16x16x32_bf16 v[40:43], v[160:163], v[192:195], v[40:43]
	v_mfma_f32_16x16x32_bf16 v[28:31], v[144:147], v[200:203], v[28:31]
	v_mfma_f32_16x16x32_bf16 v[24:27], v[160:163], v[200:203], v[24:27]
	v_mfma_f32_16x16x32_bf16 v[12:15], v[144:147], v[208:211], v[12:15]
	v_mfma_f32_16x16x32_bf16 v[8:11], v[160:163], v[208:211], v[8:11]
	v_mfma_f32_16x16x32_bf16 v[60:63], v[148:151], v[188:191], v[60:63]
	v_mfma_f32_16x16x32_bf16 v[56:59], v[164:167], v[188:191], v[56:59]
	v_mfma_f32_16x16x32_bf16 v[44:47], v[148:151], v[196:199], v[44:47]
	v_mfma_f32_16x16x32_bf16 v[40:43], v[164:167], v[196:199], v[40:43]
	v_mfma_f32_16x16x32_bf16 v[28:31], v[148:151], v[204:207], v[28:31]
	v_mfma_f32_16x16x32_bf16 v[24:27], v[164:167], v[204:207], v[24:27]
	v_mfma_f32_16x16x32_bf16 v[12:15], v[148:151], v[212:215], v[12:15]
	v_mfma_f32_16x16x32_bf16 v[8:11], v[164:167], v[212:215], v[8:11]
	v_mfma_f32_16x16x32_bf16 v[52:55], v[168:171], v[184:187], v[52:55]
	v_mfma_f32_16x16x32_bf16 v[48:51], v[176:179], v[184:187], v[48:51]
	v_mfma_f32_16x16x32_bf16 v[36:39], v[168:171], v[192:195], v[36:39]
	v_mfma_f32_16x16x32_bf16 v[32:35], v[176:179], v[192:195], v[32:35]
	v_mfma_f32_16x16x32_bf16 v[20:23], v[168:171], v[200:203], v[20:23]
	v_mfma_f32_16x16x32_bf16 v[16:19], v[176:179], v[200:203], v[16:19]
	v_mfma_f32_16x16x32_bf16 v[4:7], v[168:171], v[208:211], v[4:7]
	v_mfma_f32_16x16x32_bf16 v[0:3], v[176:179], v[208:211], v[0:3]
	v_mfma_f32_16x16x32_bf16 v[52:55], v[172:175], v[188:191], v[52:55]
	v_mfma_f32_16x16x32_bf16 v[48:51], v[180:183], v[188:191], v[48:51]
	v_mfma_f32_16x16x32_bf16 v[36:39], v[172:175], v[196:199], v[36:39]
	v_mfma_f32_16x16x32_bf16 v[32:35], v[180:183], v[196:199], v[32:35]
	v_mfma_f32_16x16x32_bf16 v[20:23], v[172:175], v[204:207], v[20:23]
	v_mfma_f32_16x16x32_bf16 v[16:19], v[180:183], v[204:207], v[16:19]
	v_mfma_f32_16x16x32_bf16 v[4:7], v[172:175], v[212:215], v[4:7]
	v_mfma_f32_16x16x32_bf16 v[0:3], v[180:183], v[212:215], v[0:3]
	s_barrier
	s_add_i32 s74, s74, 2
	s_add_u32 s56, s56, 0x100
	s_addc_u32 s57, s57, 0
	s_add_u32 s72, s72, 0x100
	s_addc_u32 s73, s73, 0
	s_cmp_gt_u32 s74, 61
	s_cbranch_scc0 .LBB0_3203
	s_and_b64 vcc, exec, s[22:23]
	s_cbranch_vccz .LBB0_3206
	s_barrier
